# FNet token-DFT B epilogue: mirrored-row gate read issued with the A1 read-back instead of behind the U store (plus the two earlier edits)
# baseline (speedup 1.0000x reference)
; DI void st_bf16x8(bf16_t* p, f32x4 a, f32x4 b) { u32x4 w = {pk2(a[0], a[1]), pk2(a[2], a[3]), pk2(b[0], b[1]), pk2(b[2], b[3])}; *(u32x4*)p = w; }
; DI void ld_bf16x8(const bf16_t* p, f32x4& a, f32x4& b) { const u32x4 w = *(const u32x4*)p; a = (f32x4){bf_lo(w.x), bf_hi(w.x), bf_lo(w.y), bf_hi(w.y)}; b = (f32x4){bf_lo(w.z), bf_hi(w.z), bf_lo(w.w), bf_hi(w.w)}; }
; DI void fnet_layer(const Args& A, LAS unsigned char* lds, const XcdBarrier& gbar, int layer, int j, bool latonly, int wv) {
;     ...
;         auto E = [=](const pg8::Unit& u, int row_l, int col_l, f32x4 v0, f32x4 v1) {
;             const int k = u.i1 * 256 + row_l, col = (u.i2 & 7) * 256 + col_l;
;             bf16_t* ap = A1 + ((size_t)u.i0 * 1024 + k) * DM + col;
;             if (u.i2 < 8) { st_bf16x8(ap, v0, v1); return; }
;             f32x4 a0, a1; ld_bf16x8(ap, a0, a1);
;             const size_t off = ((size_t)u.i0 * TB + k) * DM + col;
;             f32x4 g0, g1; ld_bf16x8(Gt + off, g0, g1);
;             st_bf16x8(U + off, (a0 + v0) * g0, (a1 + v1) * g1);
;             if (k != 0) { const size_t off2 = ((size_t)u.i0 * TB + (TL - k)) * DM + col; ld_bf16x8(Gt + off2, g0, g1); st_bf16x8(U + off2, (a0 - v0) * g0, (a1 - v1) * g1); }
.LBB0_584:
	s_lshl_b32 s1, s4, 8
	s_add_i32 s1, s1, s31
	v_mbcnt_lo_u32_b32 v128, -1, 0
	v_mbcnt_hi_u32_b32 v128, -1, v128
	s_mul_hi_i32 s67, s0, 0x900
	v_and_or_b32 v150, v128, 15, s1
	s_lshl_b32 s1, s5, 8
	s_and_b32 s48, s1, 0x700
	s_ashr_i32 s1, s0, 31
	s_lshl_b64 s[50:51], s[0:1], 22
	v_ashrrev_i32_e32 v151, 31, v150
	v_sub_u32_e32 v156, 0x800, v150
	s_cmp_gt_i32 s5, 7
	v_mad_i64_i32 v[130:131], s[4:5], s0, v188, v[150:151]
	v_ashrrev_i32_e32 v157, 31, v156
	s_mul_i32 s66, s0, 0x900
	v_lshlrev_b64 v[154:155], 11, v[130:131]
	v_mad_i64_i32 v[130:131], s[0:1], s0, v188, v[156:157]
	v_lshrrev_b32_e32 v132, 1, v128
	s_cselect_b64 s[70:71], -1, 0
	s_add_i32 s47, s48, 0x200
	v_readlane_b32 s0, v247, 46
	v_lshlrev_b64 v[128:129], 12, v[150:151]
	v_and_or_b32 v151, v132, 24, s34
	s_add_u32 s68, s0, s50
	v_readlane_b32 s0, v247, 47
	v_or_b32_e32 v189, s48, v151
	s_addc_u32 s69, s0, s51
	s_mov_b32 s98, s68
	s_lshl_b64 s[100:101], s[66:67], 12
	s_add_u32 s100, s100, s44
	s_addc_u32 s101, s101, s45
	v_lshl_add_u64 v[160:161], s[68:69], 0, v[128:129]
	v_lshlrev_b32_e32 v152, 1, v189
	v_mov_b32_e32 v153, v145
	v_cmp_ne_u32_e64 s[4:5], 0, v150
	v_lshlrev_b64 v[158:159], 11, v[130:131]
	v_lshl_add_u64 v[162:163], v[160:161], 0, v[152:153]
	s_mov_b64 s[0:1], -1
	s_and_b64 vcc, exec, s[70:71]
	s_cbranch_vccz .LBB0_601
	v_subrev_u32_e32 v248, s98, v162
	v_and_b32_e32 v249, 0xfffff000, v248
	v_and_b32_e32 v250, 0xfff, v248
	v_sub_u32_e32 v251, v250, v249
	v_add_u32_e32 v251, 0x800000, v251
	global_load_dwordx4 v[252:255], v251, s[100:101]
	global_load_dwordx4 v[128:131], v[162:163], off
	s_waitcnt vmcnt(0)
	v_lshlrev_b32_e32 v132, 16, v128
	v_and_b32_e32 v133, 0xffff0000, v128
	v_lshlrev_b32_e32 v134, 16, v129
	v_and_b32_e32 v135, 0xffff0000, v129
	v_or_b32_e32 v128, v154, v189
	v_mov_b32_e32 v129, v155
	v_lshlrev_b64 v[164:165], 1, v[128:129]
	v_lshl_add_u64 v[128:129], s[44:45], 0, v[164:165]
	v_lshlrev_b32_e32 v176, 16, v130
	v_and_b32_e32 v177, 0xffff0000, v130
	v_lshlrev_b32_e32 v178, 16, v131
	v_and_b32_e32 v179, 0xffff0000, v131
	global_load_dwordx4 v[128:131], v[128:129], off
	v_lshl_add_u64 v[174:175], s[36:37], 0, v[164:165]
	v_pk_add_f32 v[166:167], v[126:127], v[134:135]
	v_pk_add_f32 v[164:165], v[124:125], v[132:133]
	v_pk_add_f32 v[170:171], v[122:123], v[178:179]
	v_sub_f32_e32 v179, v179, v123
	v_sub_f32_e32 v178, v178, v122
	s_waitcnt vmcnt(0)
	v_lshlrev_b32_e32 v168, 16, v128
	v_and_b32_e32 v169, 0xffff0000, v128
	v_lshlrev_b32_e32 v128, 16, v129
	v_and_b32_e32 v129, 0xffff0000, v129
	v_lshlrev_b32_e32 v172, 16, v130
	v_and_b32_e32 v173, 0xffff0000, v130
	v_lshlrev_b32_e32 v130, 16, v131
	v_and_b32_e32 v131, 0xffff0000, v131
	v_pk_mul_f32 v[180:181], v[166:167], v[128:129]
	v_pk_mul_f32 v[128:129], v[164:165], v[168:169]
	v_pk_add_f32 v[168:169], v[120:121], v[176:177]
	v_pk_mul_f32 v[182:183], v[170:171], v[130:131]
	v_pk_mul_f32 v[130:131], v[168:169], v[172:173]
	v_cvt_pk_bf16_f32 v128, v128, v129
	v_cvt_pk_bf16_f32 v129, v180, v181
	v_cvt_pk_bf16_f32 v130, v130, v131
	v_cvt_pk_bf16_f32 v131, v182, v183
	global_store_dwordx4 v[174:175], v[128:131], off
	v_sub_f32_e32 v175, v135, v127
	v_sub_f32_e32 v174, v134, v126
	v_sub_f32_e32 v173, v133, v125
	v_sub_f32_e32 v172, v132, v124
	v_sub_f32_e32 v177, v177, v121
	v_sub_f32_e32 v176, v176, v120
	s_and_saveexec_b64 s[0:1], s[4:5]
	s_xor_b64 s[0:1], exec, s[0:1]
	s_cbranch_execz .LBB0_587
	v_or_b32_e32 v128, v158, v189
	v_mov_b32_e32 v129, v159
	v_lshlrev_b64 v[132:133], 1, v[128:129]
	v_lshl_add_u64 v[128:129], s[44:45], 0, v[132:133]
	v_lshl_add_u64 v[132:133], s[36:37], 0, v[132:133]
	v_mov_b32_e32 v128, v252
	v_mov_b32_e32 v129, v253
	v_mov_b32_e32 v130, v254
	v_mov_b32_e32 v131, v255
	v_lshlrev_b32_e32 v134, 16, v128
	v_and_b32_e32 v135, 0xffff0000, v128
	v_lshlrev_b32_e32 v128, 16, v129
	v_and_b32_e32 v129, 0xffff0000, v129
	v_lshlrev_b32_e32 v180, 16, v130
	v_and_b32_e32 v181, 0xffff0000, v130
	v_lshlrev_b32_e32 v130, 16, v131
	v_and_b32_e32 v131, 0xffff0000, v131
	v_pk_mul_f32 v[182:183], v[174:175], v[128:129]
	v_pk_mul_f32 v[128:129], v[172:173], v[134:135]
	v_pk_mul_f32 v[134:135], v[178:179], v[130:131]
	v_pk_mul_f32 v[130:131], v[176:177], v[180:181]
	v_cvt_pk_bf16_f32 v128, v128, v129
	v_cvt_pk_bf16_f32 v129, v182, v183
	v_cvt_pk_bf16_f32 v130, v130, v131
	v_cvt_pk_bf16_f32 v131, v134, v135
	global_store_dwordx4 v[132:133], v[128:131], off

; DI void st_bf16x8(bf16_t* p, f32x4 a, f32x4 b) { u32x4 w = {pk2(a[0], a[1]), pk2(a[2], a[3]), pk2(b[0], b[1]), pk2(b[2], b[3])}; *(u32x4*)p = w; }
; DI void ld_bf16x8(const bf16_t* p, f32x4& a, f32x4& b) { const u32x4 w = *(const u32x4*)p; a = (f32x4){bf_lo(w.x), bf_hi(w.x), bf_lo(w.y), bf_hi(w.y)}; b = (f32x4){bf_lo(w.z), bf_hi(w.z), bf_lo(w.w), bf_hi(w.w)}; }
; DI void fnet_layer(const Args& A, LAS unsigned char* lds, const XcdBarrier& gbar, int layer, int j, bool latonly, int wv) {
;     ...
;             bf16_t* ap = A1 + ((size_t)u.i0 * 1024 + k) * DM + col;
;             if (u.i2 < 8) { st_bf16x8(ap, v0, v1); return; }
;             f32x4 a0, a1; ld_bf16x8(ap, a0, a1);
;             const size_t off = ((size_t)u.i0 * TB + k) * DM + col;
;             f32x4 g0, g1; ld_bf16x8(Gt + off, g0, g1);
;             st_bf16x8(U + off, (a0 + v0) * g0, (a1 + v1) * g1);
;             if (k != 0) { const size_t off2 = ((size_t)u.i0 * TB + (TL - k)) * DM + col; ld_bf16x8(Gt + off2, g0, g1); st_bf16x8(U + off2, (a0 - v0) * g0, (a1 - v1) * g1); }
.LBB0_603:
	v_add_u32_e32 v120, s48, v151
	v_or_b32_e32 v173, 0x80, v151
	v_lshlrev_b32_e32 v128, 1, v120
	v_mov_b32_e32 v129, v145
	v_cndmask_b32_e64 v120, 0, 1, s[70:71]
	v_or_b32_e32 v172, s48, v173
	v_lshl_add_u64 v[130:131], v[160:161], 0, v[128:129]
	v_cmp_ne_u32_e64 s[0:1], 1, v120
	s_andn2_b64 vcc, exec, s[70:71]
	s_mov_b64 s[70:71], -1
	s_cbranch_vccnz .LBB0_613
	v_subrev_u32_e32 v248, s98, v130
	v_add_u32_e32 v248, 256, v248
	v_and_b32_e32 v249, 0xfffff000, v248
	v_and_b32_e32 v250, 0xfff, v248
	v_sub_u32_e32 v251, v250, v249
	v_add_u32_e32 v251, 0x800000, v251
	global_load_dwordx4 v[252:255], v251, s[100:101]
	global_load_dwordx4 v[120:123], v[130:131], off offset:256
	s_waitcnt vmcnt(0)
	v_lshlrev_b32_e32 v124, 16, v120
	v_and_b32_e32 v125, 0xffff0000, v120
	v_lshlrev_b32_e32 v126, 16, v121
	v_and_b32_e32 v127, 0xffff0000, v121
	v_or_b32_e32 v120, v154, v172
	v_mov_b32_e32 v121, v155
	v_lshlrev_b64 v[132:133], 1, v[120:121]
	v_lshl_add_u64 v[120:121], s[44:45], 0, v[132:133]
	v_lshlrev_b32_e32 v168, 16, v122
	v_and_b32_e32 v169, 0xffff0000, v122
	v_lshlrev_b32_e32 v170, 16, v123
	v_and_b32_e32 v171, 0xffff0000, v123
	global_load_dwordx4 v[120:123], v[120:121], off
	v_lshl_add_u64 v[166:167], s[36:37], 0, v[132:133]
	v_pk_add_f32 v[134:135], v[118:119], v[126:127]
	v_pk_add_f32 v[132:133], v[116:117], v[124:125]
	v_pk_add_f32 v[162:163], v[114:115], v[170:171]
	v_sub_f32_e32 v171, v171, v115
	v_sub_f32_e32 v170, v170, v114
	s_waitcnt vmcnt(0)
	v_lshlrev_b32_e32 v160, 16, v120
	v_and_b32_e32 v161, 0xffff0000, v120
	v_lshlrev_b32_e32 v120, 16, v121
	v_and_b32_e32 v121, 0xffff0000, v121
	v_lshlrev_b32_e32 v164, 16, v122
	v_and_b32_e32 v165, 0xffff0000, v122
	v_lshlrev_b32_e32 v122, 16, v123
	v_and_b32_e32 v123, 0xffff0000, v123
	v_pk_mul_f32 v[174:175], v[134:135], v[120:121]
	v_pk_mul_f32 v[120:121], v[132:133], v[160:161]
	v_pk_add_f32 v[160:161], v[112:113], v[168:169]
	v_pk_mul_f32 v[176:177], v[162:163], v[122:123]
	v_pk_mul_f32 v[122:123], v[160:161], v[164:165]
	v_cvt_pk_bf16_f32 v120, v120, v121
	v_cvt_pk_bf16_f32 v121, v174, v175
	v_cvt_pk_bf16_f32 v122, v122, v123
	v_cvt_pk_bf16_f32 v123, v176, v177
	global_store_dwordx4 v[166:167], v[120:123], off
	v_sub_f32_e32 v167, v127, v119
	v_sub_f32_e32 v166, v126, v118
	v_sub_f32_e32 v165, v125, v117
	v_sub_f32_e32 v164, v124, v116
	v_sub_f32_e32 v169, v169, v113
	v_sub_f32_e32 v168, v168, v112
	s_and_saveexec_b64 s[48:49], s[4:5]
	s_xor_b64 s[70:71], exec, s[48:49]
	s_cbranch_execz .LBB0_606
	v_or_b32_e32 v158, v158, v172
	v_lshlrev_b64 v[124:125], 1, v[158:159]
	v_lshl_add_u64 v[120:121], s[44:45], 0, v[124:125]
	v_lshl_add_u64 v[124:125], s[36:37], 0, v[124:125]
	v_mov_b32_e32 v120, v252
	v_mov_b32_e32 v121, v253
	v_mov_b32_e32 v122, v254
	v_mov_b32_e32 v123, v255
	v_lshlrev_b32_e32 v126, 16, v120
	v_and_b32_e32 v127, 0xffff0000, v120
	v_lshlrev_b32_e32 v120, 16, v121
	v_and_b32_e32 v121, 0xffff0000, v121
	v_lshlrev_b32_e32 v158, 16, v122
	v_and_b32_e32 v159, 0xffff0000, v122
	v_lshlrev_b32_e32 v122, 16, v123
	v_and_b32_e32 v123, 0xffff0000, v123
	v_pk_mul_f32 v[174:175], v[166:167], v[120:121]
	v_pk_mul_f32 v[120:121], v[164:165], v[126:127]
	v_pk_mul_f32 v[126:127], v[170:171], v[122:123]
	v_pk_mul_f32 v[122:123], v[168:169], v[158:159]
	v_cvt_pk_bf16_f32 v120, v120, v121
	v_cvt_pk_bf16_f32 v121, v174, v175
	v_cvt_pk_bf16_f32 v122, v122, v123
	v_cvt_pk_bf16_f32 v123, v126, v127
	global_store_dwordx4 v[124:125], v[120:123], off

; DI void st_bf16x8(bf16_t* p, f32x4 a, f32x4 b) { u32x4 w = {pk2(a[0], a[1]), pk2(a[2], a[3]), pk2(b[0], b[1]), pk2(b[2], b[3])}; *(u32x4*)p = w; }
; DI void ld_bf16x8(const bf16_t* p, f32x4& a, f32x4& b) { const u32x4 w = *(const u32x4*)p; a = (f32x4){bf_lo(w.x), bf_hi(w.x), bf_lo(w.y), bf_hi(w.y)}; b = (f32x4){bf_lo(w.z), bf_hi(w.z), bf_lo(w.w), bf_hi(w.w)}; }
; DI void fnet_layer(const Args& A, LAS unsigned char* lds, const XcdBarrier& gbar, int layer, int j, bool latonly, int wv) {
;     ...
;         auto E = [=](const pg8::Unit& u, int row_l, int col_l, f32x4 v0, f32x4 v1) {
;             const int k = u.i1 * 256 + row_l, col = (u.i2 & 7) * 256 + col_l;
;             bf16_t* ap = A1 + ((size_t)u.i0 * 1024 + k) * DM + col;
;             if (u.i2 < 8) { st_bf16x8(ap, v0, v1); return; }
;             f32x4 a0, a1; ld_bf16x8(ap, a0, a1);
;             const size_t off = ((size_t)u.i0 * TB + k) * DM + col;
;             f32x4 g0, g1; ld_bf16x8(Gt + off, g0, g1);
;             st_bf16x8(U + off, (a0 + v0) * g0, (a1 + v1) * g1);
;             if (k != 0) { const size_t off2 = ((size_t)u.i0 * TB + (TL - k)) * DM + col; ld_bf16x8(Gt + off2, g0, g1); st_bf16x8(U + off2, (a0 - v0) * g0, (a1 - v1) * g1); }
;             const f32x4 s0 = a0 + v0, s1 = a1 + v1, d0 = a0 - v0, d1 = a1 - v1;
;             const float sm[8] = {s0[0], s0[1], s0[2], s0[3], s1[0], s1[1], s1[2], s1[3]}, df[8] = {d0[0], d0[1], d0[2], d0[3], d1[0], d1[1], d1[2], d1[3]};
;             const size_t rowk = ((size_t)u.i0 * TB + k) * DM, rowT = ((size_t)u.i0 * TB + (TL - k)) * DM; const int cm = (col & ~255) + 512 - col_l;
;             {
;                 const bf16_t* gk_ = Gt + rowk + cm - 8; const bf16_t* gT_ = Gt + rowT + cm - 8; bf16_t* uk_ = U + rowk + cm - 8; bf16_t* uT_ = U + rowT + cm - 8;
;                 const unsigned short ka1 = gk_[1]; const unsigned ka2 = *(const unsigned*)(gk_ + 2); const u32x2 ka4 = *(const u32x2*)(gk_ + 4); const unsigned short ka0 = col_l ? gk_[8] : (unsigned short)0;
;                 unsigned short ta1 = 0, ta0 = 0; unsigned ta2 = 0; u32x2 ta4 = {0u, 0u};
;                 if (k != 0) { ta1 = gT_[1]; ta2 = *(const unsigned*)(gT_ + 2); ta4 = *(const u32x2*)(gT_ + 4); ta0 = col_l ? gT_[8] : (unsigned short)0; }
.LBB0_615:
	v_or_b32_e32 v112, 16, v150
	v_ashrrev_i32_e32 v113, 31, v112
	v_lshlrev_b64 v[114:115], 12, v[112:113]
	v_lshl_add_u64 v[116:117], s[66:67], 0, v[112:113]
	v_sub_u32_e32 v112, 0x800, v112
	v_ashrrev_i32_e32 v113, 31, v112
	v_lshl_add_u64 v[112:113], s[66:67], 0, v[112:113]
	v_lshlrev_b64 v[122:123], 11, v[112:113]
	v_lshl_add_u64 v[124:125], s[68:69], 0, v[114:115]
	v_mov_b32_e32 v153, v145
	v_sub_u32_e32 v112, s47, v151
	v_lshlrev_b64 v[120:121], 11, v[116:117]
	v_lshl_add_u64 v[126:127], v[124:125], 0, v[152:153]
	s_mov_b64 s[70:71], -1
	s_and_b64 vcc, exec, s[0:1]
	v_cmp_ne_u32_e64 s[4:5], 0, v151
	v_lshlrev_b32_e32 v144, 1, v112
	s_cbranch_vccnz .LBB0_625
	v_or_b32_e32 v130, v120, v189
	v_mov_b32_e32 v131, v121
	v_lshlrev_b64 v[134:135], 1, v[130:131]
	v_subrev_u32_e32 v248, s98, v126
	v_and_b32_e32 v249, 0xfffff000, v248
	v_and_b32_e32 v250, 0xfff, v248
	v_sub_u32_e32 v251, v250, v249
	v_add_u32_e32 v251, 0x800000, v251
	global_load_dwordx4 v[252:255], v251, s[100:101]
	global_load_dwordx4 v[112:115], v[126:127], off
	v_lshl_add_u64 v[130:131], s[44:45], 0, v[134:135]
	global_load_dwordx4 v[130:133], v[130:131], off
	v_lshl_add_u64 v[162:163], s[36:37], 0, v[134:135]
	v_mov_b32_e32 v129, 0
	s_waitcnt vmcnt(0)
	v_lshlrev_b32_e32 v116, 16, v112
	v_and_b32_e32 v117, 0xffff0000, v112
	v_lshlrev_b32_e32 v118, 16, v113
	v_and_b32_e32 v119, 0xffff0000, v113
	v_lshlrev_b32_e32 v112, 16, v114
	v_and_b32_e32 v113, 0xffff0000, v114
	v_lshlrev_b32_e32 v114, 16, v115
	v_and_b32_e32 v115, 0xffff0000, v115
	v_lshlrev_b32_e32 v154, 16, v130
	v_and_b32_e32 v155, 0xffff0000, v130
	v_lshlrev_b32_e32 v156, 16, v131
	v_and_b32_e32 v157, 0xffff0000, v131
	v_lshlrev_b32_e32 v158, 16, v132
	v_and_b32_e32 v159, 0xffff0000, v132
	v_lshlrev_b32_e32 v160, 16, v133
	v_and_b32_e32 v161, 0xffff0000, v133
	v_pk_add_f32 v[132:133], v[110:111], v[118:119]
	v_pk_add_f32 v[130:131], v[108:109], v[116:117]
	v_pk_mul_f32 v[164:165], v[132:133], v[156:157]
	v_pk_mul_f32 v[156:157], v[130:131], v[154:155]
	v_pk_add_f32 v[154:155], v[106:107], v[114:115]
	v_pk_add_f32 v[134:135], v[104:105], v[112:113]
	v_pk_mul_f32 v[160:161], v[154:155], v[160:161]
	v_pk_mul_f32 v[158:159], v[134:135], v[158:159]
	v_cvt_pk_bf16_f32 v156, v156, v157
	v_cvt_pk_bf16_f32 v157, v164, v165
	v_cvt_pk_bf16_f32 v158, v158, v159
	v_cvt_pk_bf16_f32 v159, v160, v161
	global_store_dwordx4 v[162:163], v[156:159], off
	v_sub_f32_e32 v115, v115, v107
	s_nop 0
	v_or_b32_e32 v156, v122, v189
	v_mov_b32_e32 v157, v123
	v_lshlrev_b64 v[160:161], 1, v[156:157]
	v_lshl_add_u64 v[156:157], s[44:45], 0, v[160:161]
	v_lshl_add_u64 v[170:171], s[36:37], 0, v[160:161]
	v_sub_f32_e32 v161, v119, v111
	v_mov_b32_e32 v156, v252
	v_mov_b32_e32 v157, v253
	v_mov_b32_e32 v158, v254
	v_mov_b32_e32 v159, v255
	v_lshlrev_b32_e32 v166, 16, v158
	v_and_b32_e32 v167, 0xffff0000, v158
	v_lshlrev_b32_e32 v168, 16, v159
	v_and_b32_e32 v169, 0xffff0000, v159
	v_sub_f32_e32 v158, v118, v110
	v_sub_f32_e32 v159, v117, v109
	v_lshlrev_b32_e32 v162, 16, v156
	v_and_b32_e32 v163, 0xffff0000, v156
	v_lshlrev_b32_e32 v164, 16, v157
	v_and_b32_e32 v165, 0xffff0000, v157
	v_sub_f32_e32 v156, v116, v108
	v_mov_b32_e32 v160, v158
	v_mov_b32_e32 v157, v159
	v_pk_mul_f32 v[118:119], v[160:161], v[164:165]
	v_pk_mul_f32 v[116:117], v[156:157], v[162:163]
	v_sub_f32_e32 v162, v114, v106
	v_sub_f32_e32 v163, v113, v105
	v_sub_f32_e32 v160, v112, v104
	v_mov_b32_e32 v114, v162
	v_mov_b32_e32 v164, v160
	v_mov_b32_e32 v165, v163
	v_pk_mul_f32 v[112:113], v[114:115], v[168:169]
	v_pk_mul_f32 v[164:165], v[164:165], v[166:167]
	v_cvt_pk_bf16_f32 v116, v116, v117
	v_cvt_pk_bf16_f32 v117, v118, v119
	v_cvt_pk_bf16_f32 v118, v164, v165
	v_cvt_pk_bf16_f32 v119, v112, v113
	v_lshl_add_u64 v[112:113], v[120:121], 1, s[44:45]
	global_store_dwordx4 v[170:171], v[116:119], off
	v_lshl_add_u64 v[112:113], v[112:113], 0, v[144:145]
	global_load_ushort v157, v[112:113], off offset:-14
	global_load_dwordx3 v[116:118], v[112:113], off offset:-12
	v_mov_b32_e32 v119, 0
	s_and_saveexec_b64 s[70:71], s[4:5]
	s_cbranch_execz .LBB0_618
	global_load_ushort v112, v[112:113], off
	s_waitcnt vmcnt(0)
	v_lshlrev_b32_e32 v129, 16, v112

; DI void fnet_layer(const Args& A, LAS unsigned char* lds, const XcdBarrier& gbar, int layer, int j, bool latonly, int wv) {
;     ...
;             bf16_t* ap = A1 + ((size_t)u.i0 * 1024 + k) * DM + col;
;             if (u.i2 < 8) { st_bf16x8(ap, v0, v1); return; }
;             f32x4 a0, a1; ld_bf16x8(ap, a0, a1);
;             const size_t off = ((size_t)u.i0 * TB + k) * DM + col;
;             f32x4 g0, g1; ld_bf16x8(Gt + off, g0, g1);
;             st_bf16x8(U + off, (a0 + v0) * g0, (a1 + v1) * g1);
;             if (k != 0) { const size_t off2 = ((size_t)u.i0 * TB + (TL - k)) * DM + col; ld_bf16x8(Gt + off2, g0, g1); st_bf16x8(U + off2, (a0 - v0) * g0, (a1 - v1) * g1); }
;             const f32x4 s0 = a0 + v0, s1 = a1 + v1, d0 = a0 - v0, d1 = a1 - v1;
;             const float sm[8] = {s0[0], s0[1], s0[2], s0[3], s1[0], s1[1], s1[2], s1[3]}, df[8] = {d0[0], d0[1], d0[2], d0[3], d1[0], d1[1], d1[2], d1[3]};
;             const size_t rowk = ((size_t)u.i0 * TB + k) * DM, rowT = ((size_t)u.i0 * TB + (TL - k)) * DM; const int cm = (col & ~255) + 512 - col_l;
;             {
;                 const bf16_t* gk_ = Gt + rowk + cm - 8; const bf16_t* gT_ = Gt + rowT + cm - 8; bf16_t* uk_ = U + rowk + cm - 8; bf16_t* uT_ = U + rowT + cm - 8;
;                 const unsigned short ka1 = gk_[1]; const unsigned ka2 = *(const unsigned*)(gk_ + 2); const u32x2 ka4 = *(const u32x2*)(gk_ + 4); const unsigned short ka0 = col_l ? gk_[8] : (unsigned short)0;
;                 unsigned short ta1 = 0, ta0 = 0; unsigned ta2 = 0; u32x2 ta4 = {0u, 0u};
;                 if (k != 0) { ta1 = gT_[1]; ta2 = *(const unsigned*)(gT_ + 2); ta4 = *(const u32x2*)(gT_ + 4); ta0 = col_l ? gT_[8] : (unsigned short)0; }
;                 uk_[1] = (bf16_t)(pk2(df[7] * __uint_as_float((unsigned)ka1 << 16), 0.f) & 0xffffu);
;                 *(unsigned*)(uk_ + 2) = pk2(df[6] * bf_lo(ka2), df[5] * bf_hi(ka2));
;                 *(u32x2*)(uk_ + 4) = (u32x2){pk2(df[4] * bf_lo(ka4.x), df[3] * bf_hi(ka4.x)), pk2(df[2] * bf_lo(ka4.y), df[1] * bf_hi(ka4.y))};
;                 if (col_l) uk_[8] = (bf16_t)(pk2(df[0] * __uint_as_float((unsigned)ka0 << 16), 0.f) & 0xffffu);
;                 if (k != 0) {
;                     uT_[1] = (bf16_t)(pk2(sm[7] * __uint_as_float((unsigned)ta1 << 16), 0.f) & 0xffffu);
;                     *(unsigned*)(uT_ + 2) = pk2(sm[6] * bf_lo(ta2), sm[5] * bf_hi(ta2));
.LBB0_627:
	v_mov_b32_e32 v129, v145
	v_sub_u32_e32 v104, s47, v173
	v_lshl_add_u64 v[106:107], v[124:125], 0, v[128:129]
	s_mov_b64 s[4:5], -1
	s_and_b64 vcc, exec, s[0:1]
	v_lshlrev_b32_e32 v104, 1, v104
	s_cbranch_vccnz .LBB0_629
	v_or_b32_e32 v112, v120, v172
	v_mov_b32_e32 v113, v121
	v_lshlrev_b64 v[116:117], 1, v[112:113]
	v_subrev_u32_e32 v248, s98, v106
	v_add_u32_e32 v248, 256, v248
	v_and_b32_e32 v249, 0xfffff000, v248
	v_and_b32_e32 v250, 0xfff, v248
	v_sub_u32_e32 v251, v250, v249
	v_add_u32_e32 v251, 0x800000, v251
	global_load_dwordx4 v[252:255], v251, s[100:101]
	global_load_dwordx4 v[108:111], v[106:107], off offset:256
	v_lshl_add_u64 v[112:113], s[44:45], 0, v[116:117]
	global_load_dwordx4 v[112:115], v[112:113], off
	v_or_b32_e32 v118, v122, v172
	v_mov_b32_e32 v119, v123
	v_lshlrev_b64 v[118:119], 1, v[118:119]
	v_lshl_add_u64 v[116:117], s[36:37], 0, v[116:117]
	v_lshl_add_u64 v[124:125], s[44:45], 0, v[118:119]
	v_mov_b32_e32 v105, v145
	v_lshl_add_u64 v[118:119], s[36:37], 0, v[118:119]
	s_mov_b64 s[4:5], 0
	s_waitcnt vmcnt(0)
	v_lshlrev_b32_e32 v126, 16, v108
	v_and_b32_e32 v127, 0xffff0000, v108
	v_lshlrev_b32_e32 v130, 16, v109
	v_and_b32_e32 v131, 0xffff0000, v109
	v_lshlrev_b32_e32 v132, 16, v110
	v_and_b32_e32 v133, 0xffff0000, v110
	v_lshlrev_b32_e32 v134, 16, v111
	v_and_b32_e32 v135, 0xffff0000, v111
	v_pk_add_f32 v[154:155], v[100:101], v[126:127]
	v_pk_add_f32 v[156:157], v[102:103], v[130:131]
	v_pk_add_f32 v[158:159], v[96:97], v[132:133]
	v_pk_add_f32 v[160:161], v[98:99], v[134:135]
	v_lshlrev_b32_e32 v108, 16, v112
	v_and_b32_e32 v109, 0xffff0000, v112
	v_lshlrev_b32_e32 v110, 16, v113
	v_and_b32_e32 v111, 0xffff0000, v113
	v_lshlrev_b32_e32 v112, 16, v114
	v_and_b32_e32 v113, 0xffff0000, v114
	v_lshlrev_b32_e32 v114, 16, v115
	v_and_b32_e32 v115, 0xffff0000, v115
	v_pk_mul_f32 v[110:111], v[156:157], v[110:111]
	v_pk_mul_f32 v[108:109], v[154:155], v[108:109]
	v_pk_mul_f32 v[114:115], v[160:161], v[114:115]
	v_pk_mul_f32 v[112:113], v[158:159], v[112:113]
	v_cvt_pk_bf16_f32 v108, v108, v109
	v_cvt_pk_bf16_f32 v109, v110, v111
	v_cvt_pk_bf16_f32 v110, v112, v113
	v_cvt_pk_bf16_f32 v111, v114, v115
	global_store_dwordx4 v[116:117], v[108:111], off
	v_lshlrev_b64 v[116:117], 1, v[120:121]
	v_lshlrev_b64 v[120:121], 1, v[122:123]
	v_sub_f32_e32 v123, v127, v101
	v_sub_f32_e32 v122, v126, v100
	v_sub_f32_e32 v125, v131, v103
	v_sub_f32_e32 v124, v130, v102
	v_sub_f32_e32 v127, v133, v97
	v_sub_f32_e32 v126, v132, v96
	v_sub_f32_e32 v131, v135, v99
	v_sub_f32_e32 v130, v134, v98
	v_lshl_add_u64 v[112:113], s[44:45], 0, v[116:117]
	v_lshl_add_u64 v[114:115], s[44:45], 0, v[120:121]
	v_lshl_add_u64 v[112:113], v[112:113], 0, v[104:105]
	v_lshl_add_u64 v[114:115], v[114:115], 0, v[104:105]
	v_lshl_add_u64 v[116:117], s[36:37], 0, v[116:117]
	v_lshl_add_u64 v[116:117], v[116:117], 0, v[104:105]
	v_mov_b32_e32 v108, v252
	v_mov_b32_e32 v109, v253
	v_mov_b32_e32 v110, v254
	v_mov_b32_e32 v111, v255
	v_lshlrev_b32_e32 v132, 16, v108
	v_and_b32_e32 v133, 0xffff0000, v108
	v_lshlrev_b32_e32 v108, 16, v109
	v_and_b32_e32 v109, 0xffff0000, v109
	v_lshlrev_b32_e32 v134, 16, v110
	v_and_b32_e32 v135, 0xffff0000, v110
	v_lshlrev_b32_e32 v110, 16, v111
	v_and_b32_e32 v111, 0xffff0000, v111
	v_pk_mul_f32 v[162:163], v[124:125], v[108:109]
	v_pk_mul_f32 v[108:109], v[122:123], v[132:133]
	v_pk_mul_f32 v[132:133], v[130:131], v[110:111]
	v_pk_mul_f32 v[110:111], v[126:127], v[134:135]
	v_cvt_pk_bf16_f32 v108, v108, v109
	v_cvt_pk_bf16_f32 v109, v162, v163
	v_cvt_pk_bf16_f32 v110, v110, v111
	v_cvt_pk_bf16_f32 v111, v132, v133
	global_store_dwordx4 v[118:119], v[108:111], off
	global_load_ushort v111, v[112:113], off
	s_nop 0
	global_load_ushort v129, v[114:115], off
	global_load_ushort v132, v[114:115], off offset:-14
	global_load_ushort v133, v[112:113], off offset:-14
	global_load_dwordx3 v[108:110], v[112:113], off offset:-12
	s_nop 0
	global_load_dwordx3 v[112:114], v[114:115], off offset:-12
	v_lshl_add_u64 v[118:119], s[36:37], 0, v[120:121]
	v_lshl_add_u64 v[118:119], v[118:119], 0, v[104:105]
	s_waitcnt vmcnt(5)
	v_lshlrev_b32_e32 v105, 16, v111
	s_waitcnt vmcnt(4)
	v_lshlrev_b32_e32 v115, 16, v129
	s_waitcnt vmcnt(3)
	v_lshlrev_b32_e32 v129, 16, v132
	s_waitcnt vmcnt(2)
	v_lshlrev_b32_e32 v153, 16, v133
	s_waitcnt vmcnt(1)
	v_lshlrev_b32_e32 v120, 16, v108
	v_and_b32_e32 v121, 0xffff0000, v108
	v_lshlrev_b32_e32 v108, 16, v109
	v_and_b32_e32 v109, 0xffff0000, v109
	v_lshlrev_b32_e32 v132, 16, v110
	v_and_b32_e32 v133, 0xffff0000, v110
	s_waitcnt vmcnt(0)
	v_lshlrev_b32_e32 v110, 16, v112
	v_and_b32_e32 v111, 0xffff0000, v112
	v_lshlrev_b32_e32 v112, 16, v113
	v_and_b32_e32 v113, 0xffff0000, v113
	v_lshlrev_b32_e32 v134, 16, v114
	v_and_b32_e32 v135, 0xffff0000, v114
	v_mul_f32_e32 v114, v131, v153
	v_mov_b32_e32 v131, v127
	v_mov_b32_e32 v127, v125
	v_mov_b32_e32 v125, v123
	v_mul_f32_e32 v105, v122, v105
	v_mul_f32_e32 v122, v161, v129
	v_mov_b32_e32 v161, v159
	v_mov_b32_e32 v159, v157
	v_mov_b32_e32 v157, v155
	v_mul_f32_e32 v129, v154, v115
	v_cvt_pk_bf16_f32 v153, v114, s0
	v_pk_mul_f32 v[114:115], v[130:131], v[120:121]
	v_pk_mul_f32 v[108:109], v[126:127], v[108:109]
	v_pk_mul_f32 v[120:121], v[124:125], v[132:133]
	v_cvt_pk_bf16_f32 v105, v105, s0
	v_cvt_pk_bf16_f32 v124, v122, s0
	v_pk_mul_f32 v[110:111], v[160:161], v[110:111]
	v_pk_mul_f32 v[112:113], v[158:159], v[112:113]
	v_pk_mul_f32 v[122:123], v[156:157], v[134:135]
	v_cvt_pk_bf16_f32 v125, v129, s0
	v_cvt_pk_bf16_f32 v114, v114, v115
	v_cvt_pk_bf16_f32 v108, v108, v109
	global_store_short v[116:117], v105, off
	v_cvt_pk_bf16_f32 v105, v110, v111
	v_cvt_pk_bf16_f32 v110, v112, v113
	v_cvt_pk_bf16_f32 v111, v122, v123
	v_cvt_pk_bf16_f32 v109, v120, v121
	global_store_short v[118:119], v125, off
	v_perm_b32 v112, v114, v153, s46
	global_store_short_d16_hi v[116:117], v114, off offset:-10
	global_store_dwordx2 v[116:117], v[108:109], off offset:-8
	v_perm_b32 v108, v105, v124, s46
	global_store_dwordx2 v[118:119], v[110:111], off offset:-8
	global_store_dword v[116:117], v112, off offset:-14
	global_store_short_d16_hi v[118:119], v105, off offset:-10
	global_store_dword v[118:119], v108, off offset:-14

; DI void st_bf16x8(bf16_t* p, f32x4 a, f32x4 b) { u32x4 w = {pk2(a[0], a[1]), pk2(a[2], a[3]), pk2(b[0], b[1]), pk2(b[2], b[3])}; *(u32x4*)p = w; }
; DI void ld_bf16x8(const bf16_t* p, f32x4& a, f32x4& b) { const u32x4 w = *(const u32x4*)p; a = (f32x4){bf_lo(w.x), bf_hi(w.x), bf_lo(w.y), bf_hi(w.y)}; b = (f32x4){bf_lo(w.z), bf_hi(w.z), bf_lo(w.w), bf_hi(w.w)}; }
; DI void fnet_layer(const Args& A, LAS unsigned char* lds, const XcdBarrier& gbar, int layer, int j, bool latonly, int wv) {
;     ...
;         auto E = [=](const pg8::Unit& u, int row_l, int col_l, f32x4 v0, f32x4 v1) {
;             const int k = u.i1 * 256 + row_l, col = (u.i2 & 7) * 256 + col_l;
;             bf16_t* ap = A1 + ((size_t)u.i0 * 1024 + k) * DM + col;
;             if (u.i2 < 8) { st_bf16x8(ap, v0, v1); return; }
;             f32x4 a0, a1; ld_bf16x8(ap, a0, a1);
;             const size_t off = ((size_t)u.i0 * TB + k) * DM + col;
;             f32x4 g0, g1; ld_bf16x8(Gt + off, g0, g1);
;             st_bf16x8(U + off, (a0 + v0) * g0, (a1 + v1) * g1);
;             if (k != 0) { const size_t off2 = ((size_t)u.i0 * TB + (TL - k)) * DM + col; ld_bf16x8(Gt + off2, g0, g1); st_bf16x8(U + off2, (a0 - v0) * g0, (a1 - v1) * g1); }
;             const f32x4 s0 = a0 + v0, s1 = a1 + v1, d0 = a0 - v0, d1 = a1 - v1;
;             const float sm[8] = {s0[0], s0[1], s0[2], s0[3], s1[0], s1[1], s1[2], s1[3]}, df[8] = {d0[0], d0[1], d0[2], d0[3], d1[0], d1[1], d1[2], d1[3]};
;             const size_t rowk = ((size_t)u.i0 * TB + k) * DM, rowT = ((size_t)u.i0 * TB + (TL - k)) * DM; const int cm = (col & ~255) + 512 - col_l;
;             {
;                 const bf16_t* gk_ = Gt + rowk + cm - 8; const bf16_t* gT_ = Gt + rowT + cm - 8; bf16_t* uk_ = U + rowk + cm - 8; bf16_t* uT_ = U + rowT + cm - 8;
;                 const unsigned short ka1 = gk_[1]; const unsigned ka2 = *(const unsigned*)(gk_ + 2); const u32x2 ka4 = *(const u32x2*)(gk_ + 4); const unsigned short ka0 = col_l ? gk_[8] : (unsigned short)0;
;                 unsigned short ta1 = 0, ta0 = 0; unsigned ta2 = 0; u32x2 ta4 = {0u, 0u};
;                 if (k != 0) { ta1 = gT_[1]; ta2 = *(const unsigned*)(gT_ + 2); ta4 = *(const u32x2*)(gT_ + 4); ta0 = col_l ? gT_[8] : (unsigned short)0; }
.LBB0_631:
	v_or_b32_e32 v96, 32, v150
	v_ashrrev_i32_e32 v97, 31, v96
	v_lshlrev_b64 v[98:99], 12, v[96:97]
	v_lshl_add_u64 v[100:101], s[66:67], 0, v[96:97]
	v_sub_u32_e32 v96, 0x800, v96
	v_ashrrev_i32_e32 v97, 31, v96
	v_lshl_add_u64 v[96:97], s[66:67], 0, v[96:97]
	v_lshl_add_u64 v[110:111], s[68:69], 0, v[98:99]
	v_mov_b32_e32 v153, v145
	v_lshlrev_b64 v[106:107], 11, v[100:101]
	v_lshlrev_b64 v[108:109], 11, v[96:97]
	v_lshl_add_u64 v[112:113], v[110:111], 0, v[152:153]
	s_and_b64 vcc, exec, s[0:1]
	s_mov_b64 s[4:5], -1
	s_cbranch_vccnz .LBB0_641
	v_or_b32_e32 v100, v106, v189
	v_mov_b32_e32 v101, v107
	v_lshlrev_b64 v[114:115], 1, v[100:101]
	v_subrev_u32_e32 v248, s98, v112
	v_and_b32_e32 v249, 0xfffff000, v248
	v_and_b32_e32 v250, 0xfff, v248
	v_sub_u32_e32 v251, v250, v249
	v_add_u32_e32 v251, 0x800000, v251
	global_load_dwordx4 v[252:255], v251, s[100:101]
	global_load_dwordx4 v[96:99], v[112:113], off
	v_lshl_add_u64 v[100:101], s[44:45], 0, v[114:115]
	global_load_dwordx4 v[100:103], v[100:101], off
	v_or_b32_e32 v116, v108, v189
	v_mov_b32_e32 v117, v109
	v_lshlrev_b64 v[122:123], 1, v[116:117]
	v_lshl_add_u64 v[124:125], s[36:37], 0, v[114:115]
	v_lshl_add_u64 v[126:127], s[44:45], 0, v[122:123]
	v_lshl_add_u64 v[156:157], s[36:37], 0, v[122:123]
	v_cmp_ne_u32_e32 vcc, 0, v151
	v_mov_b32_e32 v105, 0
	s_waitcnt vmcnt(0)
	v_lshlrev_b32_e32 v130, 16, v96
	v_and_b32_e32 v131, 0xffff0000, v96
	v_lshlrev_b32_e32 v132, 16, v97
	v_and_b32_e32 v133, 0xffff0000, v97
	v_lshlrev_b32_e32 v134, 16, v98
	v_and_b32_e32 v135, 0xffff0000, v98
	v_lshlrev_b32_e32 v154, 16, v99
	v_and_b32_e32 v155, 0xffff0000, v99
	v_pk_add_f32 v[116:117], v[94:95], v[132:133]
	v_pk_add_f32 v[114:115], v[92:93], v[130:131]
	v_pk_add_f32 v[120:121], v[90:91], v[154:155]
	v_pk_add_f32 v[118:119], v[88:89], v[134:135]
	v_lshlrev_b32_e32 v96, 16, v100
	v_and_b32_e32 v97, 0xffff0000, v100
	v_lshlrev_b32_e32 v98, 16, v101
	v_and_b32_e32 v99, 0xffff0000, v101
	v_lshlrev_b32_e32 v100, 16, v102
	v_and_b32_e32 v101, 0xffff0000, v102
	v_lshlrev_b32_e32 v102, 16, v103
	v_and_b32_e32 v103, 0xffff0000, v103
	v_pk_mul_f32 v[98:99], v[116:117], v[98:99]
	v_pk_mul_f32 v[96:97], v[114:115], v[96:97]
	v_pk_mul_f32 v[102:103], v[120:121], v[102:103]
	v_pk_mul_f32 v[100:101], v[118:119], v[100:101]
	v_cvt_pk_bf16_f32 v96, v96, v97
	v_cvt_pk_bf16_f32 v97, v98, v99
	v_cvt_pk_bf16_f32 v98, v100, v101
	v_cvt_pk_bf16_f32 v99, v102, v103
	global_store_dwordx4 v[124:125], v[96:99], off
	v_sub_f32_e32 v124, v132, v94
	v_sub_f32_e32 v127, v133, v95
	v_sub_f32_e32 v122, v130, v92
	v_sub_f32_e32 v99, v155, v91
	v_sub_f32_e32 v130, v154, v90
	v_mov_b32_e32 v126, v124
	v_sub_f32_e32 v125, v131, v93
	v_sub_f32_e32 v131, v135, v89
	v_mov_b32_e32 v123, v125
	v_mov_b32_e32 v98, v130
	v_mov_b32_e32 v133, v131
	v_lshl_add_u64 v[96:97], v[106:107], 1, s[44:45]
	v_lshl_add_u64 v[96:97], v[96:97], 0, v[144:145]
	v_mov_b32_e32 v100, v252
	v_mov_b32_e32 v101, v253
	v_mov_b32_e32 v102, v254
	v_mov_b32_e32 v103, v255
	v_lshlrev_b32_e32 v154, 16, v100
	v_and_b32_e32 v155, 0xffff0000, v100
	v_lshlrev_b32_e32 v100, 16, v101
	v_and_b32_e32 v101, 0xffff0000, v101
	v_pk_mul_f32 v[160:161], v[126:127], v[100:101]
	v_sub_f32_e32 v126, v134, v88
	v_lshlrev_b32_e32 v158, 16, v102
	v_and_b32_e32 v159, 0xffff0000, v102
	v_lshlrev_b32_e32 v102, 16, v103
	v_and_b32_e32 v103, 0xffff0000, v103
	v_mov_b32_e32 v132, v126
	v_pk_mul_f32 v[100:101], v[122:123], v[154:155]
	v_pk_mul_f32 v[102:103], v[98:99], v[102:103]
	v_pk_mul_f32 v[132:133], v[132:133], v[158:159]
	v_cvt_pk_bf16_f32 v100, v100, v101
	v_cvt_pk_bf16_f32 v101, v160, v161
	v_cvt_pk_bf16_f32 v103, v102, v103
	v_cvt_pk_bf16_f32 v102, v132, v133
	global_store_dwordx4 v[156:157], v[100:103], off
	global_load_ushort v129, v[96:97], off offset:-14
	s_nop 0
	global_load_dwordx3 v[100:102], v[96:97], off offset:-12
	v_mov_b32_e32 v103, 0
	s_and_saveexec_b64 s[4:5], vcc
	s_cbranch_execz .LBB0_634
	global_load_ushort v96, v[96:97], off
	s_waitcnt vmcnt(0)
	v_lshlrev_b32_e32 v105, 16, v96

; DI void fnet_layer(const Args& A, LAS unsigned char* lds, const XcdBarrier& gbar, int layer, int j, bool latonly, int wv) {
;     ...
;             bf16_t* ap = A1 + ((size_t)u.i0 * 1024 + k) * DM + col;
;             if (u.i2 < 8) { st_bf16x8(ap, v0, v1); return; }
;             f32x4 a0, a1; ld_bf16x8(ap, a0, a1);
;             const size_t off = ((size_t)u.i0 * TB + k) * DM + col;
;             f32x4 g0, g1; ld_bf16x8(Gt + off, g0, g1);
;             st_bf16x8(U + off, (a0 + v0) * g0, (a1 + v1) * g1);
;             if (k != 0) { const size_t off2 = ((size_t)u.i0 * TB + (TL - k)) * DM + col; ld_bf16x8(Gt + off2, g0, g1); st_bf16x8(U + off2, (a0 - v0) * g0, (a1 - v1) * g1); }
;             const f32x4 s0 = a0 + v0, s1 = a1 + v1, d0 = a0 - v0, d1 = a1 - v1;
;             const float sm[8] = {s0[0], s0[1], s0[2], s0[3], s1[0], s1[1], s1[2], s1[3]}, df[8] = {d0[0], d0[1], d0[2], d0[3], d1[0], d1[1], d1[2], d1[3]};
;             const size_t rowk = ((size_t)u.i0 * TB + k) * DM, rowT = ((size_t)u.i0 * TB + (TL - k)) * DM; const int cm = (col & ~255) + 512 - col_l;
;             {
;                 const bf16_t* gk_ = Gt + rowk + cm - 8; const bf16_t* gT_ = Gt + rowT + cm - 8; bf16_t* uk_ = U + rowk + cm - 8; bf16_t* uT_ = U + rowT + cm - 8;
;                 const unsigned short ka1 = gk_[1]; const unsigned ka2 = *(const unsigned*)(gk_ + 2); const u32x2 ka4 = *(const u32x2*)(gk_ + 4); const unsigned short ka0 = col_l ? gk_[8] : (unsigned short)0;
;                 unsigned short ta1 = 0, ta0 = 0; unsigned ta2 = 0; u32x2 ta4 = {0u, 0u};
;                 if (k != 0) { ta1 = gT_[1]; ta2 = *(const unsigned*)(gT_ + 2); ta4 = *(const u32x2*)(gT_ + 4); ta0 = col_l ? gT_[8] : (unsigned short)0; }
;                 uk_[1] = (bf16_t)(pk2(df[7] * __uint_as_float((unsigned)ka1 << 16), 0.f) & 0xffffu);
;                 *(unsigned*)(uk_ + 2) = pk2(df[6] * bf_lo(ka2), df[5] * bf_hi(ka2));
;                 *(u32x2*)(uk_ + 4) = (u32x2){pk2(df[4] * bf_lo(ka4.x), df[3] * bf_hi(ka4.x)), pk2(df[2] * bf_lo(ka4.y), df[1] * bf_hi(ka4.y))};
;                 if (col_l) uk_[8] = (bf16_t)(pk2(df[0] * __uint_as_float((unsigned)ka0 << 16), 0.f) & 0xffffu);
;                 if (k != 0) {
;                     uT_[1] = (bf16_t)(pk2(sm[7] * __uint_as_float((unsigned)ta1 << 16), 0.f) & 0xffffu);
;                     *(unsigned*)(uT_ + 2) = pk2(sm[6] * bf_lo(ta2), sm[5] * bf_hi(ta2));
.LBB0_643:
	v_mov_b32_e32 v129, v145
	v_lshl_add_u64 v[88:89], v[110:111], 0, v[128:129]
	s_and_b64 vcc, exec, s[0:1]
	s_mov_b64 s[4:5], -1
	s_cbranch_vccnz .LBB0_645
	v_or_b32_e32 v94, v106, v172
	v_mov_b32_e32 v95, v107
	v_lshlrev_b64 v[98:99], 1, v[94:95]
	v_subrev_u32_e32 v248, s98, v88
	v_add_u32_e32 v248, 256, v248
	v_and_b32_e32 v249, 0xfffff000, v248
	v_and_b32_e32 v250, 0xfff, v248
	v_sub_u32_e32 v251, v250, v249
	v_add_u32_e32 v251, 0x800000, v251
	global_load_dwordx4 v[252:255], v251, s[100:101]
	global_load_dwordx4 v[90:93], v[88:89], off offset:256
	v_lshl_add_u64 v[94:95], s[44:45], 0, v[98:99]
	global_load_dwordx4 v[94:97], v[94:95], off
	v_or_b32_e32 v100, v108, v172
	v_mov_b32_e32 v101, v109
	v_lshlrev_b64 v[100:101], 1, v[100:101]
	v_lshl_add_u64 v[98:99], s[36:37], 0, v[98:99]
	v_lshl_add_u64 v[102:103], s[44:45], 0, v[100:101]
	v_mov_b32_e32 v105, v145
	v_lshl_add_u64 v[100:101], s[36:37], 0, v[100:101]
	s_mov_b64 s[4:5], 0
	s_waitcnt vmcnt(0)
	v_lshlrev_b32_e32 v110, 16, v90
	v_and_b32_e32 v111, 0xffff0000, v90
	v_lshlrev_b32_e32 v112, 16, v91
	v_and_b32_e32 v113, 0xffff0000, v91
	v_lshlrev_b32_e32 v114, 16, v92
	v_and_b32_e32 v115, 0xffff0000, v92
	v_lshlrev_b32_e32 v116, 16, v93
	v_and_b32_e32 v117, 0xffff0000, v93
	v_pk_add_f32 v[118:119], v[84:85], v[110:111]
	v_pk_add_f32 v[120:121], v[86:87], v[112:113]
	v_pk_add_f32 v[122:123], v[80:81], v[114:115]
	v_pk_add_f32 v[124:125], v[82:83], v[116:117]
	v_lshlrev_b32_e32 v90, 16, v94
	v_and_b32_e32 v91, 0xffff0000, v94
	v_lshlrev_b32_e32 v92, 16, v95
	v_and_b32_e32 v93, 0xffff0000, v95
	v_lshlrev_b32_e32 v94, 16, v96
	v_and_b32_e32 v95, 0xffff0000, v96
	v_lshlrev_b32_e32 v96, 16, v97
	v_and_b32_e32 v97, 0xffff0000, v97
	v_pk_mul_f32 v[92:93], v[120:121], v[92:93]
	v_pk_mul_f32 v[90:91], v[118:119], v[90:91]
	v_pk_mul_f32 v[96:97], v[124:125], v[96:97]
	v_pk_mul_f32 v[94:95], v[122:123], v[94:95]
	v_cvt_pk_bf16_f32 v90, v90, v91
	v_cvt_pk_bf16_f32 v91, v92, v93
	v_cvt_pk_bf16_f32 v92, v94, v95
	v_cvt_pk_bf16_f32 v93, v96, v97
	global_store_dwordx4 v[98:99], v[90:93], off
	v_lshlrev_b64 v[98:99], 1, v[106:107]
	v_lshlrev_b64 v[102:103], 1, v[108:109]
	v_sub_f32_e32 v107, v111, v85
	v_sub_f32_e32 v106, v110, v84
	v_sub_f32_e32 v109, v113, v87
	v_sub_f32_e32 v108, v112, v86
	v_sub_f32_e32 v111, v115, v81
	v_sub_f32_e32 v110, v114, v80
	v_sub_f32_e32 v113, v117, v83
	v_sub_f32_e32 v112, v116, v82
	v_lshl_add_u64 v[94:95], s[44:45], 0, v[98:99]
	v_lshl_add_u64 v[96:97], s[44:45], 0, v[102:103]
	v_lshl_add_u64 v[94:95], v[94:95], 0, v[104:105]
	v_lshl_add_u64 v[96:97], v[96:97], 0, v[104:105]
	v_lshl_add_u64 v[98:99], s[36:37], 0, v[98:99]
	v_lshl_add_u64 v[98:99], v[98:99], 0, v[104:105]
	v_mov_b32_e32 v90, v252
	v_mov_b32_e32 v91, v253
	v_mov_b32_e32 v92, v254
	v_mov_b32_e32 v93, v255
	v_lshlrev_b32_e32 v114, 16, v90
	v_and_b32_e32 v115, 0xffff0000, v90
	v_lshlrev_b32_e32 v90, 16, v91
	v_and_b32_e32 v91, 0xffff0000, v91
	v_lshlrev_b32_e32 v116, 16, v92
	v_and_b32_e32 v117, 0xffff0000, v92
	v_lshlrev_b32_e32 v92, 16, v93
	v_and_b32_e32 v93, 0xffff0000, v93
	v_pk_mul_f32 v[126:127], v[108:109], v[90:91]
	v_pk_mul_f32 v[90:91], v[106:107], v[114:115]
	v_pk_mul_f32 v[114:115], v[112:113], v[92:93]
	v_pk_mul_f32 v[92:93], v[110:111], v[116:117]
	v_cvt_pk_bf16_f32 v90, v90, v91
	v_cvt_pk_bf16_f32 v91, v126, v127
	v_cvt_pk_bf16_f32 v92, v92, v93
	v_cvt_pk_bf16_f32 v93, v114, v115
	global_store_dwordx4 v[100:101], v[90:93], off
	global_load_ushort v93, v[94:95], off
	s_nop 0
	global_load_ushort v114, v[96:97], off
	global_load_ushort v115, v[96:97], off offset:-14
	global_load_ushort v116, v[94:95], off offset:-14
	global_load_dwordx3 v[90:92], v[94:95], off offset:-12
	s_nop 0
	global_load_dwordx3 v[94:96], v[96:97], off offset:-12
	v_lshl_add_u64 v[100:101], s[36:37], 0, v[102:103]
	v_lshl_add_u64 v[100:101], v[100:101], 0, v[104:105]
	s_waitcnt vmcnt(5)
	v_lshlrev_b32_e32 v97, 16, v93
	s_waitcnt vmcnt(4)
	v_lshlrev_b32_e32 v105, 16, v114
	s_waitcnt vmcnt(3)
	v_lshlrev_b32_e32 v126, 16, v115
	s_waitcnt vmcnt(2)
	v_lshlrev_b32_e32 v127, 16, v116
	s_waitcnt vmcnt(1)
	v_lshlrev_b32_e32 v102, 16, v90
	v_and_b32_e32 v103, 0xffff0000, v90
	v_lshlrev_b32_e32 v90, 16, v91
	v_and_b32_e32 v91, 0xffff0000, v91
	v_lshlrev_b32_e32 v114, 16, v92
	v_and_b32_e32 v115, 0xffff0000, v92
	s_waitcnt vmcnt(0)
	v_lshlrev_b32_e32 v92, 16, v94
	v_and_b32_e32 v93, 0xffff0000, v94
	v_lshlrev_b32_e32 v94, 16, v95
	v_and_b32_e32 v95, 0xffff0000, v95
	v_lshlrev_b32_e32 v116, 16, v96
	v_and_b32_e32 v117, 0xffff0000, v96
	v_mul_f32_e32 v96, v113, v127
	v_mov_b32_e32 v113, v111
	v_mov_b32_e32 v111, v109
	v_mov_b32_e32 v109, v107
	v_mul_f32_e32 v106, v106, v97
	v_mul_f32_e32 v107, v125, v126
	v_mov_b32_e32 v125, v123
	v_mov_b32_e32 v123, v121
	v_mov_b32_e32 v121, v119
	v_mul_f32_e32 v105, v118, v105
	v_cvt_pk_bf16_f32 v118, v96, s0
	v_pk_mul_f32 v[96:97], v[112:113], v[102:103]
	v_pk_mul_f32 v[90:91], v[110:111], v[90:91]
	v_pk_mul_f32 v[102:103], v[108:109], v[114:115]
	v_cvt_pk_bf16_f32 v108, v106, s0
	v_cvt_pk_bf16_f32 v109, v107, s0
	v_pk_mul_f32 v[92:93], v[124:125], v[92:93]
	v_pk_mul_f32 v[94:95], v[122:123], v[94:95]
	v_pk_mul_f32 v[106:107], v[120:121], v[116:117]
	v_cvt_pk_bf16_f32 v105, v105, s0
	v_cvt_pk_bf16_f32 v96, v96, v97
	v_cvt_pk_bf16_f32 v90, v90, v91
	v_cvt_pk_bf16_f32 v97, v92, v93
	v_cvt_pk_bf16_f32 v92, v94, v95
	v_cvt_pk_bf16_f32 v93, v106, v107
	v_cvt_pk_bf16_f32 v91, v102, v103
	global_store_short v[98:99], v108, off
	global_store_short v[100:101], v105, off
	v_perm_b32 v94, v96, v118, s46
	global_store_short_d16_hi v[98:99], v96, off offset:-10
	global_store_dwordx2 v[98:99], v[90:91], off offset:-8
	v_perm_b32 v90, v97, v109, s46
	global_store_dwordx2 v[100:101], v[92:93], off offset:-8
	global_store_dword v[98:99], v94, off offset:-14
	global_store_short_d16_hi v[100:101], v97, off offset:-10
	global_store_dword v[100:101], v90, off offset:-14

; DI void st_bf16x8(bf16_t* p, f32x4 a, f32x4 b) { u32x4 w = {pk2(a[0], a[1]), pk2(a[2], a[3]), pk2(b[0], b[1]), pk2(b[2], b[3])}; *(u32x4*)p = w; }
; DI void ld_bf16x8(const bf16_t* p, f32x4& a, f32x4& b) { const u32x4 w = *(const u32x4*)p; a = (f32x4){bf_lo(w.x), bf_hi(w.x), bf_lo(w.y), bf_hi(w.y)}; b = (f32x4){bf_lo(w.z), bf_hi(w.z), bf_lo(w.w), bf_hi(w.w)}; }
; DI void fnet_layer(const Args& A, LAS unsigned char* lds, const XcdBarrier& gbar, int layer, int j, bool latonly, int wv) {
;     ...
;         auto E = [=](const pg8::Unit& u, int row_l, int col_l, f32x4 v0, f32x4 v1) {
;             const int k = u.i1 * 256 + row_l, col = (u.i2 & 7) * 256 + col_l;
;             bf16_t* ap = A1 + ((size_t)u.i0 * 1024 + k) * DM + col;
;             if (u.i2 < 8) { st_bf16x8(ap, v0, v1); return; }
;             f32x4 a0, a1; ld_bf16x8(ap, a0, a1);
;             const size_t off = ((size_t)u.i0 * TB + k) * DM + col;
;             f32x4 g0, g1; ld_bf16x8(Gt + off, g0, g1);
;             st_bf16x8(U + off, (a0 + v0) * g0, (a1 + v1) * g1);
;             if (k != 0) { const size_t off2 = ((size_t)u.i0 * TB + (TL - k)) * DM + col; ld_bf16x8(Gt + off2, g0, g1); st_bf16x8(U + off2, (a0 - v0) * g0, (a1 - v1) * g1); }
;             const f32x4 s0 = a0 + v0, s1 = a1 + v1, d0 = a0 - v0, d1 = a1 - v1;
;             const float sm[8] = {s0[0], s0[1], s0[2], s0[3], s1[0], s1[1], s1[2], s1[3]}, df[8] = {d0[0], d0[1], d0[2], d0[3], d1[0], d1[1], d1[2], d1[3]};
;             const size_t rowk = ((size_t)u.i0 * TB + k) * DM, rowT = ((size_t)u.i0 * TB + (TL - k)) * DM; const int cm = (col & ~255) + 512 - col_l;
;             {
;                 const bf16_t* gk_ = Gt + rowk + cm - 8; const bf16_t* gT_ = Gt + rowT + cm - 8; bf16_t* uk_ = U + rowk + cm - 8; bf16_t* uT_ = U + rowT + cm - 8;
;                 const unsigned short ka1 = gk_[1]; const unsigned ka2 = *(const unsigned*)(gk_ + 2); const u32x2 ka4 = *(const u32x2*)(gk_ + 4); const unsigned short ka0 = col_l ? gk_[8] : (unsigned short)0;
;                 unsigned short ta1 = 0, ta0 = 0; unsigned ta2 = 0; u32x2 ta4 = {0u, 0u};
;                 if (k != 0) { ta1 = gT_[1]; ta2 = *(const unsigned*)(gT_ + 2); ta4 = *(const u32x2*)(gT_ + 4); ta0 = col_l ? gT_[8] : (unsigned short)0; }
.LBB0_647:
	v_or_b32_e32 v80, 48, v150
	v_ashrrev_i32_e32 v81, 31, v80
	v_lshlrev_b64 v[82:83], 12, v[80:81]
	v_lshl_add_u64 v[84:85], s[66:67], 0, v[80:81]
	v_sub_u32_e32 v80, 0x800, v80
	v_ashrrev_i32_e32 v81, 31, v80
	v_lshl_add_u64 v[80:81], s[66:67], 0, v[80:81]
	v_lshl_add_u64 v[92:93], s[68:69], 0, v[82:83]
	v_mov_b32_e32 v153, v145
	v_lshlrev_b64 v[88:89], 11, v[84:85]
	v_lshlrev_b64 v[90:91], 11, v[80:81]
	v_lshl_add_u64 v[94:95], v[92:93], 0, v[152:153]
	s_and_b64 vcc, exec, s[0:1]
	s_mov_b64 s[4:5], -1
	s_cbranch_vccnz .LBB0_657
	v_or_b32_e32 v84, v88, v189
	v_mov_b32_e32 v85, v89
	v_lshlrev_b64 v[96:97], 1, v[84:85]
	v_subrev_u32_e32 v248, s98, v94
	v_and_b32_e32 v249, 0xfffff000, v248
	v_and_b32_e32 v250, 0xfff, v248
	v_sub_u32_e32 v251, v250, v249
	v_add_u32_e32 v251, 0x800000, v251
	global_load_dwordx4 v[252:255], v251, s[100:101]
	global_load_dwordx4 v[80:83], v[94:95], off
	v_lshl_add_u64 v[84:85], s[44:45], 0, v[96:97]
	global_load_dwordx4 v[84:87], v[84:85], off
	v_or_b32_e32 v98, v90, v189
	v_mov_b32_e32 v99, v91
	v_lshlrev_b64 v[106:107], 1, v[98:99]
	v_lshl_add_u64 v[108:109], s[36:37], 0, v[96:97]
	v_lshl_add_u64 v[110:111], s[44:45], 0, v[106:107]
	v_lshl_add_u64 v[120:121], s[36:37], 0, v[106:107]
	v_cmp_ne_u32_e32 vcc, 0, v151
	v_mov_b32_e32 v105, 0
	s_waitcnt vmcnt(0)
	v_lshlrev_b32_e32 v112, 16, v80
	v_and_b32_e32 v113, 0xffff0000, v80
	v_lshlrev_b32_e32 v114, 16, v81
	v_and_b32_e32 v115, 0xffff0000, v81
	v_lshlrev_b32_e32 v116, 16, v82
	v_and_b32_e32 v117, 0xffff0000, v82
	v_lshlrev_b32_e32 v118, 16, v83
	v_and_b32_e32 v119, 0xffff0000, v83
	v_pk_add_f32 v[98:99], v[78:79], v[114:115]
	v_pk_add_f32 v[96:97], v[76:77], v[112:113]
	v_pk_add_f32 v[102:103], v[74:75], v[118:119]
	v_pk_add_f32 v[100:101], v[72:73], v[116:117]
	v_lshlrev_b32_e32 v80, 16, v84
	v_and_b32_e32 v81, 0xffff0000, v84
	v_lshlrev_b32_e32 v82, 16, v85
	v_and_b32_e32 v83, 0xffff0000, v85
	v_lshlrev_b32_e32 v84, 16, v86
	v_and_b32_e32 v85, 0xffff0000, v86
	v_lshlrev_b32_e32 v86, 16, v87
	v_and_b32_e32 v87, 0xffff0000, v87
	v_pk_mul_f32 v[82:83], v[98:99], v[82:83]
	v_pk_mul_f32 v[80:81], v[96:97], v[80:81]
	v_pk_mul_f32 v[86:87], v[102:103], v[86:87]
	v_pk_mul_f32 v[84:85], v[100:101], v[84:85]
	v_cvt_pk_bf16_f32 v80, v80, v81
	v_cvt_pk_bf16_f32 v81, v82, v83
	v_cvt_pk_bf16_f32 v82, v84, v85
	v_cvt_pk_bf16_f32 v83, v86, v87
	global_store_dwordx4 v[108:109], v[80:83], off
	v_sub_f32_e32 v108, v114, v78
	v_sub_f32_e32 v111, v115, v79
	v_sub_f32_e32 v106, v112, v76
	v_sub_f32_e32 v83, v119, v75
	v_sub_f32_e32 v112, v118, v74
	v_mov_b32_e32 v110, v108
	v_sub_f32_e32 v109, v113, v77
	v_sub_f32_e32 v113, v117, v73
	v_mov_b32_e32 v107, v109
	v_mov_b32_e32 v82, v112
	v_mov_b32_e32 v115, v113
	v_lshl_add_u64 v[80:81], v[88:89], 1, s[44:45]
	v_lshl_add_u64 v[80:81], v[80:81], 0, v[144:145]
	v_mov_b32_e32 v84, v252
	v_mov_b32_e32 v85, v253
	v_mov_b32_e32 v86, v254
	v_mov_b32_e32 v87, v255
	v_lshlrev_b32_e32 v118, 16, v84
	v_and_b32_e32 v119, 0xffff0000, v84
	v_lshlrev_b32_e32 v84, 16, v85
	v_and_b32_e32 v85, 0xffff0000, v85
	v_pk_mul_f32 v[124:125], v[110:111], v[84:85]
	v_sub_f32_e32 v110, v116, v72
	v_lshlrev_b32_e32 v122, 16, v86
	v_and_b32_e32 v123, 0xffff0000, v86
	v_lshlrev_b32_e32 v86, 16, v87
	v_and_b32_e32 v87, 0xffff0000, v87
	v_mov_b32_e32 v114, v110
	v_pk_mul_f32 v[84:85], v[106:107], v[118:119]
	v_pk_mul_f32 v[86:87], v[82:83], v[86:87]
	v_pk_mul_f32 v[114:115], v[114:115], v[122:123]
	v_cvt_pk_bf16_f32 v84, v84, v85
	v_cvt_pk_bf16_f32 v85, v124, v125
	v_cvt_pk_bf16_f32 v87, v86, v87
	v_cvt_pk_bf16_f32 v86, v114, v115
	global_store_dwordx4 v[120:121], v[84:87], off
	global_load_ushort v116, v[80:81], off offset:-14
	s_nop 0
	global_load_dwordx3 v[84:86], v[80:81], off offset:-12
	v_mov_b32_e32 v87, 0
	s_and_saveexec_b64 s[4:5], vcc
	s_cbranch_execz .LBB0_650
	global_load_ushort v80, v[80:81], off
	s_waitcnt vmcnt(0)
	v_lshlrev_b32_e32 v105, 16, v80

; DI void fnet_layer(const Args& A, LAS unsigned char* lds, const XcdBarrier& gbar, int layer, int j, bool latonly, int wv) {
;     ...
;             bf16_t* ap = A1 + ((size_t)u.i0 * 1024 + k) * DM + col;
;             if (u.i2 < 8) { st_bf16x8(ap, v0, v1); return; }
;             f32x4 a0, a1; ld_bf16x8(ap, a0, a1);
;             const size_t off = ((size_t)u.i0 * TB + k) * DM + col;
;             f32x4 g0, g1; ld_bf16x8(Gt + off, g0, g1);
;             st_bf16x8(U + off, (a0 + v0) * g0, (a1 + v1) * g1);
;             if (k != 0) { const size_t off2 = ((size_t)u.i0 * TB + (TL - k)) * DM + col; ld_bf16x8(Gt + off2, g0, g1); st_bf16x8(U + off2, (a0 - v0) * g0, (a1 - v1) * g1); }
;             const f32x4 s0 = a0 + v0, s1 = a1 + v1, d0 = a0 - v0, d1 = a1 - v1;
;             const float sm[8] = {s0[0], s0[1], s0[2], s0[3], s1[0], s1[1], s1[2], s1[3]}, df[8] = {d0[0], d0[1], d0[2], d0[3], d1[0], d1[1], d1[2], d1[3]};
;             const size_t rowk = ((size_t)u.i0 * TB + k) * DM, rowT = ((size_t)u.i0 * TB + (TL - k)) * DM; const int cm = (col & ~255) + 512 - col_l;
;             {
;                 const bf16_t* gk_ = Gt + rowk + cm - 8; const bf16_t* gT_ = Gt + rowT + cm - 8; bf16_t* uk_ = U + rowk + cm - 8; bf16_t* uT_ = U + rowT + cm - 8;
;                 const unsigned short ka1 = gk_[1]; const unsigned ka2 = *(const unsigned*)(gk_ + 2); const u32x2 ka4 = *(const u32x2*)(gk_ + 4); const unsigned short ka0 = col_l ? gk_[8] : (unsigned short)0;
;                 unsigned short ta1 = 0, ta0 = 0; unsigned ta2 = 0; u32x2 ta4 = {0u, 0u};
;                 if (k != 0) { ta1 = gT_[1]; ta2 = *(const unsigned*)(gT_ + 2); ta4 = *(const u32x2*)(gT_ + 4); ta0 = col_l ? gT_[8] : (unsigned short)0; }
;                 uk_[1] = (bf16_t)(pk2(df[7] * __uint_as_float((unsigned)ka1 << 16), 0.f) & 0xffffu);
;                 *(unsigned*)(uk_ + 2) = pk2(df[6] * bf_lo(ka2), df[5] * bf_hi(ka2));
;                 *(u32x2*)(uk_ + 4) = (u32x2){pk2(df[4] * bf_lo(ka4.x), df[3] * bf_hi(ka4.x)), pk2(df[2] * bf_lo(ka4.y), df[1] * bf_hi(ka4.y))};
;                 if (col_l) uk_[8] = (bf16_t)(pk2(df[0] * __uint_as_float((unsigned)ka0 << 16), 0.f) & 0xffffu);
;                 if (k != 0) {
;                     uT_[1] = (bf16_t)(pk2(sm[7] * __uint_as_float((unsigned)ta1 << 16), 0.f) & 0xffffu);
;                     *(unsigned*)(uT_ + 2) = pk2(sm[6] * bf_lo(ta2), sm[5] * bf_hi(ta2));
.LBB0_659:
	v_mov_b32_e32 v129, v145
	v_lshl_add_u64 v[72:73], v[92:93], 0, v[128:129]
	s_and_b64 vcc, exec, s[0:1]
	s_mov_b64 s[4:5], -1
	s_cbranch_vccnz .LBB0_661
	v_or_b32_e32 v78, v88, v172
	v_mov_b32_e32 v79, v89
	v_lshlrev_b64 v[82:83], 1, v[78:79]
	v_subrev_u32_e32 v248, s98, v72
	v_add_u32_e32 v248, 256, v248
	v_and_b32_e32 v249, 0xfffff000, v248
	v_and_b32_e32 v250, 0xfff, v248
	v_sub_u32_e32 v251, v250, v249
	v_add_u32_e32 v251, 0x800000, v251
	global_load_dwordx4 v[252:255], v251, s[100:101]
	global_load_dwordx4 v[74:77], v[72:73], off offset:256
	v_lshl_add_u64 v[78:79], s[44:45], 0, v[82:83]
	global_load_dwordx4 v[78:81], v[78:79], off
	v_or_b32_e32 v84, v90, v172
	v_mov_b32_e32 v85, v91
	v_lshlrev_b64 v[84:85], 1, v[84:85]
	v_lshl_add_u64 v[82:83], s[36:37], 0, v[82:83]
	v_lshl_add_u64 v[86:87], s[44:45], 0, v[84:85]
	v_mov_b32_e32 v105, v145
	v_lshl_add_u64 v[84:85], s[36:37], 0, v[84:85]
	s_mov_b64 s[4:5], 0
	s_waitcnt vmcnt(0)
	v_lshlrev_b32_e32 v92, 16, v74
	v_and_b32_e32 v93, 0xffff0000, v74
	v_lshlrev_b32_e32 v94, 16, v75
	v_and_b32_e32 v95, 0xffff0000, v75
	v_lshlrev_b32_e32 v96, 16, v76
	v_and_b32_e32 v97, 0xffff0000, v76
	v_lshlrev_b32_e32 v98, 16, v77
	v_and_b32_e32 v99, 0xffff0000, v77
	v_pk_add_f32 v[100:101], v[68:69], v[92:93]
	v_pk_add_f32 v[102:103], v[70:71], v[94:95]
	v_pk_add_f32 v[106:107], v[64:65], v[96:97]
	v_pk_add_f32 v[108:109], v[66:67], v[98:99]
	v_lshlrev_b32_e32 v74, 16, v78
	v_and_b32_e32 v75, 0xffff0000, v78
	v_lshlrev_b32_e32 v76, 16, v79
	v_and_b32_e32 v77, 0xffff0000, v79
	v_lshlrev_b32_e32 v78, 16, v80
	v_and_b32_e32 v79, 0xffff0000, v80
	v_lshlrev_b32_e32 v80, 16, v81
	v_and_b32_e32 v81, 0xffff0000, v81
	v_pk_mul_f32 v[76:77], v[102:103], v[76:77]
	v_pk_mul_f32 v[74:75], v[100:101], v[74:75]
	v_pk_mul_f32 v[80:81], v[108:109], v[80:81]
	v_pk_mul_f32 v[78:79], v[106:107], v[78:79]
	v_cvt_pk_bf16_f32 v74, v74, v75
	v_cvt_pk_bf16_f32 v75, v76, v77
	v_cvt_pk_bf16_f32 v76, v78, v79
	v_cvt_pk_bf16_f32 v77, v80, v81
	global_store_dwordx4 v[82:83], v[74:77], off
	v_lshlrev_b64 v[82:83], 1, v[88:89]
	v_lshlrev_b64 v[86:87], 1, v[90:91]
	v_sub_f32_e32 v89, v93, v69
	v_sub_f32_e32 v88, v92, v68
	v_sub_f32_e32 v91, v95, v71
	v_sub_f32_e32 v90, v94, v70
	v_sub_f32_e32 v93, v97, v65
	v_sub_f32_e32 v92, v96, v64
	v_sub_f32_e32 v95, v99, v67
	v_sub_f32_e32 v94, v98, v66
	v_lshl_add_u64 v[78:79], s[44:45], 0, v[82:83]
	v_lshl_add_u64 v[80:81], s[44:45], 0, v[86:87]
	v_lshl_add_u64 v[78:79], v[78:79], 0, v[104:105]
	v_lshl_add_u64 v[80:81], v[80:81], 0, v[104:105]
	v_lshl_add_u64 v[82:83], s[36:37], 0, v[82:83]
	v_lshl_add_u64 v[82:83], v[82:83], 0, v[104:105]
	v_mov_b32_e32 v74, v252
	v_mov_b32_e32 v75, v253
	v_mov_b32_e32 v76, v254
	v_mov_b32_e32 v77, v255
	v_lshlrev_b32_e32 v96, 16, v74
	v_and_b32_e32 v97, 0xffff0000, v74
	v_lshlrev_b32_e32 v74, 16, v75
	v_and_b32_e32 v75, 0xffff0000, v75
	v_lshlrev_b32_e32 v98, 16, v76
	v_and_b32_e32 v99, 0xffff0000, v76
	v_lshlrev_b32_e32 v76, 16, v77
	v_and_b32_e32 v77, 0xffff0000, v77
	v_pk_mul_f32 v[110:111], v[90:91], v[74:75]
	v_pk_mul_f32 v[74:75], v[88:89], v[96:97]
	v_pk_mul_f32 v[96:97], v[94:95], v[76:77]
	v_pk_mul_f32 v[76:77], v[92:93], v[98:99]
	v_cvt_pk_bf16_f32 v74, v74, v75
	v_cvt_pk_bf16_f32 v75, v110, v111
	v_cvt_pk_bf16_f32 v76, v76, v77
	v_cvt_pk_bf16_f32 v77, v96, v97
	global_store_dwordx4 v[84:85], v[74:77], off
	global_load_ushort v77, v[78:79], off
	s_nop 0
	global_load_ushort v96, v[80:81], off
	global_load_ushort v97, v[80:81], off offset:-14
	global_load_ushort v98, v[78:79], off offset:-14
	global_load_dwordx3 v[74:76], v[78:79], off offset:-12
	s_nop 0
	global_load_dwordx3 v[78:80], v[80:81], off offset:-12
	v_lshl_add_u64 v[84:85], s[36:37], 0, v[86:87]
	v_lshl_add_u64 v[84:85], v[84:85], 0, v[104:105]
	s_waitcnt vmcnt(5)
	v_lshlrev_b32_e32 v81, 16, v77
	s_waitcnt vmcnt(4)
	v_lshlrev_b32_e32 v105, 16, v96
	s_waitcnt vmcnt(3)
	v_lshlrev_b32_e32 v110, 16, v97
	s_waitcnt vmcnt(2)
	v_lshlrev_b32_e32 v111, 16, v98
	s_waitcnt vmcnt(1)
	v_lshlrev_b32_e32 v86, 16, v74
	v_and_b32_e32 v87, 0xffff0000, v74
	v_lshlrev_b32_e32 v74, 16, v75
	v_and_b32_e32 v75, 0xffff0000, v75
	v_lshlrev_b32_e32 v96, 16, v76
	v_and_b32_e32 v97, 0xffff0000, v76
	s_waitcnt vmcnt(0)
	v_lshlrev_b32_e32 v76, 16, v78
	v_and_b32_e32 v77, 0xffff0000, v78
	v_lshlrev_b32_e32 v98, 16, v80
	v_and_b32_e32 v99, 0xffff0000, v80
	v_mul_f32_e32 v80, v95, v111
	v_mov_b32_e32 v95, v93
	v_mov_b32_e32 v93, v91
	v_mov_b32_e32 v91, v89
	v_mul_f32_e32 v89, v109, v110
	v_mov_b32_e32 v109, v107
	v_lshlrev_b32_e32 v78, 16, v79
	v_and_b32_e32 v79, 0xffff0000, v79
	v_mul_f32_e32 v88, v88, v81
	v_mov_b32_e32 v107, v103
	v_mov_b32_e32 v103, v101
	v_mul_f32_e32 v100, v100, v105
	v_cvt_pk_bf16_f32 v101, v80, s0
	v_pk_mul_f32 v[80:81], v[94:95], v[86:87]
	v_pk_mul_f32 v[74:75], v[92:93], v[74:75]
	v_pk_mul_f32 v[76:77], v[108:109], v[76:77]
	v_pk_mul_f32 v[86:87], v[90:91], v[96:97]
	v_cvt_pk_bf16_f32 v90, v88, s0
	v_cvt_pk_bf16_f32 v91, v89, s0
	v_pk_mul_f32 v[78:79], v[106:107], v[78:79]
	v_pk_mul_f32 v[88:89], v[102:103], v[98:99]
	v_cvt_pk_bf16_f32 v92, v100, s0
	v_cvt_pk_bf16_f32 v80, v80, v81
	v_cvt_pk_bf16_f32 v74, v74, v75
	v_cvt_pk_bf16_f32 v81, v76, v77
	v_cvt_pk_bf16_f32 v75, v86, v87
	global_store_short v[82:83], v90, off
	v_cvt_pk_bf16_f32 v76, v78, v79
	v_cvt_pk_bf16_f32 v77, v88, v89
	global_store_short v[84:85], v92, off
	v_perm_b32 v78, v80, v101, s46
	global_store_short_d16_hi v[82:83], v80, off offset:-10
	global_store_dwordx2 v[82:83], v[74:75], off offset:-8
	v_perm_b32 v74, v81, v91, s46
	global_store_short_d16_hi v[84:85], v81, off offset:-10
	global_store_dwordx2 v[84:85], v[76:77], off offset:-8
	global_store_dword v[82:83], v78, off offset:-14
	global_store_dword v[84:85], v74, off offset:-14

; DI void st_bf16x8(bf16_t* p, f32x4 a, f32x4 b) { u32x4 w = {pk2(a[0], a[1]), pk2(a[2], a[3]), pk2(b[0], b[1]), pk2(b[2], b[3])}; *(u32x4*)p = w; }
; DI void ld_bf16x8(const bf16_t* p, f32x4& a, f32x4& b) { const u32x4 w = *(const u32x4*)p; a = (f32x4){bf_lo(w.x), bf_hi(w.x), bf_lo(w.y), bf_hi(w.y)}; b = (f32x4){bf_lo(w.z), bf_hi(w.z), bf_lo(w.w), bf_hi(w.w)}; }
; DI void fnet_layer(const Args& A, LAS unsigned char* lds, const XcdBarrier& gbar, int layer, int j, bool latonly, int wv) {
;     ...
;         auto E = [=](const pg8::Unit& u, int row_l, int col_l, f32x4 v0, f32x4 v1) {
;             const int k = u.i1 * 256 + row_l, col = (u.i2 & 7) * 256 + col_l;
;             bf16_t* ap = A1 + ((size_t)u.i0 * 1024 + k) * DM + col;
;             if (u.i2 < 8) { st_bf16x8(ap, v0, v1); return; }
;             f32x4 a0, a1; ld_bf16x8(ap, a0, a1);
;             const size_t off = ((size_t)u.i0 * TB + k) * DM + col;
;             f32x4 g0, g1; ld_bf16x8(Gt + off, g0, g1);
;             st_bf16x8(U + off, (a0 + v0) * g0, (a1 + v1) * g1);
;             if (k != 0) { const size_t off2 = ((size_t)u.i0 * TB + (TL - k)) * DM + col; ld_bf16x8(Gt + off2, g0, g1); st_bf16x8(U + off2, (a0 - v0) * g0, (a1 - v1) * g1); }
.LBB0_663:
	v_add_u32_e32 v64, 0x80, v150
	v_ashrrev_i32_e32 v65, 31, v64
	v_sub_u32_e32 v74, 0x780, v150
	v_lshlrev_b64 v[66:67], 12, v[64:65]
	v_ashrrev_i32_e32 v75, 31, v74
	v_lshl_add_u64 v[68:69], s[66:67], 0, v[64:65]
	v_cmp_ne_u32_e64 s[4:5], 0, v64
	v_lshl_add_u64 v[64:65], s[66:67], 0, v[74:75]
	v_lshl_add_u64 v[78:79], s[68:69], 0, v[66:67]
	v_mov_b32_e32 v153, v145
	v_lshlrev_b64 v[72:73], 11, v[68:69]
	v_lshlrev_b64 v[76:77], 11, v[64:65]
	v_lshl_add_u64 v[80:81], v[78:79], 0, v[152:153]
	s_and_b64 vcc, exec, s[0:1]
	s_mov_b64 s[70:71], -1
	s_cbranch_vccnz .LBB0_680
	v_or_b32_e32 v68, v72, v189
	v_mov_b32_e32 v69, v73
	v_lshlrev_b64 v[82:83], 1, v[68:69]
	v_subrev_u32_e32 v248, s98, v80
	v_and_b32_e32 v249, 0xfffff000, v248
	v_and_b32_e32 v250, 0xfff, v248
	v_sub_u32_e32 v251, v250, v249
	v_add_u32_e32 v251, 0x800000, v251
	global_load_dwordx4 v[252:255], v251, s[100:101]
	global_load_dwordx4 v[64:67], v[80:81], off
	v_lshl_add_u64 v[68:69], s[44:45], 0, v[82:83]
	global_load_dwordx4 v[68:71], v[68:69], off
	v_lshl_add_u64 v[98:99], s[36:37], 0, v[82:83]
	s_waitcnt vmcnt(0)
	v_lshlrev_b32_e32 v90, 16, v64
	v_and_b32_e32 v91, 0xffff0000, v64
	v_lshlrev_b32_e32 v64, 16, v65
	v_and_b32_e32 v65, 0xffff0000, v65
	v_lshlrev_b32_e32 v94, 16, v66
	v_and_b32_e32 v95, 0xffff0000, v66
	v_lshlrev_b32_e32 v66, 16, v67
	v_and_b32_e32 v67, 0xffff0000, v67
	v_pk_add_f32 v[84:85], v[62:63], v[64:65]
	v_pk_add_f32 v[82:83], v[60:61], v[90:91]
	v_pk_add_f32 v[88:89], v[58:59], v[66:67]
	v_pk_add_f32 v[86:87], v[56:57], v[94:95]
	v_sub_f32_e32 v93, v65, v63
	v_sub_f32_e32 v92, v64, v62
	v_sub_f32_e32 v97, v67, v59
	v_sub_f32_e32 v96, v66, v58
	v_lshlrev_b32_e32 v64, 16, v68
	v_and_b32_e32 v65, 0xffff0000, v68
	v_lshlrev_b32_e32 v66, 16, v69
	v_and_b32_e32 v67, 0xffff0000, v69
	v_lshlrev_b32_e32 v68, 16, v70
	v_and_b32_e32 v69, 0xffff0000, v70
	v_lshlrev_b32_e32 v70, 16, v71
	v_and_b32_e32 v71, 0xffff0000, v71
	v_pk_mul_f32 v[66:67], v[84:85], v[66:67]
	v_pk_mul_f32 v[64:65], v[82:83], v[64:65]
	v_pk_mul_f32 v[70:71], v[88:89], v[70:71]
	v_pk_mul_f32 v[68:69], v[86:87], v[68:69]
	v_sub_f32_e32 v91, v91, v61
	v_sub_f32_e32 v90, v90, v60
	v_sub_f32_e32 v95, v95, v57
	v_cvt_pk_bf16_f32 v64, v64, v65
	v_cvt_pk_bf16_f32 v65, v66, v67
	v_cvt_pk_bf16_f32 v66, v68, v69
	v_cvt_pk_bf16_f32 v67, v70, v71
	v_sub_f32_e32 v94, v94, v56
	global_store_dwordx4 v[98:99], v[64:67], off
	s_and_saveexec_b64 s[48:49], s[4:5]
	s_xor_b64 s[70:71], exec, s[48:49]
	s_cbranch_execz .LBB0_666
	v_or_b32_e32 v64, v76, v189
	v_mov_b32_e32 v65, v77
	v_lshlrev_b64 v[68:69], 1, v[64:65]
	v_lshl_add_u64 v[64:65], s[44:45], 0, v[68:69]
	v_lshl_add_u64 v[68:69], s[36:37], 0, v[68:69]
	v_mov_b32_e32 v64, v252
	v_mov_b32_e32 v65, v253
	v_mov_b32_e32 v66, v254
	v_mov_b32_e32 v67, v255
	v_lshlrev_b32_e32 v70, 16, v64
	v_and_b32_e32 v71, 0xffff0000, v64
	v_lshlrev_b32_e32 v64, 16, v65
	v_and_b32_e32 v65, 0xffff0000, v65
	v_lshlrev_b32_e32 v98, 16, v66
	v_and_b32_e32 v99, 0xffff0000, v66
	v_lshlrev_b32_e32 v66, 16, v67
	v_and_b32_e32 v67, 0xffff0000, v67
	v_pk_mul_f32 v[100:101], v[92:93], v[64:65]
	v_pk_mul_f32 v[64:65], v[90:91], v[70:71]
	v_pk_mul_f32 v[70:71], v[96:97], v[66:67]
	v_pk_mul_f32 v[66:67], v[94:95], v[98:99]
	v_cvt_pk_bf16_f32 v64, v64, v65
	v_cvt_pk_bf16_f32 v65, v100, v101
	v_cvt_pk_bf16_f32 v66, v66, v67
	v_cvt_pk_bf16_f32 v67, v70, v71
	global_store_dwordx4 v[68:69], v[64:67], off

; DI void st_bf16x8(bf16_t* p, f32x4 a, f32x4 b) { u32x4 w = {pk2(a[0], a[1]), pk2(a[2], a[3]), pk2(b[0], b[1]), pk2(b[2], b[3])}; *(u32x4*)p = w; }
; DI void ld_bf16x8(const bf16_t* p, f32x4& a, f32x4& b) { const u32x4 w = *(const u32x4*)p; a = (f32x4){bf_lo(w.x), bf_hi(w.x), bf_lo(w.y), bf_hi(w.y)}; b = (f32x4){bf_lo(w.z), bf_hi(w.z), bf_lo(w.w), bf_hi(w.w)}; }
; DI void fnet_layer(const Args& A, LAS unsigned char* lds, const XcdBarrier& gbar, int layer, int j, bool latonly, int wv) {
;     ...
;             bf16_t* ap = A1 + ((size_t)u.i0 * 1024 + k) * DM + col;
;             if (u.i2 < 8) { st_bf16x8(ap, v0, v1); return; }
;             f32x4 a0, a1; ld_bf16x8(ap, a0, a1);
;             const size_t off = ((size_t)u.i0 * TB + k) * DM + col;
;             f32x4 g0, g1; ld_bf16x8(Gt + off, g0, g1);
;             st_bf16x8(U + off, (a0 + v0) * g0, (a1 + v1) * g1);
;             if (k != 0) { const size_t off2 = ((size_t)u.i0 * TB + (TL - k)) * DM + col; ld_bf16x8(Gt + off2, g0, g1); st_bf16x8(U + off2, (a0 - v0) * g0, (a1 - v1) * g1); }
.LBB0_682:
	v_mov_b32_e32 v129, v145
	v_lshl_add_u64 v[64:65], v[78:79], 0, v[128:129]
	s_and_b64 vcc, exec, s[0:1]
	s_mov_b64 s[70:71], -1
	s_cbranch_vccnz .LBB0_692
	v_or_b32_e32 v60, v72, v172
	v_mov_b32_e32 v61, v73
	v_lshlrev_b64 v[66:67], 1, v[60:61]
	v_subrev_u32_e32 v248, s98, v64
	v_add_u32_e32 v248, 256, v248
	v_and_b32_e32 v249, 0xfffff000, v248
	v_and_b32_e32 v250, 0xfff, v248
	v_sub_u32_e32 v251, v250, v249
	v_add_u32_e32 v251, 0x800000, v251
	global_load_dwordx4 v[252:255], v251, s[100:101]
	global_load_dwordx4 v[56:59], v[64:65], off offset:256
	v_lshl_add_u64 v[60:61], s[44:45], 0, v[66:67]
	global_load_dwordx4 v[60:63], v[60:61], off
	v_lshl_add_u64 v[88:89], s[36:37], 0, v[66:67]
	s_waitcnt vmcnt(0)
	v_lshlrev_b32_e32 v80, 16, v56
	v_and_b32_e32 v81, 0xffff0000, v56
	v_lshlrev_b32_e32 v56, 16, v57
	v_and_b32_e32 v57, 0xffff0000, v57
	v_lshlrev_b32_e32 v84, 16, v58
	v_and_b32_e32 v85, 0xffff0000, v58
	v_lshlrev_b32_e32 v58, 16, v59
	v_and_b32_e32 v59, 0xffff0000, v59
	v_pk_add_f32 v[68:69], v[54:55], v[56:57]
	v_pk_add_f32 v[66:67], v[52:53], v[80:81]
	v_pk_add_f32 v[78:79], v[50:51], v[58:59]
	v_pk_add_f32 v[70:71], v[48:49], v[84:85]
	v_sub_f32_e32 v83, v57, v55
	v_sub_f32_e32 v82, v56, v54
	v_sub_f32_e32 v87, v59, v51
	v_sub_f32_e32 v86, v58, v50
	v_lshlrev_b32_e32 v56, 16, v60
	v_and_b32_e32 v57, 0xffff0000, v60
	v_lshlrev_b32_e32 v58, 16, v61
	v_and_b32_e32 v59, 0xffff0000, v61
	v_lshlrev_b32_e32 v60, 16, v62
	v_and_b32_e32 v61, 0xffff0000, v62
	v_lshlrev_b32_e32 v62, 16, v63
	v_and_b32_e32 v63, 0xffff0000, v63
	v_pk_mul_f32 v[58:59], v[68:69], v[58:59]
	v_pk_mul_f32 v[56:57], v[66:67], v[56:57]
	v_pk_mul_f32 v[62:63], v[78:79], v[62:63]
	v_pk_mul_f32 v[60:61], v[70:71], v[60:61]
	v_sub_f32_e32 v81, v81, v53
	v_sub_f32_e32 v80, v80, v52
	v_sub_f32_e32 v85, v85, v49
	v_cvt_pk_bf16_f32 v56, v56, v57
	v_cvt_pk_bf16_f32 v57, v58, v59
	v_cvt_pk_bf16_f32 v58, v60, v61
	v_cvt_pk_bf16_f32 v59, v62, v63
	v_sub_f32_e32 v84, v84, v48
	global_store_dwordx4 v[88:89], v[56:59], off
	s_and_saveexec_b64 s[48:49], s[4:5]
	s_xor_b64 s[70:71], exec, s[48:49]
	s_cbranch_execz .LBB0_685
	v_or_b32_e32 v76, v76, v172
	v_lshlrev_b64 v[60:61], 1, v[76:77]
	v_lshl_add_u64 v[56:57], s[44:45], 0, v[60:61]
	v_lshl_add_u64 v[60:61], s[36:37], 0, v[60:61]
	v_mov_b32_e32 v56, v252
	v_mov_b32_e32 v57, v253
	v_mov_b32_e32 v58, v254
	v_mov_b32_e32 v59, v255
	v_lshlrev_b32_e32 v62, 16, v56
	v_and_b32_e32 v63, 0xffff0000, v56
	v_lshlrev_b32_e32 v56, 16, v57
	v_and_b32_e32 v57, 0xffff0000, v57
	v_lshlrev_b32_e32 v76, 16, v58
	v_and_b32_e32 v77, 0xffff0000, v58
	v_lshlrev_b32_e32 v58, 16, v59
	v_and_b32_e32 v59, 0xffff0000, v59
	v_pk_mul_f32 v[88:89], v[82:83], v[56:57]
	v_pk_mul_f32 v[56:57], v[80:81], v[62:63]
	v_pk_mul_f32 v[62:63], v[86:87], v[58:59]
	v_pk_mul_f32 v[58:59], v[84:85], v[76:77]
	v_cvt_pk_bf16_f32 v56, v56, v57
	v_cvt_pk_bf16_f32 v57, v88, v89
	v_cvt_pk_bf16_f32 v58, v58, v59
	v_cvt_pk_bf16_f32 v59, v62, v63
	global_store_dwordx4 v[60:61], v[56:59], off

; DI void st_bf16x8(bf16_t* p, f32x4 a, f32x4 b) { u32x4 w = {pk2(a[0], a[1]), pk2(a[2], a[3]), pk2(b[0], b[1]), pk2(b[2], b[3])}; *(u32x4*)p = w; }
; DI void ld_bf16x8(const bf16_t* p, f32x4& a, f32x4& b) { const u32x4 w = *(const u32x4*)p; a = (f32x4){bf_lo(w.x), bf_hi(w.x), bf_lo(w.y), bf_hi(w.y)}; b = (f32x4){bf_lo(w.z), bf_hi(w.z), bf_lo(w.w), bf_hi(w.w)}; }
; DI void fnet_layer(const Args& A, LAS unsigned char* lds, const XcdBarrier& gbar, int layer, int j, bool latonly, int wv) {
;     ...
;         auto E = [=](const pg8::Unit& u, int row_l, int col_l, f32x4 v0, f32x4 v1) {
;             const int k = u.i1 * 256 + row_l, col = (u.i2 & 7) * 256 + col_l;
;             bf16_t* ap = A1 + ((size_t)u.i0 * 1024 + k) * DM + col;
;             if (u.i2 < 8) { st_bf16x8(ap, v0, v1); return; }
;             f32x4 a0, a1; ld_bf16x8(ap, a0, a1);
;             const size_t off = ((size_t)u.i0 * TB + k) * DM + col;
;             f32x4 g0, g1; ld_bf16x8(Gt + off, g0, g1);
;             st_bf16x8(U + off, (a0 + v0) * g0, (a1 + v1) * g1);
;             if (k != 0) { const size_t off2 = ((size_t)u.i0 * TB + (TL - k)) * DM + col; ld_bf16x8(Gt + off2, g0, g1); st_bf16x8(U + off2, (a0 - v0) * g0, (a1 - v1) * g1); }
;             const f32x4 s0 = a0 + v0, s1 = a1 + v1, d0 = a0 - v0, d1 = a1 - v1;
;             const float sm[8] = {s0[0], s0[1], s0[2], s0[3], s1[0], s1[1], s1[2], s1[3]}, df[8] = {d0[0], d0[1], d0[2], d0[3], d1[0], d1[1], d1[2], d1[3]};
;             const size_t rowk = ((size_t)u.i0 * TB + k) * DM, rowT = ((size_t)u.i0 * TB + (TL - k)) * DM; const int cm = (col & ~255) + 512 - col_l;
;             {
;                 const bf16_t* gk_ = Gt + rowk + cm - 8; const bf16_t* gT_ = Gt + rowT + cm - 8; bf16_t* uk_ = U + rowk + cm - 8; bf16_t* uT_ = U + rowT + cm - 8;
;                 const unsigned short ka1 = gk_[1]; const unsigned ka2 = *(const unsigned*)(gk_ + 2); const u32x2 ka4 = *(const u32x2*)(gk_ + 4); const unsigned short ka0 = col_l ? gk_[8] : (unsigned short)0;
;                 unsigned short ta1 = 0, ta0 = 0; unsigned ta2 = 0; u32x2 ta4 = {0u, 0u};
;                 if (k != 0) { ta1 = gT_[1]; ta2 = *(const unsigned*)(gT_ + 2); ta4 = *(const u32x2*)(gT_ + 4); ta0 = col_l ? gT_[8] : (unsigned short)0; }
.LBB0_694:
	v_add_u32_e32 v48, 0x90, v150
	v_ashrrev_i32_e32 v49, 31, v48
	v_lshlrev_b64 v[50:51], 12, v[48:49]
	v_lshl_add_u64 v[48:49], s[66:67], 0, v[48:49]
	v_lshlrev_b64 v[56:57], 11, v[48:49]
	v_sub_u32_e32 v48, 0x770, v150
	v_ashrrev_i32_e32 v49, 31, v48
	v_lshl_add_u64 v[48:49], s[66:67], 0, v[48:49]
	v_lshl_add_u64 v[60:61], s[68:69], 0, v[50:51]
	v_mov_b32_e32 v153, v145
	v_lshlrev_b64 v[58:59], 11, v[48:49]
	v_lshl_add_u64 v[62:63], v[60:61], 0, v[152:153]
	s_and_b64 vcc, exec, s[0:1]
	s_mov_b64 s[4:5], -1
	s_cbranch_vccnz .LBB0_704
	v_or_b32_e32 v52, v56, v189
	v_mov_b32_e32 v53, v57
	v_lshlrev_b64 v[64:65], 1, v[52:53]
	v_subrev_u32_e32 v248, s98, v62
	v_and_b32_e32 v249, 0xfffff000, v248
	v_and_b32_e32 v250, 0xfff, v248
	v_sub_u32_e32 v251, v250, v249
	v_add_u32_e32 v251, 0x800000, v251
	global_load_dwordx4 v[252:255], v251, s[100:101]
	global_load_dwordx4 v[48:51], v[62:63], off
	v_lshl_add_u64 v[52:53], s[44:45], 0, v[64:65]
	global_load_dwordx4 v[52:55], v[52:53], off
	v_or_b32_e32 v66, v58, v189
	v_mov_b32_e32 v67, v59
	v_lshlrev_b64 v[72:73], 1, v[66:67]
	v_lshl_add_u64 v[74:75], s[36:37], 0, v[64:65]
	v_lshl_add_u64 v[76:77], s[44:45], 0, v[72:73]
	v_lshl_add_u64 v[86:87], s[36:37], 0, v[72:73]
	v_cmp_ne_u32_e32 vcc, 0, v151
	s_waitcnt vmcnt(0)
	v_lshlrev_b32_e32 v78, 16, v48
	v_and_b32_e32 v79, 0xffff0000, v48
	v_lshlrev_b32_e32 v80, 16, v49
	v_and_b32_e32 v81, 0xffff0000, v49
	v_lshlrev_b32_e32 v82, 16, v50
	v_and_b32_e32 v83, 0xffff0000, v50
	v_lshlrev_b32_e32 v84, 16, v51
	v_and_b32_e32 v85, 0xffff0000, v51
	v_pk_add_f32 v[66:67], v[46:47], v[80:81]
	v_pk_add_f32 v[64:65], v[44:45], v[78:79]
	v_pk_add_f32 v[70:71], v[42:43], v[84:85]
	v_pk_add_f32 v[68:69], v[40:41], v[82:83]
	v_lshlrev_b32_e32 v48, 16, v52
	v_and_b32_e32 v49, 0xffff0000, v52
	v_lshlrev_b32_e32 v50, 16, v53
	v_and_b32_e32 v51, 0xffff0000, v53
	v_lshlrev_b32_e32 v52, 16, v54
	v_and_b32_e32 v53, 0xffff0000, v54
	v_lshlrev_b32_e32 v54, 16, v55
	v_and_b32_e32 v55, 0xffff0000, v55
	v_pk_mul_f32 v[50:51], v[66:67], v[50:51]
	v_pk_mul_f32 v[48:49], v[64:65], v[48:49]
	v_pk_mul_f32 v[54:55], v[70:71], v[54:55]
	v_pk_mul_f32 v[52:53], v[68:69], v[52:53]
	v_cvt_pk_bf16_f32 v48, v48, v49
	v_cvt_pk_bf16_f32 v49, v50, v51
	v_cvt_pk_bf16_f32 v50, v52, v53
	v_cvt_pk_bf16_f32 v51, v54, v55
	global_store_dwordx4 v[74:75], v[48:51], off
	v_sub_f32_e32 v74, v80, v46
	v_sub_f32_e32 v77, v81, v47
	v_sub_f32_e32 v72, v78, v44
	v_sub_f32_e32 v51, v85, v43
	v_sub_f32_e32 v78, v84, v42
	v_mov_b32_e32 v76, v74
	v_sub_f32_e32 v75, v79, v45
	v_sub_f32_e32 v79, v83, v41
	v_mov_b32_e32 v73, v75
	v_mov_b32_e32 v50, v78
	v_mov_b32_e32 v81, v79
	v_lshl_add_u64 v[48:49], v[56:57], 1, s[44:45]
	v_lshl_add_u64 v[48:49], v[48:49], 0, v[144:145]
	v_mov_b32_e32 v52, v252
	v_mov_b32_e32 v53, v253
	v_mov_b32_e32 v54, v254
	v_mov_b32_e32 v55, v255
	v_lshlrev_b32_e32 v84, 16, v52
	v_and_b32_e32 v85, 0xffff0000, v52
	v_lshlrev_b32_e32 v52, 16, v53
	v_and_b32_e32 v53, 0xffff0000, v53
	v_pk_mul_f32 v[90:91], v[76:77], v[52:53]
	v_sub_f32_e32 v76, v82, v40
	v_lshlrev_b32_e32 v88, 16, v54
	v_and_b32_e32 v89, 0xffff0000, v54
	v_lshlrev_b32_e32 v54, 16, v55
	v_and_b32_e32 v55, 0xffff0000, v55
	v_mov_b32_e32 v80, v76
	v_pk_mul_f32 v[52:53], v[72:73], v[84:85]
	v_pk_mul_f32 v[54:55], v[50:51], v[54:55]
	v_pk_mul_f32 v[80:81], v[80:81], v[88:89]
	v_cvt_pk_bf16_f32 v52, v52, v53
	v_cvt_pk_bf16_f32 v53, v90, v91
	v_cvt_pk_bf16_f32 v55, v54, v55
	v_cvt_pk_bf16_f32 v54, v80, v81
	global_store_dwordx4 v[86:87], v[52:55], off
	global_load_ushort v83, v[48:49], off offset:-14
	s_nop 0
	global_load_dwordx3 v[52:54], v[48:49], off offset:-12
	v_mov_b32_e32 v55, 0
	v_mov_b32_e32 v73, 0
	s_and_saveexec_b64 s[4:5], vcc
	s_cbranch_execz .LBB0_697
	global_load_ushort v48, v[48:49], off
	s_waitcnt vmcnt(0)
	v_lshlrev_b32_e32 v73, 16, v48

; DI void fnet_layer(const Args& A, LAS unsigned char* lds, const XcdBarrier& gbar, int layer, int j, bool latonly, int wv) {
;     ...
;             bf16_t* ap = A1 + ((size_t)u.i0 * 1024 + k) * DM + col;
;             if (u.i2 < 8) { st_bf16x8(ap, v0, v1); return; }
;             f32x4 a0, a1; ld_bf16x8(ap, a0, a1);
;             const size_t off = ((size_t)u.i0 * TB + k) * DM + col;
;             f32x4 g0, g1; ld_bf16x8(Gt + off, g0, g1);
;             st_bf16x8(U + off, (a0 + v0) * g0, (a1 + v1) * g1);
;             if (k != 0) { const size_t off2 = ((size_t)u.i0 * TB + (TL - k)) * DM + col; ld_bf16x8(Gt + off2, g0, g1); st_bf16x8(U + off2, (a0 - v0) * g0, (a1 - v1) * g1); }
;             const f32x4 s0 = a0 + v0, s1 = a1 + v1, d0 = a0 - v0, d1 = a1 - v1;
;             const float sm[8] = {s0[0], s0[1], s0[2], s0[3], s1[0], s1[1], s1[2], s1[3]}, df[8] = {d0[0], d0[1], d0[2], d0[3], d1[0], d1[1], d1[2], d1[3]};
;             const size_t rowk = ((size_t)u.i0 * TB + k) * DM, rowT = ((size_t)u.i0 * TB + (TL - k)) * DM; const int cm = (col & ~255) + 512 - col_l;
;             {
;                 const bf16_t* gk_ = Gt + rowk + cm - 8; const bf16_t* gT_ = Gt + rowT + cm - 8; bf16_t* uk_ = U + rowk + cm - 8; bf16_t* uT_ = U + rowT + cm - 8;
;                 const unsigned short ka1 = gk_[1]; const unsigned ka2 = *(const unsigned*)(gk_ + 2); const u32x2 ka4 = *(const u32x2*)(gk_ + 4); const unsigned short ka0 = col_l ? gk_[8] : (unsigned short)0;
;                 unsigned short ta1 = 0, ta0 = 0; unsigned ta2 = 0; u32x2 ta4 = {0u, 0u};
;                 if (k != 0) { ta1 = gT_[1]; ta2 = *(const unsigned*)(gT_ + 2); ta4 = *(const u32x2*)(gT_ + 4); ta0 = col_l ? gT_[8] : (unsigned short)0; }
;                 uk_[1] = (bf16_t)(pk2(df[7] * __uint_as_float((unsigned)ka1 << 16), 0.f) & 0xffffu);
;                 *(unsigned*)(uk_ + 2) = pk2(df[6] * bf_lo(ka2), df[5] * bf_hi(ka2));
;                 *(u32x2*)(uk_ + 4) = (u32x2){pk2(df[4] * bf_lo(ka4.x), df[3] * bf_hi(ka4.x)), pk2(df[2] * bf_lo(ka4.y), df[1] * bf_hi(ka4.y))};
;                 if (col_l) uk_[8] = (bf16_t)(pk2(df[0] * __uint_as_float((unsigned)ka0 << 16), 0.f) & 0xffffu);
;                 if (k != 0) {
;                     uT_[1] = (bf16_t)(pk2(sm[7] * __uint_as_float((unsigned)ta1 << 16), 0.f) & 0xffffu);
;                     *(unsigned*)(uT_ + 2) = pk2(sm[6] * bf_lo(ta2), sm[5] * bf_hi(ta2));
.LBB0_706:
	v_mov_b32_e32 v129, v145
	v_lshl_add_u64 v[40:41], v[60:61], 0, v[128:129]
	s_and_b64 vcc, exec, s[0:1]
	s_mov_b64 s[4:5], -1
	s_cbranch_vccnz .LBB0_708
	v_or_b32_e32 v46, v56, v172
	v_mov_b32_e32 v47, v57
	v_lshlrev_b64 v[50:51], 1, v[46:47]
	v_subrev_u32_e32 v248, s98, v40
	v_add_u32_e32 v248, 256, v248
	v_and_b32_e32 v249, 0xfffff000, v248
	v_and_b32_e32 v250, 0xfff, v248
	v_sub_u32_e32 v251, v250, v249
	v_add_u32_e32 v251, 0x800000, v251
	global_load_dwordx4 v[252:255], v251, s[100:101]
	global_load_dwordx4 v[42:45], v[40:41], off offset:256
	v_lshl_add_u64 v[46:47], s[44:45], 0, v[50:51]
	global_load_dwordx4 v[46:49], v[46:47], off
	v_or_b32_e32 v52, v58, v172
	v_mov_b32_e32 v53, v59
	v_lshlrev_b64 v[52:53], 1, v[52:53]
	v_lshl_add_u64 v[50:51], s[36:37], 0, v[50:51]
	v_lshl_add_u64 v[54:55], s[44:45], 0, v[52:53]
	v_mov_b32_e32 v105, v145
	v_lshl_add_u64 v[52:53], s[36:37], 0, v[52:53]
	s_mov_b64 s[4:5], 0
	s_waitcnt vmcnt(0)
	v_lshlrev_b32_e32 v60, 16, v42
	v_and_b32_e32 v61, 0xffff0000, v42
	v_lshlrev_b32_e32 v62, 16, v43
	v_and_b32_e32 v63, 0xffff0000, v43
	v_lshlrev_b32_e32 v64, 16, v44
	v_and_b32_e32 v65, 0xffff0000, v44
	v_lshlrev_b32_e32 v66, 16, v45
	v_and_b32_e32 v67, 0xffff0000, v45
	v_pk_add_f32 v[68:69], v[36:37], v[60:61]
	v_pk_add_f32 v[70:71], v[38:39], v[62:63]
	v_pk_add_f32 v[72:73], v[32:33], v[64:65]
	v_pk_add_f32 v[74:75], v[34:35], v[66:67]
	v_lshlrev_b32_e32 v42, 16, v46
	v_and_b32_e32 v43, 0xffff0000, v46
	v_lshlrev_b32_e32 v44, 16, v47
	v_and_b32_e32 v45, 0xffff0000, v47
	v_lshlrev_b32_e32 v46, 16, v48
	v_and_b32_e32 v47, 0xffff0000, v48
	v_lshlrev_b32_e32 v48, 16, v49
	v_and_b32_e32 v49, 0xffff0000, v49
	v_pk_mul_f32 v[44:45], v[70:71], v[44:45]
	v_pk_mul_f32 v[42:43], v[68:69], v[42:43]
	v_pk_mul_f32 v[48:49], v[74:75], v[48:49]
	v_pk_mul_f32 v[46:47], v[72:73], v[46:47]
	v_cvt_pk_bf16_f32 v42, v42, v43
	v_cvt_pk_bf16_f32 v43, v44, v45
	v_cvt_pk_bf16_f32 v44, v46, v47
	v_cvt_pk_bf16_f32 v45, v48, v49
	global_store_dwordx4 v[50:51], v[42:45], off
	v_lshlrev_b64 v[50:51], 1, v[56:57]
	v_lshlrev_b64 v[54:55], 1, v[58:59]
	v_sub_f32_e32 v57, v61, v37
	v_sub_f32_e32 v56, v60, v36
	v_sub_f32_e32 v59, v63, v39
	v_sub_f32_e32 v58, v62, v38
	v_sub_f32_e32 v61, v65, v33
	v_sub_f32_e32 v60, v64, v32
	v_sub_f32_e32 v63, v67, v35
	v_sub_f32_e32 v62, v66, v34
	v_lshl_add_u64 v[46:47], s[44:45], 0, v[50:51]
	v_lshl_add_u64 v[48:49], s[44:45], 0, v[54:55]
	v_lshl_add_u64 v[46:47], v[46:47], 0, v[104:105]
	v_lshl_add_u64 v[48:49], v[48:49], 0, v[104:105]
	v_lshl_add_u64 v[50:51], s[36:37], 0, v[50:51]
	v_lshl_add_u64 v[50:51], v[50:51], 0, v[104:105]
	v_mov_b32_e32 v42, v252
	v_mov_b32_e32 v43, v253
	v_mov_b32_e32 v44, v254
	v_mov_b32_e32 v45, v255
	v_lshlrev_b32_e32 v64, 16, v42
	v_and_b32_e32 v65, 0xffff0000, v42
	v_lshlrev_b32_e32 v42, 16, v43
	v_and_b32_e32 v43, 0xffff0000, v43
	v_lshlrev_b32_e32 v66, 16, v44
	v_and_b32_e32 v67, 0xffff0000, v44
	v_lshlrev_b32_e32 v44, 16, v45
	v_and_b32_e32 v45, 0xffff0000, v45
	v_pk_mul_f32 v[76:77], v[58:59], v[42:43]
	v_pk_mul_f32 v[42:43], v[56:57], v[64:65]
	v_pk_mul_f32 v[64:65], v[62:63], v[44:45]
	v_pk_mul_f32 v[44:45], v[60:61], v[66:67]
	v_cvt_pk_bf16_f32 v42, v42, v43
	v_cvt_pk_bf16_f32 v43, v76, v77
	v_cvt_pk_bf16_f32 v44, v44, v45
	v_cvt_pk_bf16_f32 v45, v64, v65
	global_store_dwordx4 v[52:53], v[42:45], off
	global_load_ushort v45, v[46:47], off
	s_nop 0
	global_load_ushort v64, v[48:49], off
	global_load_ushort v65, v[48:49], off offset:-14
	global_load_ushort v66, v[46:47], off offset:-14
	global_load_dwordx3 v[42:44], v[46:47], off offset:-12
	s_nop 0
	global_load_dwordx3 v[46:48], v[48:49], off offset:-12
	v_lshl_add_u64 v[52:53], s[36:37], 0, v[54:55]
	v_lshl_add_u64 v[52:53], v[52:53], 0, v[104:105]
	s_waitcnt vmcnt(5)
	v_lshlrev_b32_e32 v49, 16, v45
	s_waitcnt vmcnt(4)
	v_lshlrev_b32_e32 v76, 16, v64
	s_waitcnt vmcnt(3)
	v_lshlrev_b32_e32 v77, 16, v65
	s_waitcnt vmcnt(2)
	v_lshlrev_b32_e32 v78, 16, v66
	s_waitcnt vmcnt(1)
	v_lshlrev_b32_e32 v54, 16, v42
	v_and_b32_e32 v55, 0xffff0000, v42
	v_lshlrev_b32_e32 v42, 16, v43
	v_and_b32_e32 v43, 0xffff0000, v43
	v_lshlrev_b32_e32 v64, 16, v44
	v_and_b32_e32 v65, 0xffff0000, v44
	s_waitcnt vmcnt(0)
	v_lshlrev_b32_e32 v44, 16, v46
	v_and_b32_e32 v45, 0xffff0000, v46
	v_lshlrev_b32_e32 v66, 16, v48
	v_and_b32_e32 v67, 0xffff0000, v48
	v_mul_f32_e32 v48, v63, v78
	v_mov_b32_e32 v63, v61
	v_mov_b32_e32 v61, v59
	v_mov_b32_e32 v59, v57
	v_mul_f32_e32 v57, v75, v77
	v_mov_b32_e32 v75, v73
	v_lshlrev_b32_e32 v46, 16, v47
	v_and_b32_e32 v47, 0xffff0000, v47
	v_mul_f32_e32 v56, v56, v49
	v_mov_b32_e32 v73, v71
	v_mov_b32_e32 v71, v69
	v_mul_f32_e32 v68, v68, v76
	v_cvt_pk_bf16_f32 v69, v48, s0
	v_pk_mul_f32 v[48:49], v[62:63], v[54:55]
	v_pk_mul_f32 v[42:43], v[60:61], v[42:43]
	v_pk_mul_f32 v[44:45], v[74:75], v[44:45]
	v_pk_mul_f32 v[54:55], v[58:59], v[64:65]
	v_cvt_pk_bf16_f32 v58, v56, s0
	v_cvt_pk_bf16_f32 v59, v57, s0
	v_pk_mul_f32 v[46:47], v[72:73], v[46:47]
	v_pk_mul_f32 v[56:57], v[70:71], v[66:67]
	v_cvt_pk_bf16_f32 v60, v68, s0
	v_cvt_pk_bf16_f32 v48, v48, v49
	v_cvt_pk_bf16_f32 v42, v42, v43
	v_cvt_pk_bf16_f32 v49, v44, v45
	v_cvt_pk_bf16_f32 v43, v54, v55
	global_store_short v[50:51], v58, off
	v_cvt_pk_bf16_f32 v44, v46, v47
	v_cvt_pk_bf16_f32 v45, v56, v57
	global_store_short v[52:53], v60, off
	v_perm_b32 v46, v48, v69, s46
	global_store_short_d16_hi v[50:51], v48, off offset:-10
	global_store_dwordx2 v[50:51], v[42:43], off offset:-8
	v_perm_b32 v42, v49, v59, s46
	global_store_short_d16_hi v[52:53], v49, off offset:-10
	global_store_dwordx2 v[52:53], v[44:45], off offset:-8
	global_store_dword v[50:51], v46, off offset:-14
	global_store_dword v[52:53], v42, off offset:-14

; DI void st_bf16x8(bf16_t* p, f32x4 a, f32x4 b) { u32x4 w = {pk2(a[0], a[1]), pk2(a[2], a[3]), pk2(b[0], b[1]), pk2(b[2], b[3])}; *(u32x4*)p = w; }
; DI void ld_bf16x8(const bf16_t* p, f32x4& a, f32x4& b) { const u32x4 w = *(const u32x4*)p; a = (f32x4){bf_lo(w.x), bf_hi(w.x), bf_lo(w.y), bf_hi(w.y)}; b = (f32x4){bf_lo(w.z), bf_hi(w.z), bf_lo(w.w), bf_hi(w.w)}; }
; DI void fnet_layer(const Args& A, LAS unsigned char* lds, const XcdBarrier& gbar, int layer, int j, bool latonly, int wv) {
;     ...
;         auto E = [=](const pg8::Unit& u, int row_l, int col_l, f32x4 v0, f32x4 v1) {
;             const int k = u.i1 * 256 + row_l, col = (u.i2 & 7) * 256 + col_l;
;             bf16_t* ap = A1 + ((size_t)u.i0 * 1024 + k) * DM + col;
;             if (u.i2 < 8) { st_bf16x8(ap, v0, v1); return; }
;             f32x4 a0, a1; ld_bf16x8(ap, a0, a1);
;             const size_t off = ((size_t)u.i0 * TB + k) * DM + col;
;             f32x4 g0, g1; ld_bf16x8(Gt + off, g0, g1);
;             st_bf16x8(U + off, (a0 + v0) * g0, (a1 + v1) * g1);
;             if (k != 0) { const size_t off2 = ((size_t)u.i0 * TB + (TL - k)) * DM + col; ld_bf16x8(Gt + off2, g0, g1); st_bf16x8(U + off2, (a0 - v0) * g0, (a1 - v1) * g1); }
;             const f32x4 s0 = a0 + v0, s1 = a1 + v1, d0 = a0 - v0, d1 = a1 - v1;
;             const float sm[8] = {s0[0], s0[1], s0[2], s0[3], s1[0], s1[1], s1[2], s1[3]}, df[8] = {d0[0], d0[1], d0[2], d0[3], d1[0], d1[1], d1[2], d1[3]};
;             const size_t rowk = ((size_t)u.i0 * TB + k) * DM, rowT = ((size_t)u.i0 * TB + (TL - k)) * DM; const int cm = (col & ~255) + 512 - col_l;
;             {
;                 const bf16_t* gk_ = Gt + rowk + cm - 8; const bf16_t* gT_ = Gt + rowT + cm - 8; bf16_t* uk_ = U + rowk + cm - 8; bf16_t* uT_ = U + rowT + cm - 8;
;                 const unsigned short ka1 = gk_[1]; const unsigned ka2 = *(const unsigned*)(gk_ + 2); const u32x2 ka4 = *(const u32x2*)(gk_ + 4); const unsigned short ka0 = col_l ? gk_[8] : (unsigned short)0;
;                 unsigned short ta1 = 0, ta0 = 0; unsigned ta2 = 0; u32x2 ta4 = {0u, 0u};
;                 if (k != 0) { ta1 = gT_[1]; ta2 = *(const unsigned*)(gT_ + 2); ta4 = *(const u32x2*)(gT_ + 4); ta0 = col_l ? gT_[8] : (unsigned short)0; }
.LBB0_710:
	v_add_u32_e32 v32, 0xa0, v150
	v_ashrrev_i32_e32 v33, 31, v32
	v_lshlrev_b64 v[34:35], 12, v[32:33]
	v_lshl_add_u64 v[32:33], s[66:67], 0, v[32:33]
	v_lshlrev_b64 v[40:41], 11, v[32:33]
	v_sub_u32_e32 v32, 0x760, v150
	v_ashrrev_i32_e32 v33, 31, v32
	v_lshl_add_u64 v[32:33], s[66:67], 0, v[32:33]
	v_lshl_add_u64 v[44:45], s[68:69], 0, v[34:35]
	v_mov_b32_e32 v153, v145
	v_lshlrev_b64 v[42:43], 11, v[32:33]
	v_lshl_add_u64 v[46:47], v[44:45], 0, v[152:153]
	s_and_b64 vcc, exec, s[0:1]
	s_mov_b64 s[4:5], -1
	s_cbranch_vccnz .LBB0_720
	v_or_b32_e32 v36, v40, v189
	v_mov_b32_e32 v37, v41
	v_lshlrev_b64 v[48:49], 1, v[36:37]
	v_subrev_u32_e32 v248, s98, v46
	v_and_b32_e32 v249, 0xfffff000, v248
	v_and_b32_e32 v250, 0xfff, v248
	v_sub_u32_e32 v251, v250, v249
	v_add_u32_e32 v251, 0x800000, v251
	global_load_dwordx4 v[252:255], v251, s[100:101]
	global_load_dwordx4 v[32:35], v[46:47], off
	v_lshl_add_u64 v[36:37], s[44:45], 0, v[48:49]
	global_load_dwordx4 v[36:39], v[36:37], off
	v_or_b32_e32 v50, v42, v189
	v_mov_b32_e32 v51, v43
	v_lshlrev_b64 v[56:57], 1, v[50:51]
	v_lshl_add_u64 v[58:59], s[36:37], 0, v[48:49]
	v_lshl_add_u64 v[60:61], s[44:45], 0, v[56:57]
	v_lshl_add_u64 v[70:71], s[36:37], 0, v[56:57]
	v_cmp_ne_u32_e32 vcc, 0, v151
	s_waitcnt vmcnt(0)
	v_lshlrev_b32_e32 v62, 16, v32
	v_and_b32_e32 v63, 0xffff0000, v32
	v_lshlrev_b32_e32 v64, 16, v33
	v_and_b32_e32 v65, 0xffff0000, v33
	v_lshlrev_b32_e32 v66, 16, v34
	v_and_b32_e32 v67, 0xffff0000, v34
	v_lshlrev_b32_e32 v68, 16, v35
	v_and_b32_e32 v69, 0xffff0000, v35
	v_pk_add_f32 v[50:51], v[30:31], v[64:65]
	v_pk_add_f32 v[48:49], v[28:29], v[62:63]
	v_pk_add_f32 v[54:55], v[26:27], v[68:69]
	v_pk_add_f32 v[52:53], v[24:25], v[66:67]
	v_lshlrev_b32_e32 v32, 16, v36
	v_and_b32_e32 v33, 0xffff0000, v36
	v_lshlrev_b32_e32 v34, 16, v37
	v_and_b32_e32 v35, 0xffff0000, v37
	v_lshlrev_b32_e32 v36, 16, v38
	v_and_b32_e32 v37, 0xffff0000, v38
	v_lshlrev_b32_e32 v38, 16, v39
	v_and_b32_e32 v39, 0xffff0000, v39
	v_pk_mul_f32 v[34:35], v[50:51], v[34:35]
	v_pk_mul_f32 v[32:33], v[48:49], v[32:33]
	v_pk_mul_f32 v[38:39], v[54:55], v[38:39]
	v_pk_mul_f32 v[36:37], v[52:53], v[36:37]
	v_cvt_pk_bf16_f32 v32, v32, v33
	v_cvt_pk_bf16_f32 v33, v34, v35
	v_cvt_pk_bf16_f32 v34, v36, v37
	v_cvt_pk_bf16_f32 v35, v38, v39
	global_store_dwordx4 v[58:59], v[32:35], off
	v_sub_f32_e32 v58, v64, v30
	v_sub_f32_e32 v61, v65, v31
	v_sub_f32_e32 v56, v62, v28
	v_sub_f32_e32 v35, v69, v27
	v_sub_f32_e32 v62, v68, v26
	v_mov_b32_e32 v60, v58
	v_sub_f32_e32 v59, v63, v29
	v_sub_f32_e32 v63, v67, v25
	v_mov_b32_e32 v57, v59
	v_mov_b32_e32 v34, v62
	v_mov_b32_e32 v65, v63
	v_lshl_add_u64 v[32:33], v[40:41], 1, s[44:45]
	v_lshl_add_u64 v[32:33], v[32:33], 0, v[144:145]
	v_mov_b32_e32 v36, v252
	v_mov_b32_e32 v37, v253
	v_mov_b32_e32 v38, v254
	v_mov_b32_e32 v39, v255
	v_lshlrev_b32_e32 v68, 16, v36
	v_and_b32_e32 v69, 0xffff0000, v36
	v_lshlrev_b32_e32 v36, 16, v37
	v_and_b32_e32 v37, 0xffff0000, v37
	v_pk_mul_f32 v[74:75], v[60:61], v[36:37]
	v_sub_f32_e32 v60, v66, v24
	v_lshlrev_b32_e32 v72, 16, v38
	v_and_b32_e32 v73, 0xffff0000, v38
	v_lshlrev_b32_e32 v38, 16, v39
	v_and_b32_e32 v39, 0xffff0000, v39
	v_mov_b32_e32 v64, v60
	v_pk_mul_f32 v[36:37], v[56:57], v[68:69]
	v_pk_mul_f32 v[38:39], v[34:35], v[38:39]
	v_pk_mul_f32 v[64:65], v[64:65], v[72:73]
	v_cvt_pk_bf16_f32 v36, v36, v37
	v_cvt_pk_bf16_f32 v37, v74, v75
	v_cvt_pk_bf16_f32 v39, v38, v39
	v_cvt_pk_bf16_f32 v38, v64, v65
	global_store_dwordx4 v[70:71], v[36:39], off
	global_load_ushort v67, v[32:33], off offset:-14
	s_nop 0
	global_load_dwordx3 v[36:38], v[32:33], off offset:-12
	v_mov_b32_e32 v39, 0
	v_mov_b32_e32 v57, 0
	s_and_saveexec_b64 s[4:5], vcc
	s_cbranch_execz .LBB0_713
	global_load_ushort v32, v[32:33], off
	s_waitcnt vmcnt(0)
	v_lshlrev_b32_e32 v57, 16, v32

; DI void fnet_layer(const Args& A, LAS unsigned char* lds, const XcdBarrier& gbar, int layer, int j, bool latonly, int wv) {
;     ...
;             bf16_t* ap = A1 + ((size_t)u.i0 * 1024 + k) * DM + col;
;             if (u.i2 < 8) { st_bf16x8(ap, v0, v1); return; }
;             f32x4 a0, a1; ld_bf16x8(ap, a0, a1);
;             const size_t off = ((size_t)u.i0 * TB + k) * DM + col;
;             f32x4 g0, g1; ld_bf16x8(Gt + off, g0, g1);
;             st_bf16x8(U + off, (a0 + v0) * g0, (a1 + v1) * g1);
;             if (k != 0) { const size_t off2 = ((size_t)u.i0 * TB + (TL - k)) * DM + col; ld_bf16x8(Gt + off2, g0, g1); st_bf16x8(U + off2, (a0 - v0) * g0, (a1 - v1) * g1); }
;             const f32x4 s0 = a0 + v0, s1 = a1 + v1, d0 = a0 - v0, d1 = a1 - v1;
;             const float sm[8] = {s0[0], s0[1], s0[2], s0[3], s1[0], s1[1], s1[2], s1[3]}, df[8] = {d0[0], d0[1], d0[2], d0[3], d1[0], d1[1], d1[2], d1[3]};
;             const size_t rowk = ((size_t)u.i0 * TB + k) * DM, rowT = ((size_t)u.i0 * TB + (TL - k)) * DM; const int cm = (col & ~255) + 512 - col_l;
;             {
;                 const bf16_t* gk_ = Gt + rowk + cm - 8; const bf16_t* gT_ = Gt + rowT + cm - 8; bf16_t* uk_ = U + rowk + cm - 8; bf16_t* uT_ = U + rowT + cm - 8;
;                 const unsigned short ka1 = gk_[1]; const unsigned ka2 = *(const unsigned*)(gk_ + 2); const u32x2 ka4 = *(const u32x2*)(gk_ + 4); const unsigned short ka0 = col_l ? gk_[8] : (unsigned short)0;
;                 unsigned short ta1 = 0, ta0 = 0; unsigned ta2 = 0; u32x2 ta4 = {0u, 0u};
;                 if (k != 0) { ta1 = gT_[1]; ta2 = *(const unsigned*)(gT_ + 2); ta4 = *(const u32x2*)(gT_ + 4); ta0 = col_l ? gT_[8] : (unsigned short)0; }
;                 uk_[1] = (bf16_t)(pk2(df[7] * __uint_as_float((unsigned)ka1 << 16), 0.f) & 0xffffu);
;                 *(unsigned*)(uk_ + 2) = pk2(df[6] * bf_lo(ka2), df[5] * bf_hi(ka2));
;                 *(u32x2*)(uk_ + 4) = (u32x2){pk2(df[4] * bf_lo(ka4.x), df[3] * bf_hi(ka4.x)), pk2(df[2] * bf_lo(ka4.y), df[1] * bf_hi(ka4.y))};
;                 if (col_l) uk_[8] = (bf16_t)(pk2(df[0] * __uint_as_float((unsigned)ka0 << 16), 0.f) & 0xffffu);
;                 if (k != 0) {
;                     uT_[1] = (bf16_t)(pk2(sm[7] * __uint_as_float((unsigned)ta1 << 16), 0.f) & 0xffffu);
;                     *(unsigned*)(uT_ + 2) = pk2(sm[6] * bf_lo(ta2), sm[5] * bf_hi(ta2));
.LBB0_722:
	v_mov_b32_e32 v129, v145
	v_lshl_add_u64 v[24:25], v[44:45], 0, v[128:129]
	s_and_b64 vcc, exec, s[0:1]
	s_mov_b64 s[4:5], -1
	s_cbranch_vccnz .LBB0_724
	v_or_b32_e32 v30, v40, v172
	v_mov_b32_e32 v31, v41
	v_lshlrev_b64 v[34:35], 1, v[30:31]
	v_subrev_u32_e32 v248, s98, v24
	v_add_u32_e32 v248, 256, v248
	v_and_b32_e32 v249, 0xfffff000, v248
	v_and_b32_e32 v250, 0xfff, v248
	v_sub_u32_e32 v251, v250, v249
	v_add_u32_e32 v251, 0x800000, v251
	global_load_dwordx4 v[252:255], v251, s[100:101]
	global_load_dwordx4 v[26:29], v[24:25], off offset:256
	v_lshl_add_u64 v[30:31], s[44:45], 0, v[34:35]
	global_load_dwordx4 v[30:33], v[30:31], off
	v_or_b32_e32 v36, v42, v172
	v_mov_b32_e32 v37, v43
	v_lshlrev_b64 v[36:37], 1, v[36:37]
	v_lshl_add_u64 v[34:35], s[36:37], 0, v[34:35]
	v_lshl_add_u64 v[38:39], s[44:45], 0, v[36:37]
	v_mov_b32_e32 v105, v145
	v_lshl_add_u64 v[36:37], s[36:37], 0, v[36:37]
	s_mov_b64 s[4:5], 0
	s_waitcnt vmcnt(0)
	v_lshlrev_b32_e32 v44, 16, v26
	v_and_b32_e32 v45, 0xffff0000, v26
	v_lshlrev_b32_e32 v46, 16, v27
	v_and_b32_e32 v47, 0xffff0000, v27
	v_lshlrev_b32_e32 v48, 16, v28
	v_and_b32_e32 v49, 0xffff0000, v28
	v_lshlrev_b32_e32 v50, 16, v29
	v_and_b32_e32 v51, 0xffff0000, v29
	v_pk_add_f32 v[52:53], v[20:21], v[44:45]
	v_pk_add_f32 v[54:55], v[22:23], v[46:47]
	v_pk_add_f32 v[56:57], v[16:17], v[48:49]
	v_pk_add_f32 v[58:59], v[18:19], v[50:51]
	v_lshlrev_b32_e32 v26, 16, v30
	v_and_b32_e32 v27, 0xffff0000, v30
	v_lshlrev_b32_e32 v28, 16, v31
	v_and_b32_e32 v29, 0xffff0000, v31
	v_lshlrev_b32_e32 v30, 16, v32
	v_and_b32_e32 v31, 0xffff0000, v32
	v_lshlrev_b32_e32 v32, 16, v33
	v_and_b32_e32 v33, 0xffff0000, v33
	v_pk_mul_f32 v[28:29], v[54:55], v[28:29]
	v_pk_mul_f32 v[26:27], v[52:53], v[26:27]
	v_pk_mul_f32 v[32:33], v[58:59], v[32:33]
	v_pk_mul_f32 v[30:31], v[56:57], v[30:31]
	v_cvt_pk_bf16_f32 v26, v26, v27
	v_cvt_pk_bf16_f32 v27, v28, v29
	v_cvt_pk_bf16_f32 v28, v30, v31
	v_cvt_pk_bf16_f32 v29, v32, v33
	global_store_dwordx4 v[34:35], v[26:29], off
	v_lshlrev_b64 v[34:35], 1, v[40:41]
	v_lshlrev_b64 v[38:39], 1, v[42:43]
	v_sub_f32_e32 v41, v45, v21
	v_sub_f32_e32 v40, v44, v20
	v_sub_f32_e32 v43, v47, v23
	v_sub_f32_e32 v42, v46, v22
	v_sub_f32_e32 v45, v49, v17
	v_sub_f32_e32 v44, v48, v16
	v_sub_f32_e32 v47, v51, v19
	v_sub_f32_e32 v46, v50, v18
	v_lshl_add_u64 v[30:31], s[44:45], 0, v[34:35]
	v_lshl_add_u64 v[32:33], s[44:45], 0, v[38:39]
	v_lshl_add_u64 v[30:31], v[30:31], 0, v[104:105]
	v_lshl_add_u64 v[32:33], v[32:33], 0, v[104:105]
	v_lshl_add_u64 v[34:35], s[36:37], 0, v[34:35]
	v_lshl_add_u64 v[34:35], v[34:35], 0, v[104:105]
	v_mov_b32_e32 v26, v252
	v_mov_b32_e32 v27, v253
	v_mov_b32_e32 v28, v254
	v_mov_b32_e32 v29, v255
	v_lshlrev_b32_e32 v48, 16, v26
	v_and_b32_e32 v49, 0xffff0000, v26
	v_lshlrev_b32_e32 v26, 16, v27
	v_and_b32_e32 v27, 0xffff0000, v27
	v_lshlrev_b32_e32 v50, 16, v28
	v_and_b32_e32 v51, 0xffff0000, v28
	v_lshlrev_b32_e32 v28, 16, v29
	v_and_b32_e32 v29, 0xffff0000, v29
	v_pk_mul_f32 v[60:61], v[42:43], v[26:27]
	v_pk_mul_f32 v[26:27], v[40:41], v[48:49]
	v_pk_mul_f32 v[48:49], v[46:47], v[28:29]
	v_pk_mul_f32 v[28:29], v[44:45], v[50:51]
	v_cvt_pk_bf16_f32 v26, v26, v27
	v_cvt_pk_bf16_f32 v27, v60, v61
	v_cvt_pk_bf16_f32 v28, v28, v29
	v_cvt_pk_bf16_f32 v29, v48, v49
	global_store_dwordx4 v[36:37], v[26:29], off
	global_load_ushort v29, v[30:31], off
	s_nop 0
	global_load_ushort v48, v[32:33], off
	global_load_ushort v49, v[32:33], off offset:-14
	global_load_ushort v50, v[30:31], off offset:-14
	global_load_dwordx3 v[26:28], v[30:31], off offset:-12
	s_nop 0
	global_load_dwordx3 v[30:32], v[32:33], off offset:-12
	v_lshl_add_u64 v[36:37], s[36:37], 0, v[38:39]
	v_lshl_add_u64 v[36:37], v[36:37], 0, v[104:105]
	s_waitcnt vmcnt(5)
	v_lshlrev_b32_e32 v33, 16, v29
	s_waitcnt vmcnt(4)
	v_lshlrev_b32_e32 v60, 16, v48
	s_waitcnt vmcnt(3)
	v_lshlrev_b32_e32 v61, 16, v49
	s_waitcnt vmcnt(2)
	v_lshlrev_b32_e32 v62, 16, v50
	s_waitcnt vmcnt(1)
	v_lshlrev_b32_e32 v38, 16, v26
	v_and_b32_e32 v39, 0xffff0000, v26
	v_lshlrev_b32_e32 v26, 16, v27
	v_and_b32_e32 v27, 0xffff0000, v27
	v_lshlrev_b32_e32 v48, 16, v28
	v_and_b32_e32 v49, 0xffff0000, v28
	s_waitcnt vmcnt(0)
	v_lshlrev_b32_e32 v28, 16, v30
	v_and_b32_e32 v29, 0xffff0000, v30
	v_lshlrev_b32_e32 v30, 16, v31
	v_and_b32_e32 v31, 0xffff0000, v31
	v_lshlrev_b32_e32 v50, 16, v32
	v_and_b32_e32 v51, 0xffff0000, v32
	v_mul_f32_e32 v32, v47, v62
	v_mov_b32_e32 v47, v45
	v_mov_b32_e32 v45, v43
	v_mov_b32_e32 v43, v41
	v_mul_f32_e32 v40, v40, v33
	v_mul_f32_e32 v41, v59, v61
	v_mov_b32_e32 v59, v57
	v_mov_b32_e32 v57, v55
	v_mov_b32_e32 v55, v53
	v_mul_f32_e32 v52, v52, v60
	v_cvt_pk_bf16_f32 v53, v32, s0
	v_pk_mul_f32 v[32:33], v[46:47], v[38:39]
	v_pk_mul_f32 v[26:27], v[44:45], v[26:27]
	v_pk_mul_f32 v[38:39], v[42:43], v[48:49]
	v_cvt_pk_bf16_f32 v42, v40, s0
	v_cvt_pk_bf16_f32 v43, v41, s0
	v_pk_mul_f32 v[28:29], v[58:59], v[28:29]
	v_pk_mul_f32 v[30:31], v[56:57], v[30:31]
	v_pk_mul_f32 v[40:41], v[54:55], v[50:51]
	v_cvt_pk_bf16_f32 v44, v52, s0
	v_cvt_pk_bf16_f32 v32, v32, v33
	v_cvt_pk_bf16_f32 v26, v26, v27
	v_cvt_pk_bf16_f32 v33, v28, v29
	v_cvt_pk_bf16_f32 v28, v30, v31
	v_cvt_pk_bf16_f32 v29, v40, v41
	v_cvt_pk_bf16_f32 v27, v38, v39
	global_store_short v[34:35], v42, off
	global_store_short v[36:37], v44, off
	v_perm_b32 v30, v32, v53, s46
	global_store_short_d16_hi v[34:35], v32, off offset:-10
	global_store_dwordx2 v[34:35], v[26:27], off offset:-8
	v_perm_b32 v26, v33, v43, s46
	global_store_dwordx2 v[36:37], v[28:29], off offset:-8
	global_store_dword v[34:35], v30, off offset:-14
	global_store_short_d16_hi v[36:37], v33, off offset:-10
	global_store_dword v[36:37], v26, off offset:-14

; DI void st_bf16x8(bf16_t* p, f32x4 a, f32x4 b) { u32x4 w = {pk2(a[0], a[1]), pk2(a[2], a[3]), pk2(b[0], b[1]), pk2(b[2], b[3])}; *(u32x4*)p = w; }
; DI void ld_bf16x8(const bf16_t* p, f32x4& a, f32x4& b) { const u32x4 w = *(const u32x4*)p; a = (f32x4){bf_lo(w.x), bf_hi(w.x), bf_lo(w.y), bf_hi(w.y)}; b = (f32x4){bf_lo(w.z), bf_hi(w.z), bf_lo(w.w), bf_hi(w.w)}; }
; DI void fnet_layer(const Args& A, LAS unsigned char* lds, const XcdBarrier& gbar, int layer, int j, bool latonly, int wv) {
;     ...
;         auto E = [=](const pg8::Unit& u, int row_l, int col_l, f32x4 v0, f32x4 v1) {
;             const int k = u.i1 * 256 + row_l, col = (u.i2 & 7) * 256 + col_l;
;             bf16_t* ap = A1 + ((size_t)u.i0 * 1024 + k) * DM + col;
;             if (u.i2 < 8) { st_bf16x8(ap, v0, v1); return; }
;             f32x4 a0, a1; ld_bf16x8(ap, a0, a1);
;             const size_t off = ((size_t)u.i0 * TB + k) * DM + col;
;             f32x4 g0, g1; ld_bf16x8(Gt + off, g0, g1);
;             st_bf16x8(U + off, (a0 + v0) * g0, (a1 + v1) * g1);
;             if (k != 0) { const size_t off2 = ((size_t)u.i0 * TB + (TL - k)) * DM + col; ld_bf16x8(Gt + off2, g0, g1); st_bf16x8(U + off2, (a0 - v0) * g0, (a1 - v1) * g1); }
;             const f32x4 s0 = a0 + v0, s1 = a1 + v1, d0 = a0 - v0, d1 = a1 - v1;
;             const float sm[8] = {s0[0], s0[1], s0[2], s0[3], s1[0], s1[1], s1[2], s1[3]}, df[8] = {d0[0], d0[1], d0[2], d0[3], d1[0], d1[1], d1[2], d1[3]};
;             const size_t rowk = ((size_t)u.i0 * TB + k) * DM, rowT = ((size_t)u.i0 * TB + (TL - k)) * DM; const int cm = (col & ~255) + 512 - col_l;
;             {
;                 const bf16_t* gk_ = Gt + rowk + cm - 8; const bf16_t* gT_ = Gt + rowT + cm - 8; bf16_t* uk_ = U + rowk + cm - 8; bf16_t* uT_ = U + rowT + cm - 8;
;                 const unsigned short ka1 = gk_[1]; const unsigned ka2 = *(const unsigned*)(gk_ + 2); const u32x2 ka4 = *(const u32x2*)(gk_ + 4); const unsigned short ka0 = col_l ? gk_[8] : (unsigned short)0;
;                 unsigned short ta1 = 0, ta0 = 0; unsigned ta2 = 0; u32x2 ta4 = {0u, 0u};
;                 if (k != 0) { ta1 = gT_[1]; ta2 = *(const unsigned*)(gT_ + 2); ta4 = *(const u32x2*)(gT_ + 4); ta0 = col_l ? gT_[8] : (unsigned short)0; }
.LBB0_726:
	v_add_u32_e32 v16, 0xb0, v150
	v_ashrrev_i32_e32 v17, 31, v16
	v_lshlrev_b64 v[18:19], 12, v[16:17]
	v_lshl_add_u64 v[16:17], s[66:67], 0, v[16:17]
	v_lshlrev_b64 v[24:25], 11, v[16:17]
	v_sub_u32_e32 v16, 0x750, v150
	v_ashrrev_i32_e32 v17, 31, v16
	v_lshl_add_u64 v[16:17], s[66:67], 0, v[16:17]
	v_lshl_add_u64 v[28:29], s[68:69], 0, v[18:19]
	v_mov_b32_e32 v153, v145
	v_lshlrev_b64 v[26:27], 11, v[16:17]
	v_lshl_add_u64 v[30:31], v[28:29], 0, v[152:153]
	s_and_b64 vcc, exec, s[0:1]
	s_mov_b64 s[4:5], -1
	s_cbranch_vccnz .LBB0_736
	v_or_b32_e32 v20, v24, v189
	v_mov_b32_e32 v21, v25
	v_lshlrev_b64 v[32:33], 1, v[20:21]
	v_subrev_u32_e32 v248, s98, v30
	v_and_b32_e32 v249, 0xfffff000, v248
	v_and_b32_e32 v250, 0xfff, v248
	v_sub_u32_e32 v251, v250, v249
	v_add_u32_e32 v251, 0x800000, v251
	global_load_dwordx4 v[252:255], v251, s[100:101]
	global_load_dwordx4 v[16:19], v[30:31], off
	v_lshl_add_u64 v[20:21], s[44:45], 0, v[32:33]
	global_load_dwordx4 v[20:23], v[20:21], off
	v_or_b32_e32 v34, v26, v189
	v_mov_b32_e32 v35, v27
	v_lshlrev_b64 v[40:41], 1, v[34:35]
	v_lshl_add_u64 v[42:43], s[36:37], 0, v[32:33]
	v_lshl_add_u64 v[44:45], s[44:45], 0, v[40:41]
	v_lshl_add_u64 v[54:55], s[36:37], 0, v[40:41]
	v_cmp_ne_u32_e32 vcc, 0, v151
	s_waitcnt vmcnt(0)
	v_lshlrev_b32_e32 v46, 16, v16
	v_and_b32_e32 v47, 0xffff0000, v16
	v_lshlrev_b32_e32 v48, 16, v17
	v_and_b32_e32 v49, 0xffff0000, v17
	v_lshlrev_b32_e32 v50, 16, v18
	v_and_b32_e32 v51, 0xffff0000, v18
	v_lshlrev_b32_e32 v52, 16, v19
	v_and_b32_e32 v53, 0xffff0000, v19
	v_pk_add_f32 v[34:35], v[14:15], v[48:49]
	v_pk_add_f32 v[32:33], v[12:13], v[46:47]
	v_pk_add_f32 v[38:39], v[10:11], v[52:53]
	v_pk_add_f32 v[36:37], v[8:9], v[50:51]
	v_lshlrev_b32_e32 v16, 16, v20
	v_and_b32_e32 v17, 0xffff0000, v20
	v_lshlrev_b32_e32 v18, 16, v21
	v_and_b32_e32 v19, 0xffff0000, v21
	v_lshlrev_b32_e32 v20, 16, v22
	v_and_b32_e32 v21, 0xffff0000, v22
	v_lshlrev_b32_e32 v22, 16, v23
	v_and_b32_e32 v23, 0xffff0000, v23
	v_pk_mul_f32 v[18:19], v[34:35], v[18:19]
	v_pk_mul_f32 v[16:17], v[32:33], v[16:17]
	v_pk_mul_f32 v[22:23], v[38:39], v[22:23]
	v_pk_mul_f32 v[20:21], v[36:37], v[20:21]
	v_cvt_pk_bf16_f32 v16, v16, v17
	v_cvt_pk_bf16_f32 v17, v18, v19
	v_cvt_pk_bf16_f32 v18, v20, v21
	v_cvt_pk_bf16_f32 v19, v22, v23
	global_store_dwordx4 v[42:43], v[16:19], off
	v_sub_f32_e32 v42, v48, v14
	v_sub_f32_e32 v45, v49, v15
	v_sub_f32_e32 v40, v46, v12
	v_sub_f32_e32 v19, v53, v11
	v_sub_f32_e32 v46, v52, v10
	v_mov_b32_e32 v44, v42
	v_sub_f32_e32 v43, v47, v13
	v_sub_f32_e32 v47, v51, v9
	v_mov_b32_e32 v41, v43
	v_mov_b32_e32 v18, v46
	v_mov_b32_e32 v49, v47
	v_lshl_add_u64 v[16:17], v[24:25], 1, s[44:45]
	v_lshl_add_u64 v[16:17], v[16:17], 0, v[144:145]
	v_mov_b32_e32 v20, v252
	v_mov_b32_e32 v21, v253
	v_mov_b32_e32 v22, v254
	v_mov_b32_e32 v23, v255
	v_lshlrev_b32_e32 v52, 16, v20
	v_and_b32_e32 v53, 0xffff0000, v20
	v_lshlrev_b32_e32 v20, 16, v21
	v_and_b32_e32 v21, 0xffff0000, v21
	v_pk_mul_f32 v[58:59], v[44:45], v[20:21]
	v_sub_f32_e32 v44, v50, v8
	v_lshlrev_b32_e32 v56, 16, v22
	v_and_b32_e32 v57, 0xffff0000, v22
	v_lshlrev_b32_e32 v22, 16, v23
	v_and_b32_e32 v23, 0xffff0000, v23
	v_mov_b32_e32 v48, v44
	v_pk_mul_f32 v[20:21], v[40:41], v[52:53]
	v_pk_mul_f32 v[22:23], v[18:19], v[22:23]
	v_pk_mul_f32 v[48:49], v[48:49], v[56:57]
	v_cvt_pk_bf16_f32 v20, v20, v21
	v_cvt_pk_bf16_f32 v21, v58, v59
	v_cvt_pk_bf16_f32 v23, v22, v23
	v_cvt_pk_bf16_f32 v22, v48, v49
	global_store_dwordx4 v[54:55], v[20:23], off
	global_load_ushort v51, v[16:17], off offset:-14
	s_nop 0
	global_load_dwordx3 v[20:22], v[16:17], off offset:-12
	v_mov_b32_e32 v23, 0
	v_mov_b32_e32 v41, 0
	s_and_saveexec_b64 s[4:5], vcc
	s_cbranch_execz .LBB0_729
	global_load_ushort v16, v[16:17], off
	s_waitcnt vmcnt(0)
	v_lshlrev_b32_e32 v41, 16, v16

; DI void fnet_layer(const Args& A, LAS unsigned char* lds, const XcdBarrier& gbar, int layer, int j, bool latonly, int wv) {
;     ...
;             bf16_t* ap = A1 + ((size_t)u.i0 * 1024 + k) * DM + col;
;             if (u.i2 < 8) { st_bf16x8(ap, v0, v1); return; }
;             f32x4 a0, a1; ld_bf16x8(ap, a0, a1);
;             const size_t off = ((size_t)u.i0 * TB + k) * DM + col;
;             f32x4 g0, g1; ld_bf16x8(Gt + off, g0, g1);
;             st_bf16x8(U + off, (a0 + v0) * g0, (a1 + v1) * g1);
;             if (k != 0) { const size_t off2 = ((size_t)u.i0 * TB + (TL - k)) * DM + col; ld_bf16x8(Gt + off2, g0, g1); st_bf16x8(U + off2, (a0 - v0) * g0, (a1 - v1) * g1); }
;             const f32x4 s0 = a0 + v0, s1 = a1 + v1, d0 = a0 - v0, d1 = a1 - v1;
;             const float sm[8] = {s0[0], s0[1], s0[2], s0[3], s1[0], s1[1], s1[2], s1[3]}, df[8] = {d0[0], d0[1], d0[2], d0[3], d1[0], d1[1], d1[2], d1[3]};
;             const size_t rowk = ((size_t)u.i0 * TB + k) * DM, rowT = ((size_t)u.i0 * TB + (TL - k)) * DM; const int cm = (col & ~255) + 512 - col_l;
;             {
;                 const bf16_t* gk_ = Gt + rowk + cm - 8; const bf16_t* gT_ = Gt + rowT + cm - 8; bf16_t* uk_ = U + rowk + cm - 8; bf16_t* uT_ = U + rowT + cm - 8;
;                 const unsigned short ka1 = gk_[1]; const unsigned ka2 = *(const unsigned*)(gk_ + 2); const u32x2 ka4 = *(const u32x2*)(gk_ + 4); const unsigned short ka0 = col_l ? gk_[8] : (unsigned short)0;
;                 unsigned short ta1 = 0, ta0 = 0; unsigned ta2 = 0; u32x2 ta4 = {0u, 0u};
;                 if (k != 0) { ta1 = gT_[1]; ta2 = *(const unsigned*)(gT_ + 2); ta4 = *(const u32x2*)(gT_ + 4); ta0 = col_l ? gT_[8] : (unsigned short)0; }
;                 uk_[1] = (bf16_t)(pk2(df[7] * __uint_as_float((unsigned)ka1 << 16), 0.f) & 0xffffu);
;                 *(unsigned*)(uk_ + 2) = pk2(df[6] * bf_lo(ka2), df[5] * bf_hi(ka2));
;                 *(u32x2*)(uk_ + 4) = (u32x2){pk2(df[4] * bf_lo(ka4.x), df[3] * bf_hi(ka4.x)), pk2(df[2] * bf_lo(ka4.y), df[1] * bf_hi(ka4.y))};
;                 if (col_l) uk_[8] = (bf16_t)(pk2(df[0] * __uint_as_float((unsigned)ka0 << 16), 0.f) & 0xffffu);
;                 if (k != 0) {
;                     uT_[1] = (bf16_t)(pk2(sm[7] * __uint_as_float((unsigned)ta1 << 16), 0.f) & 0xffffu);
;                     *(unsigned*)(uT_ + 2) = pk2(sm[6] * bf_lo(ta2), sm[5] * bf_hi(ta2));
.LBB0_738:
	v_mov_b32_e32 v129, v145
	v_lshl_add_u64 v[8:9], v[28:29], 0, v[128:129]
	s_and_b64 vcc, exec, s[0:1]
	s_mov_b64 s[0:1], -1
	s_cbranch_vccnz .LBB0_741
	v_or_b32_e32 v14, v24, v172
	v_mov_b32_e32 v15, v25
	v_lshlrev_b64 v[18:19], 1, v[14:15]
	v_subrev_u32_e32 v248, s98, v8
	v_add_u32_e32 v248, 256, v248
	v_and_b32_e32 v249, 0xfffff000, v248
	v_and_b32_e32 v250, 0xfff, v248
	v_sub_u32_e32 v251, v250, v249
	v_add_u32_e32 v251, 0x800000, v251
	global_load_dwordx4 v[252:255], v251, s[100:101]
	global_load_dwordx4 v[10:13], v[8:9], off offset:256
	v_lshl_add_u64 v[14:15], s[44:45], 0, v[18:19]
	global_load_dwordx4 v[14:17], v[14:15], off
	v_or_b32_e32 v20, v26, v172
	v_mov_b32_e32 v21, v27
	v_lshlrev_b64 v[20:21], 1, v[20:21]
	v_lshl_add_u64 v[18:19], s[36:37], 0, v[18:19]
	v_lshl_add_u64 v[22:23], s[44:45], 0, v[20:21]
	v_mov_b32_e32 v105, v145
	v_lshl_add_u64 v[20:21], s[36:37], 0, v[20:21]
	s_waitcnt vmcnt(0)
	v_lshlrev_b32_e32 v28, 16, v10
	v_and_b32_e32 v29, 0xffff0000, v10
	v_lshlrev_b32_e32 v30, 16, v11
	v_and_b32_e32 v31, 0xffff0000, v11
	v_lshlrev_b32_e32 v32, 16, v12
	v_and_b32_e32 v33, 0xffff0000, v12
	v_lshlrev_b32_e32 v34, 16, v13
	v_and_b32_e32 v35, 0xffff0000, v13
	v_pk_add_f32 v[36:37], v[4:5], v[28:29]
	v_pk_add_f32 v[38:39], v[6:7], v[30:31]
	v_pk_add_f32 v[40:41], v[0:1], v[32:33]
	v_pk_add_f32 v[42:43], v[2:3], v[34:35]
	v_lshlrev_b32_e32 v10, 16, v14
	v_and_b32_e32 v11, 0xffff0000, v14
	v_lshlrev_b32_e32 v12, 16, v15
	v_and_b32_e32 v13, 0xffff0000, v15
	v_lshlrev_b32_e32 v14, 16, v16
	v_and_b32_e32 v15, 0xffff0000, v16
	v_lshlrev_b32_e32 v16, 16, v17
	v_and_b32_e32 v17, 0xffff0000, v17
	v_pk_mul_f32 v[12:13], v[38:39], v[12:13]
	v_pk_mul_f32 v[10:11], v[36:37], v[10:11]
	v_pk_mul_f32 v[16:17], v[42:43], v[16:17]
	v_pk_mul_f32 v[14:15], v[40:41], v[14:15]
	v_cvt_pk_bf16_f32 v10, v10, v11
	v_cvt_pk_bf16_f32 v11, v12, v13
	v_cvt_pk_bf16_f32 v12, v14, v15
	v_cvt_pk_bf16_f32 v13, v16, v17
	global_store_dwordx4 v[18:19], v[10:13], off
	v_lshlrev_b64 v[18:19], 1, v[24:25]
	v_lshlrev_b64 v[22:23], 1, v[26:27]
	v_sub_f32_e32 v25, v29, v5
	v_sub_f32_e32 v24, v28, v4
	v_sub_f32_e32 v27, v31, v7
	v_sub_f32_e32 v26, v30, v6
	v_sub_f32_e32 v29, v33, v1
	v_sub_f32_e32 v28, v32, v0
	v_sub_f32_e32 v31, v35, v3
	v_sub_f32_e32 v30, v34, v2
	v_lshl_add_u64 v[14:15], s[44:45], 0, v[18:19]
	v_lshl_add_u64 v[16:17], s[44:45], 0, v[22:23]
	v_lshl_add_u64 v[14:15], v[14:15], 0, v[104:105]
	v_lshl_add_u64 v[16:17], v[16:17], 0, v[104:105]
	v_lshl_add_u64 v[18:19], s[36:37], 0, v[18:19]
	v_lshl_add_u64 v[18:19], v[18:19], 0, v[104:105]
	v_mov_b32_e32 v10, v252
	v_mov_b32_e32 v11, v253
	v_mov_b32_e32 v12, v254
	v_mov_b32_e32 v13, v255
	v_lshlrev_b32_e32 v32, 16, v10
	v_and_b32_e32 v33, 0xffff0000, v10
	v_lshlrev_b32_e32 v10, 16, v11
	v_and_b32_e32 v11, 0xffff0000, v11
	v_lshlrev_b32_e32 v34, 16, v12
	v_and_b32_e32 v35, 0xffff0000, v12
	v_lshlrev_b32_e32 v12, 16, v13
	v_and_b32_e32 v13, 0xffff0000, v13
	v_pk_mul_f32 v[44:45], v[26:27], v[10:11]
	v_pk_mul_f32 v[10:11], v[24:25], v[32:33]
	v_pk_mul_f32 v[32:33], v[30:31], v[12:13]
	v_pk_mul_f32 v[12:13], v[28:29], v[34:35]
	v_cvt_pk_bf16_f32 v10, v10, v11
	v_cvt_pk_bf16_f32 v11, v44, v45
	v_cvt_pk_bf16_f32 v12, v12, v13
	v_cvt_pk_bf16_f32 v13, v32, v33
	global_store_dwordx4 v[20:21], v[10:13], off
	global_load_ushort v13, v[14:15], off
	s_nop 0
	global_load_ushort v32, v[16:17], off
	global_load_ushort v33, v[16:17], off offset:-14
	global_load_ushort v34, v[14:15], off offset:-14
	global_load_dwordx3 v[10:12], v[14:15], off offset:-12
	s_nop 0
	global_load_dwordx3 v[14:16], v[16:17], off offset:-12
	v_lshl_add_u64 v[20:21], s[36:37], 0, v[22:23]
	v_lshl_add_u64 v[20:21], v[20:21], 0, v[104:105]
	s_waitcnt vmcnt(5)
	v_lshlrev_b32_e32 v17, 16, v13
	s_waitcnt vmcnt(4)
	v_lshlrev_b32_e32 v44, 16, v32
	s_waitcnt vmcnt(3)
	v_lshlrev_b32_e32 v45, 16, v33
	s_waitcnt vmcnt(2)
	v_lshlrev_b32_e32 v46, 16, v34
	s_waitcnt vmcnt(1)
	v_lshlrev_b32_e32 v22, 16, v10
	v_and_b32_e32 v23, 0xffff0000, v10
	v_lshlrev_b32_e32 v10, 16, v11
	v_and_b32_e32 v11, 0xffff0000, v11
	v_lshlrev_b32_e32 v32, 16, v12
	v_and_b32_e32 v33, 0xffff0000, v12
	s_waitcnt vmcnt(0)
	v_lshlrev_b32_e32 v12, 16, v14
	v_and_b32_e32 v13, 0xffff0000, v14
	v_lshlrev_b32_e32 v34, 16, v16
	v_and_b32_e32 v35, 0xffff0000, v16
	v_mul_f32_e32 v16, v31, v46
	v_mov_b32_e32 v31, v29
	v_mov_b32_e32 v29, v27
	v_mov_b32_e32 v27, v25
	v_mul_f32_e32 v25, v43, v45
	v_mov_b32_e32 v43, v41
	v_lshlrev_b32_e32 v14, 16, v15
	v_and_b32_e32 v15, 0xffff0000, v15
	v_mul_f32_e32 v24, v24, v17
	v_mov_b32_e32 v41, v39
	v_mov_b32_e32 v39, v37
	v_mul_f32_e32 v36, v36, v44
	v_cvt_pk_bf16_f32 v37, v16, s0
	v_pk_mul_f32 v[16:17], v[30:31], v[22:23]
	v_pk_mul_f32 v[10:11], v[28:29], v[10:11]
	v_pk_mul_f32 v[12:13], v[42:43], v[12:13]
	v_pk_mul_f32 v[22:23], v[26:27], v[32:33]
	v_cvt_pk_bf16_f32 v26, v24, s0
	v_cvt_pk_bf16_f32 v27, v25, s0
	v_pk_mul_f32 v[14:15], v[40:41], v[14:15]
	v_pk_mul_f32 v[24:25], v[38:39], v[34:35]
	v_cvt_pk_bf16_f32 v28, v36, s0
	v_cvt_pk_bf16_f32 v16, v16, v17
	v_cvt_pk_bf16_f32 v10, v10, v11
	v_cvt_pk_bf16_f32 v17, v12, v13
	v_cvt_pk_bf16_f32 v11, v22, v23
	global_store_short v[18:19], v26, off
	v_cvt_pk_bf16_f32 v12, v14, v15
	v_cvt_pk_bf16_f32 v13, v24, v25
	global_store_short v[20:21], v28, off
	v_perm_b32 v14, v16, v37, s46
	global_store_short_d16_hi v[18:19], v16, off offset:-10
	global_store_dwordx2 v[18:19], v[10:11], off offset:-8
	v_perm_b32 v10, v17, v27, s46
	global_store_short_d16_hi v[20:21], v17, off offset:-10
	global_store_dwordx2 v[20:21], v[12:13], off offset:-8
	global_store_dword v[18:19], v14, off offset:-14
	global_store_dword v[20:21], v10, off offset:-14
	s_cbranch_execz .LBB0_742

; DI void st_bf16x8(bf16_t* p, f32x4 a, f32x4 b) { u32x4 w = {pk2(a[0], a[1]), pk2(a[2], a[3]), pk2(b[0], b[1]), pk2(b[2], b[3])}; *(u32x4*)p = w; }
; DI void ld_bf16x8(const bf16_t* p, f32x4& a, f32x4& b) { const u32x4 w = *(const u32x4*)p; a = (f32x4){bf_lo(w.x), bf_hi(w.x), bf_lo(w.y), bf_hi(w.y)}; b = (f32x4){bf_lo(w.z), bf_hi(w.z), bf_lo(w.w), bf_hi(w.w)}; }
; DI void fnet_layer(const Args& A, LAS unsigned char* lds, const XcdBarrier& gbar, int layer, int j, bool latonly, int wv) {
;     ...
;             const int k = u.i1 * 256 + row_l, col = (u.i2 & 7) * 256 + col_l;
;             bf16_t* ap = A1 + ((size_t)u.i0 * 1024 + k) * DM + col;
;             if (u.i2 < 8) { st_bf16x8(ap, v0, v1); return; }
;             f32x4 a0, a1; ld_bf16x8(ap, a0, a1);
;             const size_t off = ((size_t)u.i0 * TB + k) * DM + col;
;             f32x4 g0, g1; ld_bf16x8(Gt + off, g0, g1);
;             st_bf16x8(U + off, (a0 + v0) * g0, (a1 + v1) * g1);
;             if (k != 0) { const size_t off2 = ((size_t)u.i0 * TB + (TL - k)) * DM + col; ld_bf16x8(Gt + off2, g0, g1); st_bf16x8(U + off2, (a0 - v0) * g0, (a1 - v1) * g1); }
.LBB0_2483:
	s_lshl_b32 s5, s6, 8
	s_add_i32 s5, s5, s34
	v_mbcnt_lo_u32_b32 v128, -1, 0
	v_mbcnt_hi_u32_b32 v128, -1, v128
	s_mul_hi_i32 s41, s4, 0x900
	v_and_or_b32 v150, v128, 15, s5
	s_lshl_b32 s5, s7, 8
	s_and_b32 s61, s5, 0x700
	s_ashr_i32 s5, s4, 31
	s_lshl_b64 s[42:43], s[4:5], 22
	v_ashrrev_i32_e32 v151, 31, v150
	v_sub_u32_e32 v156, 0x800, v150
	s_cmp_gt_i32 s7, 7
	v_mad_i64_i32 v[130:131], s[6:7], s4, v188, v[150:151]
	v_ashrrev_i32_e32 v157, 31, v156
	s_mul_i32 s40, s4, 0x900
	v_lshlrev_b64 v[154:155], 11, v[130:131]
	v_mad_i64_i32 v[130:131], s[4:5], s4, v188, v[156:157]
	v_lshrrev_b32_e32 v132, 1, v128
	s_cselect_b64 s[46:47], -1, 0
	s_add_i32 s23, s61, 0x200
	v_readlane_b32 s4, v247, 46
	v_lshlrev_b64 v[128:129], 12, v[150:151]
	v_and_or_b32 v151, v132, 24, s35
	s_add_u32 s42, s4, s42
	v_readlane_b32 s4, v247, 47
	v_or_b32_e32 v189, s61, v151
	s_addc_u32 s43, s4, s43
	s_mov_b32 s98, s42
	s_lshl_b64 s[100:101], s[40:41], 12
	s_add_u32 s100, s100, s44
	s_addc_u32 s101, s101, s45
	v_lshl_add_u64 v[160:161], s[42:43], 0, v[128:129]
	v_lshlrev_b32_e32 v152, 1, v189
	v_mov_b32_e32 v153, v145
	v_cmp_ne_u32_e64 s[6:7], 0, v150
	v_lshlrev_b64 v[158:159], 11, v[130:131]
	v_lshl_add_u64 v[162:163], v[160:161], 0, v[152:153]
	s_mov_b64 s[4:5], -1
	s_and_b64 vcc, exec, s[46:47]
	s_cbranch_vccz .LBB0_2500
	v_or_b32_e32 v132, v154, v189
	v_mov_b32_e32 v133, v155
	v_lshlrev_b64 v[164:165], 1, v[132:133]
	v_subrev_u32_e32 v248, s98, v162
	v_and_b32_e32 v249, 0xfffff000, v248
	v_and_b32_e32 v250, 0xfff, v248
	v_sub_u32_e32 v251, v250, v249
	v_add_u32_e32 v251, 0x800000, v251
	global_load_dwordx4 v[252:255], v251, s[100:101]
	global_load_dwordx4 v[128:131], v[162:163], off
	v_lshl_add_u64 v[132:133], s[44:45], 0, v[164:165]
	global_load_dwordx4 v[132:135], v[132:133], off
	v_lshl_add_u64 v[180:181], s[36:37], 0, v[164:165]
	s_waitcnt vmcnt(0)
	v_lshlrev_b32_e32 v172, 16, v128
	v_and_b32_e32 v173, 0xffff0000, v128
	v_lshlrev_b32_e32 v128, 16, v129
	v_and_b32_e32 v129, 0xffff0000, v129
	v_lshlrev_b32_e32 v176, 16, v130
	v_and_b32_e32 v177, 0xffff0000, v130
	v_lshlrev_b32_e32 v130, 16, v131
	v_and_b32_e32 v131, 0xffff0000, v131
	v_pk_add_f32 v[166:167], v[126:127], v[128:129]
	v_pk_add_f32 v[164:165], v[124:125], v[172:173]
	v_pk_add_f32 v[170:171], v[122:123], v[130:131]
	v_pk_add_f32 v[168:169], v[120:121], v[176:177]
	v_sub_f32_e32 v175, v129, v127
	v_sub_f32_e32 v174, v128, v126
	v_sub_f32_e32 v179, v131, v123
	v_sub_f32_e32 v178, v130, v122
	v_lshlrev_b32_e32 v128, 16, v132
	v_and_b32_e32 v129, 0xffff0000, v132
	v_lshlrev_b32_e32 v130, 16, v133
	v_and_b32_e32 v131, 0xffff0000, v133
	v_lshlrev_b32_e32 v132, 16, v134
	v_and_b32_e32 v133, 0xffff0000, v134
	v_lshlrev_b32_e32 v134, 16, v135
	v_and_b32_e32 v135, 0xffff0000, v135
	v_pk_mul_f32 v[130:131], v[166:167], v[130:131]
	v_pk_mul_f32 v[128:129], v[164:165], v[128:129]
	v_pk_mul_f32 v[134:135], v[170:171], v[134:135]
	v_pk_mul_f32 v[132:133], v[168:169], v[132:133]
	v_sub_f32_e32 v173, v173, v125
	v_sub_f32_e32 v172, v172, v124
	v_sub_f32_e32 v177, v177, v121
	v_cvt_pk_bf16_f32 v128, v128, v129
	v_cvt_pk_bf16_f32 v129, v130, v131
	v_cvt_pk_bf16_f32 v130, v132, v133
	v_cvt_pk_bf16_f32 v131, v134, v135
	v_sub_f32_e32 v176, v176, v120
	global_store_dwordx4 v[180:181], v[128:131], off
	s_and_saveexec_b64 s[4:5], s[6:7]
	s_xor_b64 s[4:5], exec, s[4:5]
	s_cbranch_execz .LBB0_2486
	v_or_b32_e32 v128, v158, v189
	v_mov_b32_e32 v129, v159
	v_lshlrev_b64 v[132:133], 1, v[128:129]
	v_lshl_add_u64 v[128:129], s[44:45], 0, v[132:133]
	v_lshl_add_u64 v[132:133], s[36:37], 0, v[132:133]
	v_mov_b32_e32 v128, v252
	v_mov_b32_e32 v129, v253
	v_mov_b32_e32 v130, v254
	v_mov_b32_e32 v131, v255
	v_lshlrev_b32_e32 v134, 16, v128
	v_and_b32_e32 v135, 0xffff0000, v128
	v_lshlrev_b32_e32 v128, 16, v129
	v_and_b32_e32 v129, 0xffff0000, v129
	v_lshlrev_b32_e32 v180, 16, v130
	v_and_b32_e32 v181, 0xffff0000, v130
	v_lshlrev_b32_e32 v130, 16, v131
	v_and_b32_e32 v131, 0xffff0000, v131
	v_pk_mul_f32 v[182:183], v[174:175], v[128:129]
	v_pk_mul_f32 v[128:129], v[172:173], v[134:135]
	v_pk_mul_f32 v[134:135], v[178:179], v[130:131]
	v_pk_mul_f32 v[130:131], v[176:177], v[180:181]
	v_cvt_pk_bf16_f32 v128, v128, v129
	v_cvt_pk_bf16_f32 v129, v182, v183
	v_cvt_pk_bf16_f32 v130, v130, v131
	v_cvt_pk_bf16_f32 v131, v134, v135
	global_store_dwordx4 v[132:133], v[128:131], off

; DI void st_bf16x8(bf16_t* p, f32x4 a, f32x4 b) { u32x4 w = {pk2(a[0], a[1]), pk2(a[2], a[3]), pk2(b[0], b[1]), pk2(b[2], b[3])}; *(u32x4*)p = w; }
; DI void ld_bf16x8(const bf16_t* p, f32x4& a, f32x4& b) { const u32x4 w = *(const u32x4*)p; a = (f32x4){bf_lo(w.x), bf_hi(w.x), bf_lo(w.y), bf_hi(w.y)}; b = (f32x4){bf_lo(w.z), bf_hi(w.z), bf_lo(w.w), bf_hi(w.w)}; }
; DI void fnet_layer(const Args& A, LAS unsigned char* lds, const XcdBarrier& gbar, int layer, int j, bool latonly, int wv) {
;     ...
;             bf16_t* ap = A1 + ((size_t)u.i0 * 1024 + k) * DM + col;
;             if (u.i2 < 8) { st_bf16x8(ap, v0, v1); return; }
;             f32x4 a0, a1; ld_bf16x8(ap, a0, a1);
;             const size_t off = ((size_t)u.i0 * TB + k) * DM + col;
;             f32x4 g0, g1; ld_bf16x8(Gt + off, g0, g1);
;             st_bf16x8(U + off, (a0 + v0) * g0, (a1 + v1) * g1);
;             if (k != 0) { const size_t off2 = ((size_t)u.i0 * TB + (TL - k)) * DM + col; ld_bf16x8(Gt + off2, g0, g1); st_bf16x8(U + off2, (a0 - v0) * g0, (a1 - v1) * g1); }
.LBB0_2502:
	v_add_u32_e32 v120, s61, v151
	v_or_b32_e32 v173, 0x80, v151
	v_lshlrev_b32_e32 v128, 1, v120
	v_mov_b32_e32 v129, v145
	v_cndmask_b32_e64 v120, 0, 1, s[46:47]
	v_or_b32_e32 v172, s61, v173
	v_lshl_add_u64 v[130:131], v[160:161], 0, v[128:129]
	v_cmp_ne_u32_e64 s[4:5], 1, v120
	s_andn2_b64 vcc, exec, s[46:47]
	s_mov_b64 s[46:47], -1
	s_cbranch_vccnz .LBB0_2512
	v_or_b32_e32 v124, v154, v172
	v_mov_b32_e32 v125, v155
	v_lshlrev_b64 v[132:133], 1, v[124:125]
	v_subrev_u32_e32 v248, s98, v130
	v_add_u32_e32 v248, 256, v248
	v_and_b32_e32 v249, 0xfffff000, v248
	v_and_b32_e32 v250, 0xfff, v248
	v_sub_u32_e32 v251, v250, v249
	v_add_u32_e32 v251, 0x800000, v251
	global_load_dwordx4 v[252:255], v251, s[100:101]
	global_load_dwordx4 v[120:123], v[130:131], off offset:256
	v_lshl_add_u64 v[124:125], s[44:45], 0, v[132:133]
	global_load_dwordx4 v[124:127], v[124:125], off
	v_lshl_add_u64 v[174:175], s[36:37], 0, v[132:133]
	s_waitcnt vmcnt(0)
	v_lshlrev_b32_e32 v164, 16, v120
	v_and_b32_e32 v165, 0xffff0000, v120
	v_lshlrev_b32_e32 v120, 16, v121
	v_and_b32_e32 v121, 0xffff0000, v121
	v_lshlrev_b32_e32 v168, 16, v122
	v_and_b32_e32 v169, 0xffff0000, v122
	v_lshlrev_b32_e32 v122, 16, v123
	v_and_b32_e32 v123, 0xffff0000, v123
	v_pk_add_f32 v[134:135], v[118:119], v[120:121]
	v_pk_add_f32 v[132:133], v[116:117], v[164:165]
	v_pk_add_f32 v[162:163], v[114:115], v[122:123]
	v_pk_add_f32 v[160:161], v[112:113], v[168:169]
	v_sub_f32_e32 v167, v121, v119
	v_sub_f32_e32 v166, v120, v118
	v_sub_f32_e32 v171, v123, v115
	v_sub_f32_e32 v170, v122, v114
	v_lshlrev_b32_e32 v120, 16, v124
	v_and_b32_e32 v121, 0xffff0000, v124
	v_lshlrev_b32_e32 v122, 16, v125
	v_and_b32_e32 v123, 0xffff0000, v125
	v_lshlrev_b32_e32 v124, 16, v126
	v_and_b32_e32 v125, 0xffff0000, v126
	v_lshlrev_b32_e32 v126, 16, v127
	v_and_b32_e32 v127, 0xffff0000, v127
	v_pk_mul_f32 v[122:123], v[134:135], v[122:123]
	v_pk_mul_f32 v[120:121], v[132:133], v[120:121]
	v_pk_mul_f32 v[126:127], v[162:163], v[126:127]
	v_pk_mul_f32 v[124:125], v[160:161], v[124:125]
	v_sub_f32_e32 v165, v165, v117
	v_sub_f32_e32 v164, v164, v116
	v_sub_f32_e32 v169, v169, v113
	v_cvt_pk_bf16_f32 v120, v120, v121
	v_cvt_pk_bf16_f32 v121, v122, v123
	v_cvt_pk_bf16_f32 v122, v124, v125
	v_cvt_pk_bf16_f32 v123, v126, v127
	v_sub_f32_e32 v168, v168, v112
	global_store_dwordx4 v[174:175], v[120:123], off
	s_and_saveexec_b64 s[46:47], s[6:7]
	s_xor_b64 s[46:47], exec, s[46:47]
	s_cbranch_execz .LBB0_2505
	v_or_b32_e32 v158, v158, v172
	v_lshlrev_b64 v[124:125], 1, v[158:159]
	v_lshl_add_u64 v[120:121], s[44:45], 0, v[124:125]
	v_lshl_add_u64 v[124:125], s[36:37], 0, v[124:125]
	v_mov_b32_e32 v120, v252
	v_mov_b32_e32 v121, v253
	v_mov_b32_e32 v122, v254
	v_mov_b32_e32 v123, v255
	v_lshlrev_b32_e32 v126, 16, v120
	v_and_b32_e32 v127, 0xffff0000, v120
	v_lshlrev_b32_e32 v120, 16, v121
	v_and_b32_e32 v121, 0xffff0000, v121
	v_lshlrev_b32_e32 v158, 16, v122
	v_and_b32_e32 v159, 0xffff0000, v122
	v_lshlrev_b32_e32 v122, 16, v123
	v_and_b32_e32 v123, 0xffff0000, v123
	v_pk_mul_f32 v[174:175], v[166:167], v[120:121]
	v_pk_mul_f32 v[120:121], v[164:165], v[126:127]
	v_pk_mul_f32 v[126:127], v[170:171], v[122:123]
	v_pk_mul_f32 v[122:123], v[168:169], v[158:159]
	v_cvt_pk_bf16_f32 v120, v120, v121
	v_cvt_pk_bf16_f32 v121, v174, v175
	v_cvt_pk_bf16_f32 v122, v122, v123
	v_cvt_pk_bf16_f32 v123, v126, v127
	global_store_dwordx4 v[124:125], v[120:123], off

; DI unsigned pk2(float a, float b) { f32x2 v = {a, b}; return __builtin_bit_cast(unsigned, __builtin_convertvector(v, bf16v2)); }
; DI float bf_lo(unsigned w) { return __uint_as_float(w << 16); }
; DI void fnet_layer(const Args& A, LAS unsigned char* lds, const XcdBarrier& gbar, int layer, int j, bool latonly, int wv) {
;     ...
;             bf16_t* ap = A1 + ((size_t)u.i0 * 1024 + k) * DM + col;
;             if (u.i2 < 8) { st_bf16x8(ap, v0, v1); return; }
;             f32x4 a0, a1; ld_bf16x8(ap, a0, a1);
;             const size_t off = ((size_t)u.i0 * TB + k) * DM + col;
;             f32x4 g0, g1; ld_bf16x8(Gt + off, g0, g1);
;             st_bf16x8(U + off, (a0 + v0) * g0, (a1 + v1) * g1);
;             if (k != 0) { const size_t off2 = ((size_t)u.i0 * TB + (TL - k)) * DM + col; ld_bf16x8(Gt + off2, g0, g1); st_bf16x8(U + off2, (a0 - v0) * g0, (a1 - v1) * g1); }
;             const f32x4 s0 = a0 + v0, s1 = a1 + v1, d0 = a0 - v0, d1 = a1 - v1;
;             const float sm[8] = {s0[0], s0[1], s0[2], s0[3], s1[0], s1[1], s1[2], s1[3]}, df[8] = {d0[0], d0[1], d0[2], d0[3], d1[0], d1[1], d1[2], d1[3]};
;             const size_t rowk = ((size_t)u.i0 * TB + k) * DM, rowT = ((size_t)u.i0 * TB + (TL - k)) * DM; const int cm = (col & ~255) + 512 - col_l;
;             {
;                 const bf16_t* gk_ = Gt + rowk + cm - 8; const bf16_t* gT_ = Gt + rowT + cm - 8; bf16_t* uk_ = U + rowk + cm - 8; bf16_t* uT_ = U + rowT + cm - 8;
;                 const unsigned short ka1 = gk_[1]; const unsigned ka2 = *(const unsigned*)(gk_ + 2); const u32x2 ka4 = *(const u32x2*)(gk_ + 4); const unsigned short ka0 = col_l ? gk_[8] : (unsigned short)0;
;                 unsigned short ta1 = 0, ta0 = 0; unsigned ta2 = 0; u32x2 ta4 = {0u, 0u};
;                 if (k != 0) { ta1 = gT_[1]; ta2 = *(const unsigned*)(gT_ + 2); ta4 = *(const u32x2*)(gT_ + 4); ta0 = col_l ? gT_[8] : (unsigned short)0; }
;                 uk_[1] = (bf16_t)(pk2(df[7] * __uint_as_float((unsigned)ka1 << 16), 0.f) & 0xffffu);
;                 *(unsigned*)(uk_ + 2) = pk2(df[6] * bf_lo(ka2), df[5] * bf_hi(ka2));
;                 *(u32x2*)(uk_ + 4) = (u32x2){pk2(df[4] * bf_lo(ka4.x), df[3] * bf_hi(ka4.x)), pk2(df[2] * bf_lo(ka4.y), df[1] * bf_hi(ka4.y))};
;                 if (col_l) uk_[8] = (bf16_t)(pk2(df[0] * __uint_as_float((unsigned)ka0 << 16), 0.f) & 0xffffu);
.LBB0_2514:
	v_or_b32_e32 v112, 16, v150
	v_ashrrev_i32_e32 v113, 31, v112
	v_lshlrev_b64 v[114:115], 12, v[112:113]
	v_lshl_add_u64 v[116:117], s[40:41], 0, v[112:113]
	v_sub_u32_e32 v112, 0x800, v112
	v_ashrrev_i32_e32 v113, 31, v112
	v_lshl_add_u64 v[112:113], s[40:41], 0, v[112:113]
	v_lshlrev_b64 v[122:123], 11, v[112:113]
	v_lshl_add_u64 v[124:125], s[42:43], 0, v[114:115]
	v_mov_b32_e32 v153, v145
	v_sub_u32_e32 v112, s23, v151
	v_lshlrev_b64 v[120:121], 11, v[116:117]
	v_lshl_add_u64 v[126:127], v[124:125], 0, v[152:153]
	s_mov_b64 s[46:47], -1
	s_and_b64 vcc, exec, s[4:5]
	v_cmp_ne_u32_e64 s[6:7], 0, v151
	v_lshlrev_b32_e32 v144, 1, v112
	s_cbranch_vccnz .LBB0_2524
	v_or_b32_e32 v116, v120, v189
	v_mov_b32_e32 v117, v121
	v_lshlrev_b64 v[130:131], 1, v[116:117]
	v_subrev_u32_e32 v248, s98, v126
	v_and_b32_e32 v249, 0xfffff000, v248
	v_and_b32_e32 v250, 0xfff, v248
	v_sub_u32_e32 v251, v250, v249
	v_add_u32_e32 v251, 0x800000, v251
	global_load_dwordx4 v[252:255], v251, s[100:101]
	global_load_dwordx4 v[112:115], v[126:127], off
	v_lshl_add_u64 v[116:117], s[44:45], 0, v[130:131]
	global_load_dwordx4 v[116:119], v[116:117], off
	v_or_b32_e32 v132, v122, v189
	v_mov_b32_e32 v133, v123
	v_lshlrev_b64 v[156:157], 1, v[132:133]
	v_lshl_add_u64 v[158:159], s[36:37], 0, v[130:131]
	v_lshl_add_u64 v[160:161], s[44:45], 0, v[156:157]
	v_lshl_add_u64 v[170:171], s[36:37], 0, v[156:157]
	v_mov_b32_e32 v129, 0
	s_waitcnt vmcnt(0)
	v_lshlrev_b32_e32 v162, 16, v112
	v_and_b32_e32 v163, 0xffff0000, v112
	v_lshlrev_b32_e32 v164, 16, v113
	v_and_b32_e32 v165, 0xffff0000, v113
	v_lshlrev_b32_e32 v166, 16, v114
	v_and_b32_e32 v167, 0xffff0000, v114
	v_lshlrev_b32_e32 v168, 16, v115
	v_and_b32_e32 v169, 0xffff0000, v115
	v_pk_add_f32 v[132:133], v[110:111], v[164:165]
	v_pk_add_f32 v[130:131], v[108:109], v[162:163]
	v_pk_add_f32 v[154:155], v[106:107], v[168:169]
	v_pk_add_f32 v[134:135], v[104:105], v[166:167]
	v_lshlrev_b32_e32 v112, 16, v116
	v_and_b32_e32 v113, 0xffff0000, v116
	v_lshlrev_b32_e32 v114, 16, v117
	v_and_b32_e32 v115, 0xffff0000, v117
	v_lshlrev_b32_e32 v116, 16, v118
	v_and_b32_e32 v117, 0xffff0000, v118
	v_lshlrev_b32_e32 v118, 16, v119
	v_and_b32_e32 v119, 0xffff0000, v119
	v_pk_mul_f32 v[114:115], v[132:133], v[114:115]
	v_pk_mul_f32 v[112:113], v[130:131], v[112:113]
	v_pk_mul_f32 v[118:119], v[154:155], v[118:119]
	v_pk_mul_f32 v[116:117], v[134:135], v[116:117]
	v_cvt_pk_bf16_f32 v112, v112, v113
	v_cvt_pk_bf16_f32 v113, v114, v115
	v_cvt_pk_bf16_f32 v114, v116, v117
	v_cvt_pk_bf16_f32 v115, v118, v119
	global_store_dwordx4 v[158:159], v[112:115], off
	v_sub_f32_e32 v158, v164, v110
	v_sub_f32_e32 v161, v165, v111
	v_sub_f32_e32 v156, v162, v108
	v_sub_f32_e32 v115, v169, v107
	v_sub_f32_e32 v162, v168, v106
	v_mov_b32_e32 v160, v158
	v_sub_f32_e32 v159, v163, v109
	v_sub_f32_e32 v163, v167, v105
	v_mov_b32_e32 v157, v159
	v_mov_b32_e32 v114, v162
	v_mov_b32_e32 v165, v163
	v_lshl_add_u64 v[112:113], v[120:121], 1, s[44:45]
	v_lshl_add_u64 v[112:113], v[112:113], 0, v[144:145]
	v_mov_b32_e32 v116, v252
	v_mov_b32_e32 v117, v253
	v_mov_b32_e32 v118, v254
	v_mov_b32_e32 v119, v255
	v_lshlrev_b32_e32 v168, 16, v116
	v_and_b32_e32 v169, 0xffff0000, v116
	v_lshlrev_b32_e32 v116, 16, v117
	v_and_b32_e32 v117, 0xffff0000, v117
	v_pk_mul_f32 v[176:177], v[160:161], v[116:117]
	v_sub_f32_e32 v160, v166, v104
	v_lshlrev_b32_e32 v174, 16, v118
	v_and_b32_e32 v175, 0xffff0000, v118
	v_lshlrev_b32_e32 v118, 16, v119
	v_and_b32_e32 v119, 0xffff0000, v119
	v_mov_b32_e32 v164, v160
	v_pk_mul_f32 v[116:117], v[156:157], v[168:169]
	v_pk_mul_f32 v[118:119], v[114:115], v[118:119]
	v_pk_mul_f32 v[164:165], v[164:165], v[174:175]
	v_cvt_pk_bf16_f32 v116, v116, v117
	v_cvt_pk_bf16_f32 v117, v176, v177
	v_cvt_pk_bf16_f32 v119, v118, v119
	v_cvt_pk_bf16_f32 v118, v164, v165
	global_store_dwordx4 v[170:171], v[116:119], off
	global_load_ushort v157, v[112:113], off offset:-14
	s_nop 0
	global_load_dwordx3 v[116:118], v[112:113], off offset:-12
	v_mov_b32_e32 v119, 0
	s_and_saveexec_b64 s[46:47], s[6:7]
	s_cbranch_execz .LBB0_2517
	global_load_ushort v112, v[112:113], off
	s_waitcnt vmcnt(0)
	v_lshlrev_b32_e32 v129, 16, v112

; DI void fnet_layer(const Args& A, LAS unsigned char* lds, const XcdBarrier& gbar, int layer, int j, bool latonly, int wv) {
;     ...
;             bf16_t* ap = A1 + ((size_t)u.i0 * 1024 + k) * DM + col;
;             if (u.i2 < 8) { st_bf16x8(ap, v0, v1); return; }
;             f32x4 a0, a1; ld_bf16x8(ap, a0, a1);
;             const size_t off = ((size_t)u.i0 * TB + k) * DM + col;
;             f32x4 g0, g1; ld_bf16x8(Gt + off, g0, g1);
;             st_bf16x8(U + off, (a0 + v0) * g0, (a1 + v1) * g1);
;             if (k != 0) { const size_t off2 = ((size_t)u.i0 * TB + (TL - k)) * DM + col; ld_bf16x8(Gt + off2, g0, g1); st_bf16x8(U + off2, (a0 - v0) * g0, (a1 - v1) * g1); }
;             const f32x4 s0 = a0 + v0, s1 = a1 + v1, d0 = a0 - v0, d1 = a1 - v1;
;             const float sm[8] = {s0[0], s0[1], s0[2], s0[3], s1[0], s1[1], s1[2], s1[3]}, df[8] = {d0[0], d0[1], d0[2], d0[3], d1[0], d1[1], d1[2], d1[3]};
;             const size_t rowk = ((size_t)u.i0 * TB + k) * DM, rowT = ((size_t)u.i0 * TB + (TL - k)) * DM; const int cm = (col & ~255) + 512 - col_l;
;             {
;                 const bf16_t* gk_ = Gt + rowk + cm - 8; const bf16_t* gT_ = Gt + rowT + cm - 8; bf16_t* uk_ = U + rowk + cm - 8; bf16_t* uT_ = U + rowT + cm - 8;
;                 const unsigned short ka1 = gk_[1]; const unsigned ka2 = *(const unsigned*)(gk_ + 2); const u32x2 ka4 = *(const u32x2*)(gk_ + 4); const unsigned short ka0 = col_l ? gk_[8] : (unsigned short)0;
;                 unsigned short ta1 = 0, ta0 = 0; unsigned ta2 = 0; u32x2 ta4 = {0u, 0u};
;                 if (k != 0) { ta1 = gT_[1]; ta2 = *(const unsigned*)(gT_ + 2); ta4 = *(const u32x2*)(gT_ + 4); ta0 = col_l ? gT_[8] : (unsigned short)0; }
;                 uk_[1] = (bf16_t)(pk2(df[7] * __uint_as_float((unsigned)ka1 << 16), 0.f) & 0xffffu);
;                 *(unsigned*)(uk_ + 2) = pk2(df[6] * bf_lo(ka2), df[5] * bf_hi(ka2));
;                 *(u32x2*)(uk_ + 4) = (u32x2){pk2(df[4] * bf_lo(ka4.x), df[3] * bf_hi(ka4.x)), pk2(df[2] * bf_lo(ka4.y), df[1] * bf_hi(ka4.y))};
;                 if (col_l) uk_[8] = (bf16_t)(pk2(df[0] * __uint_as_float((unsigned)ka0 << 16), 0.f) & 0xffffu);
;                 if (k != 0) {
;                     uT_[1] = (bf16_t)(pk2(sm[7] * __uint_as_float((unsigned)ta1 << 16), 0.f) & 0xffffu);
;                     *(unsigned*)(uT_ + 2) = pk2(sm[6] * bf_lo(ta2), sm[5] * bf_hi(ta2));
.LBB0_2526:
	v_mov_b32_e32 v129, v145
	v_sub_u32_e32 v104, s23, v173
	v_lshl_add_u64 v[106:107], v[124:125], 0, v[128:129]
	s_mov_b64 s[6:7], -1
	s_and_b64 vcc, exec, s[4:5]
	v_lshlrev_b32_e32 v104, 1, v104
	s_cbranch_vccnz .LBB0_2528
	v_or_b32_e32 v112, v120, v172
	v_mov_b32_e32 v113, v121
	v_lshlrev_b64 v[116:117], 1, v[112:113]
	v_subrev_u32_e32 v248, s98, v106
	v_add_u32_e32 v248, 256, v248
	v_and_b32_e32 v249, 0xfffff000, v248
	v_and_b32_e32 v250, 0xfff, v248
	v_sub_u32_e32 v251, v250, v249
	v_add_u32_e32 v251, 0x800000, v251
	global_load_dwordx4 v[252:255], v251, s[100:101]
	global_load_dwordx4 v[108:111], v[106:107], off offset:256
	v_lshl_add_u64 v[112:113], s[44:45], 0, v[116:117]
	global_load_dwordx4 v[112:115], v[112:113], off
	v_or_b32_e32 v118, v122, v172
	v_mov_b32_e32 v119, v123
	v_lshlrev_b64 v[118:119], 1, v[118:119]
	v_lshl_add_u64 v[116:117], s[36:37], 0, v[116:117]
	v_lshl_add_u64 v[124:125], s[44:45], 0, v[118:119]
	v_mov_b32_e32 v105, v145
	v_lshl_add_u64 v[118:119], s[36:37], 0, v[118:119]
	s_mov_b64 s[6:7], 0
	s_waitcnt vmcnt(0)
	v_lshlrev_b32_e32 v126, 16, v108
	v_and_b32_e32 v127, 0xffff0000, v108
	v_lshlrev_b32_e32 v130, 16, v109
	v_and_b32_e32 v131, 0xffff0000, v109
	v_lshlrev_b32_e32 v132, 16, v110
	v_and_b32_e32 v133, 0xffff0000, v110
	v_lshlrev_b32_e32 v134, 16, v111
	v_and_b32_e32 v135, 0xffff0000, v111
	v_pk_add_f32 v[154:155], v[100:101], v[126:127]
	v_pk_add_f32 v[156:157], v[102:103], v[130:131]
	v_pk_add_f32 v[158:159], v[96:97], v[132:133]
	v_pk_add_f32 v[160:161], v[98:99], v[134:135]
	v_lshlrev_b32_e32 v108, 16, v112
	v_and_b32_e32 v109, 0xffff0000, v112
	v_lshlrev_b32_e32 v110, 16, v113
	v_and_b32_e32 v111, 0xffff0000, v113
	v_lshlrev_b32_e32 v112, 16, v114
	v_and_b32_e32 v113, 0xffff0000, v114
	v_lshlrev_b32_e32 v114, 16, v115
	v_and_b32_e32 v115, 0xffff0000, v115
	v_pk_mul_f32 v[110:111], v[156:157], v[110:111]
	v_pk_mul_f32 v[108:109], v[154:155], v[108:109]
	v_pk_mul_f32 v[114:115], v[160:161], v[114:115]
	v_pk_mul_f32 v[112:113], v[158:159], v[112:113]
	v_cvt_pk_bf16_f32 v108, v108, v109
	v_cvt_pk_bf16_f32 v109, v110, v111
	v_cvt_pk_bf16_f32 v110, v112, v113
	v_cvt_pk_bf16_f32 v111, v114, v115
	global_store_dwordx4 v[116:117], v[108:111], off
	v_lshlrev_b64 v[116:117], 1, v[120:121]
	v_lshlrev_b64 v[120:121], 1, v[122:123]
	v_sub_f32_e32 v123, v127, v101
	v_sub_f32_e32 v122, v126, v100
	v_sub_f32_e32 v125, v131, v103
	v_sub_f32_e32 v124, v130, v102
	v_sub_f32_e32 v127, v133, v97
	v_sub_f32_e32 v126, v132, v96
	v_sub_f32_e32 v131, v135, v99
	v_sub_f32_e32 v130, v134, v98
	v_lshl_add_u64 v[112:113], s[44:45], 0, v[116:117]
	v_lshl_add_u64 v[114:115], s[44:45], 0, v[120:121]
	v_lshl_add_u64 v[112:113], v[112:113], 0, v[104:105]
	v_lshl_add_u64 v[114:115], v[114:115], 0, v[104:105]
	v_lshl_add_u64 v[116:117], s[36:37], 0, v[116:117]
	v_lshl_add_u64 v[116:117], v[116:117], 0, v[104:105]
	v_mov_b32_e32 v108, v252
	v_mov_b32_e32 v109, v253
	v_mov_b32_e32 v110, v254
	v_mov_b32_e32 v111, v255
	v_lshlrev_b32_e32 v132, 16, v108
	v_and_b32_e32 v133, 0xffff0000, v108
	v_lshlrev_b32_e32 v108, 16, v109
	v_and_b32_e32 v109, 0xffff0000, v109
	v_lshlrev_b32_e32 v134, 16, v110
	v_and_b32_e32 v135, 0xffff0000, v110
	v_lshlrev_b32_e32 v110, 16, v111
	v_and_b32_e32 v111, 0xffff0000, v111
	v_pk_mul_f32 v[162:163], v[124:125], v[108:109]
	v_pk_mul_f32 v[108:109], v[122:123], v[132:133]
	v_pk_mul_f32 v[132:133], v[130:131], v[110:111]
	v_pk_mul_f32 v[110:111], v[126:127], v[134:135]
	v_cvt_pk_bf16_f32 v108, v108, v109
	v_cvt_pk_bf16_f32 v109, v162, v163
	v_cvt_pk_bf16_f32 v110, v110, v111
	v_cvt_pk_bf16_f32 v111, v132, v133
	global_store_dwordx4 v[118:119], v[108:111], off
	global_load_ushort v111, v[112:113], off
	s_nop 0
	global_load_ushort v129, v[114:115], off
	global_load_ushort v132, v[114:115], off offset:-14
	global_load_ushort v133, v[112:113], off offset:-14
	global_load_dwordx3 v[108:110], v[112:113], off offset:-12
	s_nop 0
	global_load_dwordx3 v[112:114], v[114:115], off offset:-12
	v_lshl_add_u64 v[118:119], s[36:37], 0, v[120:121]
	v_lshl_add_u64 v[118:119], v[118:119], 0, v[104:105]
	s_waitcnt vmcnt(5)
	v_lshlrev_b32_e32 v105, 16, v111
	s_waitcnt vmcnt(4)
	v_lshlrev_b32_e32 v115, 16, v129
	s_waitcnt vmcnt(3)
	v_lshlrev_b32_e32 v129, 16, v132
	s_waitcnt vmcnt(2)
	v_lshlrev_b32_e32 v153, 16, v133
	s_waitcnt vmcnt(1)
	v_lshlrev_b32_e32 v120, 16, v108
	v_and_b32_e32 v121, 0xffff0000, v108
	v_lshlrev_b32_e32 v108, 16, v109
	v_and_b32_e32 v109, 0xffff0000, v109
	v_lshlrev_b32_e32 v132, 16, v110
	v_and_b32_e32 v133, 0xffff0000, v110
	s_waitcnt vmcnt(0)
	v_lshlrev_b32_e32 v110, 16, v112
	v_and_b32_e32 v111, 0xffff0000, v112
	v_lshlrev_b32_e32 v112, 16, v113
	v_and_b32_e32 v113, 0xffff0000, v113
	v_lshlrev_b32_e32 v134, 16, v114
	v_and_b32_e32 v135, 0xffff0000, v114
	v_mul_f32_e32 v114, v131, v153
	v_mov_b32_e32 v131, v127
	v_mov_b32_e32 v127, v125
	v_mov_b32_e32 v125, v123
	v_mul_f32_e32 v105, v122, v105
	v_mul_f32_e32 v122, v161, v129
	v_mov_b32_e32 v161, v159
	v_mov_b32_e32 v159, v157
	v_mov_b32_e32 v157, v155
	v_mul_f32_e32 v129, v154, v115
	v_cvt_pk_bf16_f32 v153, v114, s0
	v_pk_mul_f32 v[114:115], v[130:131], v[120:121]
	v_pk_mul_f32 v[108:109], v[126:127], v[108:109]
	v_pk_mul_f32 v[120:121], v[124:125], v[132:133]
	v_cvt_pk_bf16_f32 v105, v105, s0
	v_cvt_pk_bf16_f32 v124, v122, s0
	v_pk_mul_f32 v[110:111], v[160:161], v[110:111]
	v_pk_mul_f32 v[112:113], v[158:159], v[112:113]
	v_pk_mul_f32 v[122:123], v[156:157], v[134:135]
	v_cvt_pk_bf16_f32 v125, v129, s0
	v_cvt_pk_bf16_f32 v114, v114, v115
	v_cvt_pk_bf16_f32 v108, v108, v109
	global_store_short v[116:117], v105, off
	v_cvt_pk_bf16_f32 v105, v110, v111
	v_cvt_pk_bf16_f32 v110, v112, v113
	v_cvt_pk_bf16_f32 v111, v122, v123
	v_cvt_pk_bf16_f32 v109, v120, v121
	global_store_short v[118:119], v125, off
	v_perm_b32 v112, v114, v153, s60
	global_store_short_d16_hi v[116:117], v114, off offset:-10
	global_store_dwordx2 v[116:117], v[108:109], off offset:-8
	v_perm_b32 v108, v105, v124, s60
	global_store_dwordx2 v[118:119], v[110:111], off offset:-8
	global_store_dword v[116:117], v112, off offset:-14
	global_store_short_d16_hi v[118:119], v105, off offset:-10
	global_store_dword v[118:119], v108, off offset:-14

; DI unsigned pk2(float a, float b) { f32x2 v = {a, b}; return __builtin_bit_cast(unsigned, __builtin_convertvector(v, bf16v2)); }
; DI float bf_lo(unsigned w) { return __uint_as_float(w << 16); }
; DI void fnet_layer(const Args& A, LAS unsigned char* lds, const XcdBarrier& gbar, int layer, int j, bool latonly, int wv) {
;     ...
;             bf16_t* ap = A1 + ((size_t)u.i0 * 1024 + k) * DM + col;
;             if (u.i2 < 8) { st_bf16x8(ap, v0, v1); return; }
;             f32x4 a0, a1; ld_bf16x8(ap, a0, a1);
;             const size_t off = ((size_t)u.i0 * TB + k) * DM + col;
;             f32x4 g0, g1; ld_bf16x8(Gt + off, g0, g1);
;             st_bf16x8(U + off, (a0 + v0) * g0, (a1 + v1) * g1);
;             if (k != 0) { const size_t off2 = ((size_t)u.i0 * TB + (TL - k)) * DM + col; ld_bf16x8(Gt + off2, g0, g1); st_bf16x8(U + off2, (a0 - v0) * g0, (a1 - v1) * g1); }
;             const f32x4 s0 = a0 + v0, s1 = a1 + v1, d0 = a0 - v0, d1 = a1 - v1;
;             const float sm[8] = {s0[0], s0[1], s0[2], s0[3], s1[0], s1[1], s1[2], s1[3]}, df[8] = {d0[0], d0[1], d0[2], d0[3], d1[0], d1[1], d1[2], d1[3]};
;             const size_t rowk = ((size_t)u.i0 * TB + k) * DM, rowT = ((size_t)u.i0 * TB + (TL - k)) * DM; const int cm = (col & ~255) + 512 - col_l;
;             {
;                 const bf16_t* gk_ = Gt + rowk + cm - 8; const bf16_t* gT_ = Gt + rowT + cm - 8; bf16_t* uk_ = U + rowk + cm - 8; bf16_t* uT_ = U + rowT + cm - 8;
;                 const unsigned short ka1 = gk_[1]; const unsigned ka2 = *(const unsigned*)(gk_ + 2); const u32x2 ka4 = *(const u32x2*)(gk_ + 4); const unsigned short ka0 = col_l ? gk_[8] : (unsigned short)0;
;                 unsigned short ta1 = 0, ta0 = 0; unsigned ta2 = 0; u32x2 ta4 = {0u, 0u};
;                 if (k != 0) { ta1 = gT_[1]; ta2 = *(const unsigned*)(gT_ + 2); ta4 = *(const u32x2*)(gT_ + 4); ta0 = col_l ? gT_[8] : (unsigned short)0; }
;                 uk_[1] = (bf16_t)(pk2(df[7] * __uint_as_float((unsigned)ka1 << 16), 0.f) & 0xffffu);
;                 *(unsigned*)(uk_ + 2) = pk2(df[6] * bf_lo(ka2), df[5] * bf_hi(ka2));
;                 *(u32x2*)(uk_ + 4) = (u32x2){pk2(df[4] * bf_lo(ka4.x), df[3] * bf_hi(ka4.x)), pk2(df[2] * bf_lo(ka4.y), df[1] * bf_hi(ka4.y))};
;                 if (col_l) uk_[8] = (bf16_t)(pk2(df[0] * __uint_as_float((unsigned)ka0 << 16), 0.f) & 0xffffu);
.LBB0_2530:
	v_or_b32_e32 v96, 32, v150
	v_ashrrev_i32_e32 v97, 31, v96
	v_lshlrev_b64 v[98:99], 12, v[96:97]
	v_lshl_add_u64 v[100:101], s[40:41], 0, v[96:97]
	v_sub_u32_e32 v96, 0x800, v96
	v_ashrrev_i32_e32 v97, 31, v96
	v_lshl_add_u64 v[96:97], s[40:41], 0, v[96:97]
	v_lshl_add_u64 v[110:111], s[42:43], 0, v[98:99]
	v_mov_b32_e32 v153, v145
	v_lshlrev_b64 v[106:107], 11, v[100:101]
	v_lshlrev_b64 v[108:109], 11, v[96:97]
	v_lshl_add_u64 v[112:113], v[110:111], 0, v[152:153]
	s_and_b64 vcc, exec, s[4:5]
	s_mov_b64 s[6:7], -1
	s_cbranch_vccnz .LBB0_2540
	v_or_b32_e32 v100, v106, v189
	v_mov_b32_e32 v101, v107
	v_lshlrev_b64 v[114:115], 1, v[100:101]
	v_subrev_u32_e32 v248, s98, v112
	v_and_b32_e32 v249, 0xfffff000, v248
	v_and_b32_e32 v250, 0xfff, v248
	v_sub_u32_e32 v251, v250, v249
	v_add_u32_e32 v251, 0x800000, v251
	global_load_dwordx4 v[252:255], v251, s[100:101]
	global_load_dwordx4 v[96:99], v[112:113], off
	v_lshl_add_u64 v[100:101], s[44:45], 0, v[114:115]
	global_load_dwordx4 v[100:103], v[100:101], off
	v_or_b32_e32 v116, v108, v189
	v_mov_b32_e32 v117, v109
	v_lshlrev_b64 v[122:123], 1, v[116:117]
	v_lshl_add_u64 v[124:125], s[36:37], 0, v[114:115]
	v_lshl_add_u64 v[126:127], s[44:45], 0, v[122:123]
	v_lshl_add_u64 v[156:157], s[36:37], 0, v[122:123]
	v_cmp_ne_u32_e32 vcc, 0, v151
	v_mov_b32_e32 v105, 0
	s_waitcnt vmcnt(0)
	v_lshlrev_b32_e32 v130, 16, v96
	v_and_b32_e32 v131, 0xffff0000, v96
	v_lshlrev_b32_e32 v132, 16, v97
	v_and_b32_e32 v133, 0xffff0000, v97
	v_lshlrev_b32_e32 v134, 16, v98
	v_and_b32_e32 v135, 0xffff0000, v98
	v_lshlrev_b32_e32 v154, 16, v99
	v_and_b32_e32 v155, 0xffff0000, v99
	v_pk_add_f32 v[116:117], v[94:95], v[132:133]
	v_pk_add_f32 v[114:115], v[92:93], v[130:131]
	v_pk_add_f32 v[120:121], v[90:91], v[154:155]
	v_pk_add_f32 v[118:119], v[88:89], v[134:135]
	v_lshlrev_b32_e32 v96, 16, v100
	v_and_b32_e32 v97, 0xffff0000, v100
	v_lshlrev_b32_e32 v98, 16, v101
	v_and_b32_e32 v99, 0xffff0000, v101
	v_lshlrev_b32_e32 v100, 16, v102
	v_and_b32_e32 v101, 0xffff0000, v102
	v_lshlrev_b32_e32 v102, 16, v103
	v_and_b32_e32 v103, 0xffff0000, v103
	v_pk_mul_f32 v[98:99], v[116:117], v[98:99]
	v_pk_mul_f32 v[96:97], v[114:115], v[96:97]
	v_pk_mul_f32 v[102:103], v[120:121], v[102:103]
	v_pk_mul_f32 v[100:101], v[118:119], v[100:101]
	v_cvt_pk_bf16_f32 v96, v96, v97
	v_cvt_pk_bf16_f32 v97, v98, v99
	v_cvt_pk_bf16_f32 v98, v100, v101
	v_cvt_pk_bf16_f32 v99, v102, v103
	global_store_dwordx4 v[124:125], v[96:99], off
	v_sub_f32_e32 v124, v132, v94
	v_sub_f32_e32 v127, v133, v95
	v_sub_f32_e32 v122, v130, v92
	v_sub_f32_e32 v99, v155, v91
	v_sub_f32_e32 v130, v154, v90
	v_mov_b32_e32 v126, v124
	v_sub_f32_e32 v125, v131, v93
	v_sub_f32_e32 v131, v135, v89
	v_mov_b32_e32 v123, v125
	v_mov_b32_e32 v98, v130
	v_mov_b32_e32 v133, v131
	v_lshl_add_u64 v[96:97], v[106:107], 1, s[44:45]
	v_lshl_add_u64 v[96:97], v[96:97], 0, v[144:145]
	v_mov_b32_e32 v100, v252
	v_mov_b32_e32 v101, v253
	v_mov_b32_e32 v102, v254
	v_mov_b32_e32 v103, v255
	v_lshlrev_b32_e32 v154, 16, v100
	v_and_b32_e32 v155, 0xffff0000, v100
	v_lshlrev_b32_e32 v100, 16, v101
	v_and_b32_e32 v101, 0xffff0000, v101
	v_pk_mul_f32 v[160:161], v[126:127], v[100:101]
	v_sub_f32_e32 v126, v134, v88
	v_lshlrev_b32_e32 v158, 16, v102
	v_and_b32_e32 v159, 0xffff0000, v102
	v_lshlrev_b32_e32 v102, 16, v103
	v_and_b32_e32 v103, 0xffff0000, v103
	v_mov_b32_e32 v132, v126
	v_pk_mul_f32 v[100:101], v[122:123], v[154:155]
	v_pk_mul_f32 v[102:103], v[98:99], v[102:103]
	v_pk_mul_f32 v[132:133], v[132:133], v[158:159]
	v_cvt_pk_bf16_f32 v100, v100, v101
	v_cvt_pk_bf16_f32 v101, v160, v161
	v_cvt_pk_bf16_f32 v103, v102, v103
	v_cvt_pk_bf16_f32 v102, v132, v133
	global_store_dwordx4 v[156:157], v[100:103], off
	global_load_ushort v129, v[96:97], off offset:-14
	s_nop 0
	global_load_dwordx3 v[100:102], v[96:97], off offset:-12
	v_mov_b32_e32 v103, 0
	s_and_saveexec_b64 s[6:7], vcc
	s_cbranch_execz .LBB0_2533
	global_load_ushort v96, v[96:97], off
	s_waitcnt vmcnt(0)
	v_lshlrev_b32_e32 v105, 16, v96

; DI void fnet_layer(const Args& A, LAS unsigned char* lds, const XcdBarrier& gbar, int layer, int j, bool latonly, int wv) {
;     ...
;             bf16_t* ap = A1 + ((size_t)u.i0 * 1024 + k) * DM + col;
;             if (u.i2 < 8) { st_bf16x8(ap, v0, v1); return; }
;             f32x4 a0, a1; ld_bf16x8(ap, a0, a1);
;             const size_t off = ((size_t)u.i0 * TB + k) * DM + col;
;             f32x4 g0, g1; ld_bf16x8(Gt + off, g0, g1);
;             st_bf16x8(U + off, (a0 + v0) * g0, (a1 + v1) * g1);
;             if (k != 0) { const size_t off2 = ((size_t)u.i0 * TB + (TL - k)) * DM + col; ld_bf16x8(Gt + off2, g0, g1); st_bf16x8(U + off2, (a0 - v0) * g0, (a1 - v1) * g1); }
;             const f32x4 s0 = a0 + v0, s1 = a1 + v1, d0 = a0 - v0, d1 = a1 - v1;
;             const float sm[8] = {s0[0], s0[1], s0[2], s0[3], s1[0], s1[1], s1[2], s1[3]}, df[8] = {d0[0], d0[1], d0[2], d0[3], d1[0], d1[1], d1[2], d1[3]};
;             const size_t rowk = ((size_t)u.i0 * TB + k) * DM, rowT = ((size_t)u.i0 * TB + (TL - k)) * DM; const int cm = (col & ~255) + 512 - col_l;
;             {
;                 const bf16_t* gk_ = Gt + rowk + cm - 8; const bf16_t* gT_ = Gt + rowT + cm - 8; bf16_t* uk_ = U + rowk + cm - 8; bf16_t* uT_ = U + rowT + cm - 8;
;                 const unsigned short ka1 = gk_[1]; const unsigned ka2 = *(const unsigned*)(gk_ + 2); const u32x2 ka4 = *(const u32x2*)(gk_ + 4); const unsigned short ka0 = col_l ? gk_[8] : (unsigned short)0;
;                 unsigned short ta1 = 0, ta0 = 0; unsigned ta2 = 0; u32x2 ta4 = {0u, 0u};
;                 if (k != 0) { ta1 = gT_[1]; ta2 = *(const unsigned*)(gT_ + 2); ta4 = *(const u32x2*)(gT_ + 4); ta0 = col_l ? gT_[8] : (unsigned short)0; }
;                 uk_[1] = (bf16_t)(pk2(df[7] * __uint_as_float((unsigned)ka1 << 16), 0.f) & 0xffffu);
;                 *(unsigned*)(uk_ + 2) = pk2(df[6] * bf_lo(ka2), df[5] * bf_hi(ka2));
;                 *(u32x2*)(uk_ + 4) = (u32x2){pk2(df[4] * bf_lo(ka4.x), df[3] * bf_hi(ka4.x)), pk2(df[2] * bf_lo(ka4.y), df[1] * bf_hi(ka4.y))};
;                 if (col_l) uk_[8] = (bf16_t)(pk2(df[0] * __uint_as_float((unsigned)ka0 << 16), 0.f) & 0xffffu);
;                 if (k != 0) {
;                     uT_[1] = (bf16_t)(pk2(sm[7] * __uint_as_float((unsigned)ta1 << 16), 0.f) & 0xffffu);
;                     *(unsigned*)(uT_ + 2) = pk2(sm[6] * bf_lo(ta2), sm[5] * bf_hi(ta2));
.LBB0_2542:
	v_mov_b32_e32 v129, v145
	v_lshl_add_u64 v[88:89], v[110:111], 0, v[128:129]
	s_and_b64 vcc, exec, s[4:5]
	s_mov_b64 s[6:7], -1
	s_cbranch_vccnz .LBB0_2544
	v_or_b32_e32 v94, v106, v172
	v_mov_b32_e32 v95, v107
	v_lshlrev_b64 v[98:99], 1, v[94:95]
	v_subrev_u32_e32 v248, s98, v88
	v_add_u32_e32 v248, 256, v248
	v_and_b32_e32 v249, 0xfffff000, v248
	v_and_b32_e32 v250, 0xfff, v248
	v_sub_u32_e32 v251, v250, v249
	v_add_u32_e32 v251, 0x800000, v251
	global_load_dwordx4 v[252:255], v251, s[100:101]
	global_load_dwordx4 v[90:93], v[88:89], off offset:256
	v_lshl_add_u64 v[94:95], s[44:45], 0, v[98:99]
	global_load_dwordx4 v[94:97], v[94:95], off
	v_or_b32_e32 v100, v108, v172
	v_mov_b32_e32 v101, v109
	v_lshlrev_b64 v[100:101], 1, v[100:101]
	v_lshl_add_u64 v[98:99], s[36:37], 0, v[98:99]
	v_lshl_add_u64 v[102:103], s[44:45], 0, v[100:101]
	v_mov_b32_e32 v105, v145
	v_lshl_add_u64 v[100:101], s[36:37], 0, v[100:101]
	s_mov_b64 s[6:7], 0
	s_waitcnt vmcnt(0)
	v_lshlrev_b32_e32 v110, 16, v90
	v_and_b32_e32 v111, 0xffff0000, v90
	v_lshlrev_b32_e32 v112, 16, v91
	v_and_b32_e32 v113, 0xffff0000, v91
	v_lshlrev_b32_e32 v114, 16, v92
	v_and_b32_e32 v115, 0xffff0000, v92
	v_lshlrev_b32_e32 v116, 16, v93
	v_and_b32_e32 v117, 0xffff0000, v93
	v_pk_add_f32 v[118:119], v[84:85], v[110:111]
	v_pk_add_f32 v[120:121], v[86:87], v[112:113]
	v_pk_add_f32 v[122:123], v[80:81], v[114:115]
	v_pk_add_f32 v[124:125], v[82:83], v[116:117]
	v_lshlrev_b32_e32 v90, 16, v94
	v_and_b32_e32 v91, 0xffff0000, v94
	v_lshlrev_b32_e32 v92, 16, v95
	v_and_b32_e32 v93, 0xffff0000, v95
	v_lshlrev_b32_e32 v94, 16, v96
	v_and_b32_e32 v95, 0xffff0000, v96
	v_lshlrev_b32_e32 v96, 16, v97
	v_and_b32_e32 v97, 0xffff0000, v97
	v_pk_mul_f32 v[92:93], v[120:121], v[92:93]
	v_pk_mul_f32 v[90:91], v[118:119], v[90:91]
	v_pk_mul_f32 v[96:97], v[124:125], v[96:97]
	v_pk_mul_f32 v[94:95], v[122:123], v[94:95]
	v_cvt_pk_bf16_f32 v90, v90, v91
	v_cvt_pk_bf16_f32 v91, v92, v93
	v_cvt_pk_bf16_f32 v92, v94, v95
	v_cvt_pk_bf16_f32 v93, v96, v97
	global_store_dwordx4 v[98:99], v[90:93], off
	v_lshlrev_b64 v[98:99], 1, v[106:107]
	v_lshlrev_b64 v[102:103], 1, v[108:109]
	v_sub_f32_e32 v107, v111, v85
	v_sub_f32_e32 v106, v110, v84
	v_sub_f32_e32 v109, v113, v87
	v_sub_f32_e32 v108, v112, v86
	v_sub_f32_e32 v111, v115, v81
	v_sub_f32_e32 v110, v114, v80
	v_sub_f32_e32 v113, v117, v83
	v_sub_f32_e32 v112, v116, v82
	v_lshl_add_u64 v[94:95], s[44:45], 0, v[98:99]
	v_lshl_add_u64 v[96:97], s[44:45], 0, v[102:103]
	v_lshl_add_u64 v[94:95], v[94:95], 0, v[104:105]
	v_lshl_add_u64 v[96:97], v[96:97], 0, v[104:105]
	v_lshl_add_u64 v[98:99], s[36:37], 0, v[98:99]
	v_lshl_add_u64 v[98:99], v[98:99], 0, v[104:105]
	v_mov_b32_e32 v90, v252
	v_mov_b32_e32 v91, v253
	v_mov_b32_e32 v92, v254
	v_mov_b32_e32 v93, v255
	v_lshlrev_b32_e32 v114, 16, v90
	v_and_b32_e32 v115, 0xffff0000, v90
	v_lshlrev_b32_e32 v90, 16, v91
	v_and_b32_e32 v91, 0xffff0000, v91
	v_lshlrev_b32_e32 v116, 16, v92
	v_and_b32_e32 v117, 0xffff0000, v92
	v_lshlrev_b32_e32 v92, 16, v93
	v_and_b32_e32 v93, 0xffff0000, v93
	v_pk_mul_f32 v[126:127], v[108:109], v[90:91]
	v_pk_mul_f32 v[90:91], v[106:107], v[114:115]
	v_pk_mul_f32 v[114:115], v[112:113], v[92:93]
	v_pk_mul_f32 v[92:93], v[110:111], v[116:117]
	v_cvt_pk_bf16_f32 v90, v90, v91
	v_cvt_pk_bf16_f32 v91, v126, v127
	v_cvt_pk_bf16_f32 v92, v92, v93
	v_cvt_pk_bf16_f32 v93, v114, v115
	global_store_dwordx4 v[100:101], v[90:93], off
	global_load_ushort v93, v[94:95], off
	s_nop 0
	global_load_ushort v114, v[96:97], off
	global_load_ushort v115, v[96:97], off offset:-14
	global_load_ushort v116, v[94:95], off offset:-14
	global_load_dwordx3 v[90:92], v[94:95], off offset:-12
	s_nop 0
	global_load_dwordx3 v[94:96], v[96:97], off offset:-12
	v_lshl_add_u64 v[100:101], s[36:37], 0, v[102:103]
	v_lshl_add_u64 v[100:101], v[100:101], 0, v[104:105]
	s_waitcnt vmcnt(5)
	v_lshlrev_b32_e32 v97, 16, v93
	s_waitcnt vmcnt(4)
	v_lshlrev_b32_e32 v105, 16, v114
	s_waitcnt vmcnt(3)
	v_lshlrev_b32_e32 v126, 16, v115
	s_waitcnt vmcnt(2)
	v_lshlrev_b32_e32 v127, 16, v116
	s_waitcnt vmcnt(1)
	v_lshlrev_b32_e32 v102, 16, v90
	v_and_b32_e32 v103, 0xffff0000, v90
	v_lshlrev_b32_e32 v90, 16, v91
	v_and_b32_e32 v91, 0xffff0000, v91
	v_lshlrev_b32_e32 v114, 16, v92
	v_and_b32_e32 v115, 0xffff0000, v92
	s_waitcnt vmcnt(0)
	v_lshlrev_b32_e32 v92, 16, v94
	v_and_b32_e32 v93, 0xffff0000, v94
	v_lshlrev_b32_e32 v94, 16, v95
	v_and_b32_e32 v95, 0xffff0000, v95
	v_lshlrev_b32_e32 v116, 16, v96
	v_and_b32_e32 v117, 0xffff0000, v96
	v_mul_f32_e32 v96, v113, v127
	v_mov_b32_e32 v113, v111
	v_mov_b32_e32 v111, v109
	v_mov_b32_e32 v109, v107
	v_mul_f32_e32 v106, v106, v97
	v_mul_f32_e32 v107, v125, v126
	v_mov_b32_e32 v125, v123
	v_mov_b32_e32 v123, v121
	v_mov_b32_e32 v121, v119
	v_mul_f32_e32 v105, v118, v105
	v_cvt_pk_bf16_f32 v118, v96, s0
	v_pk_mul_f32 v[96:97], v[112:113], v[102:103]
	v_pk_mul_f32 v[90:91], v[110:111], v[90:91]
	v_pk_mul_f32 v[102:103], v[108:109], v[114:115]
	v_cvt_pk_bf16_f32 v108, v106, s0
	v_cvt_pk_bf16_f32 v109, v107, s0
	v_pk_mul_f32 v[92:93], v[124:125], v[92:93]
	v_pk_mul_f32 v[94:95], v[122:123], v[94:95]
	v_pk_mul_f32 v[106:107], v[120:121], v[116:117]
	v_cvt_pk_bf16_f32 v105, v105, s0
	v_cvt_pk_bf16_f32 v96, v96, v97
	v_cvt_pk_bf16_f32 v90, v90, v91
	v_cvt_pk_bf16_f32 v97, v92, v93
	v_cvt_pk_bf16_f32 v92, v94, v95
	v_cvt_pk_bf16_f32 v93, v106, v107
	v_cvt_pk_bf16_f32 v91, v102, v103
	global_store_short v[98:99], v108, off
	global_store_short v[100:101], v105, off
	v_perm_b32 v94, v96, v118, s60
	global_store_short_d16_hi v[98:99], v96, off offset:-10
	global_store_dwordx2 v[98:99], v[90:91], off offset:-8
	v_perm_b32 v90, v97, v109, s60
	global_store_dwordx2 v[100:101], v[92:93], off offset:-8
	global_store_dword v[98:99], v94, off offset:-14
	global_store_short_d16_hi v[100:101], v97, off offset:-10
	global_store_dword v[100:101], v90, off offset:-14

; DI unsigned pk2(float a, float b) { f32x2 v = {a, b}; return __builtin_bit_cast(unsigned, __builtin_convertvector(v, bf16v2)); }
; DI float bf_lo(unsigned w) { return __uint_as_float(w << 16); }
; DI void fnet_layer(const Args& A, LAS unsigned char* lds, const XcdBarrier& gbar, int layer, int j, bool latonly, int wv) {
;     ...
;             bf16_t* ap = A1 + ((size_t)u.i0 * 1024 + k) * DM + col;
;             if (u.i2 < 8) { st_bf16x8(ap, v0, v1); return; }
;             f32x4 a0, a1; ld_bf16x8(ap, a0, a1);
;             const size_t off = ((size_t)u.i0 * TB + k) * DM + col;
;             f32x4 g0, g1; ld_bf16x8(Gt + off, g0, g1);
;             st_bf16x8(U + off, (a0 + v0) * g0, (a1 + v1) * g1);
;             if (k != 0) { const size_t off2 = ((size_t)u.i0 * TB + (TL - k)) * DM + col; ld_bf16x8(Gt + off2, g0, g1); st_bf16x8(U + off2, (a0 - v0) * g0, (a1 - v1) * g1); }
;             const f32x4 s0 = a0 + v0, s1 = a1 + v1, d0 = a0 - v0, d1 = a1 - v1;
;             const float sm[8] = {s0[0], s0[1], s0[2], s0[3], s1[0], s1[1], s1[2], s1[3]}, df[8] = {d0[0], d0[1], d0[2], d0[3], d1[0], d1[1], d1[2], d1[3]};
;             const size_t rowk = ((size_t)u.i0 * TB + k) * DM, rowT = ((size_t)u.i0 * TB + (TL - k)) * DM; const int cm = (col & ~255) + 512 - col_l;
;             {
;                 const bf16_t* gk_ = Gt + rowk + cm - 8; const bf16_t* gT_ = Gt + rowT + cm - 8; bf16_t* uk_ = U + rowk + cm - 8; bf16_t* uT_ = U + rowT + cm - 8;
;                 const unsigned short ka1 = gk_[1]; const unsigned ka2 = *(const unsigned*)(gk_ + 2); const u32x2 ka4 = *(const u32x2*)(gk_ + 4); const unsigned short ka0 = col_l ? gk_[8] : (unsigned short)0;
;                 unsigned short ta1 = 0, ta0 = 0; unsigned ta2 = 0; u32x2 ta4 = {0u, 0u};
;                 if (k != 0) { ta1 = gT_[1]; ta2 = *(const unsigned*)(gT_ + 2); ta4 = *(const u32x2*)(gT_ + 4); ta0 = col_l ? gT_[8] : (unsigned short)0; }
;                 uk_[1] = (bf16_t)(pk2(df[7] * __uint_as_float((unsigned)ka1 << 16), 0.f) & 0xffffu);
;                 *(unsigned*)(uk_ + 2) = pk2(df[6] * bf_lo(ka2), df[5] * bf_hi(ka2));
;                 *(u32x2*)(uk_ + 4) = (u32x2){pk2(df[4] * bf_lo(ka4.x), df[3] * bf_hi(ka4.x)), pk2(df[2] * bf_lo(ka4.y), df[1] * bf_hi(ka4.y))};
;                 if (col_l) uk_[8] = (bf16_t)(pk2(df[0] * __uint_as_float((unsigned)ka0 << 16), 0.f) & 0xffffu);
.LBB0_2546:
	v_or_b32_e32 v80, 48, v150
	v_ashrrev_i32_e32 v81, 31, v80
	v_lshlrev_b64 v[82:83], 12, v[80:81]
	v_lshl_add_u64 v[84:85], s[40:41], 0, v[80:81]
	v_sub_u32_e32 v80, 0x800, v80
	v_ashrrev_i32_e32 v81, 31, v80
	v_lshl_add_u64 v[80:81], s[40:41], 0, v[80:81]
	v_lshl_add_u64 v[92:93], s[42:43], 0, v[82:83]
	v_mov_b32_e32 v153, v145
	v_lshlrev_b64 v[88:89], 11, v[84:85]
	v_lshlrev_b64 v[90:91], 11, v[80:81]
	v_lshl_add_u64 v[94:95], v[92:93], 0, v[152:153]
	s_and_b64 vcc, exec, s[4:5]
	s_mov_b64 s[6:7], -1
	s_cbranch_vccnz .LBB0_2556
	v_or_b32_e32 v84, v88, v189
	v_mov_b32_e32 v85, v89
	v_lshlrev_b64 v[96:97], 1, v[84:85]
	v_subrev_u32_e32 v248, s98, v94
	v_and_b32_e32 v249, 0xfffff000, v248
	v_and_b32_e32 v250, 0xfff, v248
	v_sub_u32_e32 v251, v250, v249
	v_add_u32_e32 v251, 0x800000, v251
	global_load_dwordx4 v[252:255], v251, s[100:101]
	global_load_dwordx4 v[80:83], v[94:95], off
	v_lshl_add_u64 v[84:85], s[44:45], 0, v[96:97]
	global_load_dwordx4 v[84:87], v[84:85], off
	v_or_b32_e32 v98, v90, v189
	v_mov_b32_e32 v99, v91
	v_lshlrev_b64 v[106:107], 1, v[98:99]
	v_lshl_add_u64 v[108:109], s[36:37], 0, v[96:97]
	v_lshl_add_u64 v[110:111], s[44:45], 0, v[106:107]
	v_lshl_add_u64 v[120:121], s[36:37], 0, v[106:107]
	v_cmp_ne_u32_e32 vcc, 0, v151
	v_mov_b32_e32 v105, 0
	s_waitcnt vmcnt(0)
	v_lshlrev_b32_e32 v112, 16, v80
	v_and_b32_e32 v113, 0xffff0000, v80
	v_lshlrev_b32_e32 v114, 16, v81
	v_and_b32_e32 v115, 0xffff0000, v81
	v_lshlrev_b32_e32 v116, 16, v82
	v_and_b32_e32 v117, 0xffff0000, v82
	v_lshlrev_b32_e32 v118, 16, v83
	v_and_b32_e32 v119, 0xffff0000, v83
	v_pk_add_f32 v[98:99], v[78:79], v[114:115]
	v_pk_add_f32 v[96:97], v[76:77], v[112:113]
	v_pk_add_f32 v[102:103], v[74:75], v[118:119]
	v_pk_add_f32 v[100:101], v[72:73], v[116:117]
	v_lshlrev_b32_e32 v80, 16, v84
	v_and_b32_e32 v81, 0xffff0000, v84
	v_lshlrev_b32_e32 v82, 16, v85
	v_and_b32_e32 v83, 0xffff0000, v85
	v_lshlrev_b32_e32 v84, 16, v86
	v_and_b32_e32 v85, 0xffff0000, v86
	v_lshlrev_b32_e32 v86, 16, v87
	v_and_b32_e32 v87, 0xffff0000, v87
	v_pk_mul_f32 v[82:83], v[98:99], v[82:83]
	v_pk_mul_f32 v[80:81], v[96:97], v[80:81]
	v_pk_mul_f32 v[86:87], v[102:103], v[86:87]
	v_pk_mul_f32 v[84:85], v[100:101], v[84:85]
	v_cvt_pk_bf16_f32 v80, v80, v81
	v_cvt_pk_bf16_f32 v81, v82, v83
	v_cvt_pk_bf16_f32 v82, v84, v85
	v_cvt_pk_bf16_f32 v83, v86, v87
	global_store_dwordx4 v[108:109], v[80:83], off
	v_sub_f32_e32 v108, v114, v78
	v_sub_f32_e32 v111, v115, v79
	v_sub_f32_e32 v106, v112, v76
	v_sub_f32_e32 v83, v119, v75
	v_sub_f32_e32 v112, v118, v74
	v_mov_b32_e32 v110, v108
	v_sub_f32_e32 v109, v113, v77
	v_sub_f32_e32 v113, v117, v73
	v_mov_b32_e32 v107, v109
	v_mov_b32_e32 v82, v112
	v_mov_b32_e32 v115, v113
	v_lshl_add_u64 v[80:81], v[88:89], 1, s[44:45]
	v_lshl_add_u64 v[80:81], v[80:81], 0, v[144:145]
	v_mov_b32_e32 v84, v252
	v_mov_b32_e32 v85, v253
	v_mov_b32_e32 v86, v254
	v_mov_b32_e32 v87, v255
	v_lshlrev_b32_e32 v118, 16, v84
	v_and_b32_e32 v119, 0xffff0000, v84
	v_lshlrev_b32_e32 v84, 16, v85
	v_and_b32_e32 v85, 0xffff0000, v85
	v_pk_mul_f32 v[124:125], v[110:111], v[84:85]
	v_sub_f32_e32 v110, v116, v72
	v_lshlrev_b32_e32 v122, 16, v86
	v_and_b32_e32 v123, 0xffff0000, v86
	v_lshlrev_b32_e32 v86, 16, v87
	v_and_b32_e32 v87, 0xffff0000, v87
	v_mov_b32_e32 v114, v110
	v_pk_mul_f32 v[84:85], v[106:107], v[118:119]
	v_pk_mul_f32 v[86:87], v[82:83], v[86:87]
	v_pk_mul_f32 v[114:115], v[114:115], v[122:123]
	v_cvt_pk_bf16_f32 v84, v84, v85
	v_cvt_pk_bf16_f32 v85, v124, v125
	v_cvt_pk_bf16_f32 v87, v86, v87
	v_cvt_pk_bf16_f32 v86, v114, v115
	global_store_dwordx4 v[120:121], v[84:87], off
	global_load_ushort v116, v[80:81], off offset:-14
	s_nop 0
	global_load_dwordx3 v[84:86], v[80:81], off offset:-12
	v_mov_b32_e32 v87, 0
	s_and_saveexec_b64 s[6:7], vcc
	s_cbranch_execz .LBB0_2549
	global_load_ushort v80, v[80:81], off
	s_waitcnt vmcnt(0)
	v_lshlrev_b32_e32 v105, 16, v80

; DI void fnet_layer(const Args& A, LAS unsigned char* lds, const XcdBarrier& gbar, int layer, int j, bool latonly, int wv) {
;     ...
;             bf16_t* ap = A1 + ((size_t)u.i0 * 1024 + k) * DM + col;
;             if (u.i2 < 8) { st_bf16x8(ap, v0, v1); return; }
;             f32x4 a0, a1; ld_bf16x8(ap, a0, a1);
;             const size_t off = ((size_t)u.i0 * TB + k) * DM + col;
;             f32x4 g0, g1; ld_bf16x8(Gt + off, g0, g1);
;             st_bf16x8(U + off, (a0 + v0) * g0, (a1 + v1) * g1);
;             if (k != 0) { const size_t off2 = ((size_t)u.i0 * TB + (TL - k)) * DM + col; ld_bf16x8(Gt + off2, g0, g1); st_bf16x8(U + off2, (a0 - v0) * g0, (a1 - v1) * g1); }
;             const f32x4 s0 = a0 + v0, s1 = a1 + v1, d0 = a0 - v0, d1 = a1 - v1;
;             const float sm[8] = {s0[0], s0[1], s0[2], s0[3], s1[0], s1[1], s1[2], s1[3]}, df[8] = {d0[0], d0[1], d0[2], d0[3], d1[0], d1[1], d1[2], d1[3]};
;             const size_t rowk = ((size_t)u.i0 * TB + k) * DM, rowT = ((size_t)u.i0 * TB + (TL - k)) * DM; const int cm = (col & ~255) + 512 - col_l;
;             {
;                 const bf16_t* gk_ = Gt + rowk + cm - 8; const bf16_t* gT_ = Gt + rowT + cm - 8; bf16_t* uk_ = U + rowk + cm - 8; bf16_t* uT_ = U + rowT + cm - 8;
;                 const unsigned short ka1 = gk_[1]; const unsigned ka2 = *(const unsigned*)(gk_ + 2); const u32x2 ka4 = *(const u32x2*)(gk_ + 4); const unsigned short ka0 = col_l ? gk_[8] : (unsigned short)0;
;                 unsigned short ta1 = 0, ta0 = 0; unsigned ta2 = 0; u32x2 ta4 = {0u, 0u};
;                 if (k != 0) { ta1 = gT_[1]; ta2 = *(const unsigned*)(gT_ + 2); ta4 = *(const u32x2*)(gT_ + 4); ta0 = col_l ? gT_[8] : (unsigned short)0; }
;                 uk_[1] = (bf16_t)(pk2(df[7] * __uint_as_float((unsigned)ka1 << 16), 0.f) & 0xffffu);
;                 *(unsigned*)(uk_ + 2) = pk2(df[6] * bf_lo(ka2), df[5] * bf_hi(ka2));
;                 *(u32x2*)(uk_ + 4) = (u32x2){pk2(df[4] * bf_lo(ka4.x), df[3] * bf_hi(ka4.x)), pk2(df[2] * bf_lo(ka4.y), df[1] * bf_hi(ka4.y))};
;                 if (col_l) uk_[8] = (bf16_t)(pk2(df[0] * __uint_as_float((unsigned)ka0 << 16), 0.f) & 0xffffu);
;                 if (k != 0) {
;                     uT_[1] = (bf16_t)(pk2(sm[7] * __uint_as_float((unsigned)ta1 << 16), 0.f) & 0xffffu);
;                     *(unsigned*)(uT_ + 2) = pk2(sm[6] * bf_lo(ta2), sm[5] * bf_hi(ta2));
.LBB0_2558:
	v_mov_b32_e32 v129, v145
	v_lshl_add_u64 v[72:73], v[92:93], 0, v[128:129]
	s_and_b64 vcc, exec, s[4:5]
	s_mov_b64 s[6:7], -1
	s_cbranch_vccnz .LBB0_2560
	v_or_b32_e32 v78, v88, v172
	v_mov_b32_e32 v79, v89
	v_lshlrev_b64 v[82:83], 1, v[78:79]
	v_subrev_u32_e32 v248, s98, v72
	v_add_u32_e32 v248, 256, v248
	v_and_b32_e32 v249, 0xfffff000, v248
	v_and_b32_e32 v250, 0xfff, v248
	v_sub_u32_e32 v251, v250, v249
	v_add_u32_e32 v251, 0x800000, v251
	global_load_dwordx4 v[252:255], v251, s[100:101]
	global_load_dwordx4 v[74:77], v[72:73], off offset:256
	v_lshl_add_u64 v[78:79], s[44:45], 0, v[82:83]
	global_load_dwordx4 v[78:81], v[78:79], off
	v_or_b32_e32 v84, v90, v172
	v_mov_b32_e32 v85, v91
	v_lshlrev_b64 v[84:85], 1, v[84:85]
	v_lshl_add_u64 v[82:83], s[36:37], 0, v[82:83]
	v_lshl_add_u64 v[86:87], s[44:45], 0, v[84:85]
	v_mov_b32_e32 v105, v145
	v_lshl_add_u64 v[84:85], s[36:37], 0, v[84:85]
	s_mov_b64 s[6:7], 0
	s_waitcnt vmcnt(0)
	v_lshlrev_b32_e32 v92, 16, v74
	v_and_b32_e32 v93, 0xffff0000, v74
	v_lshlrev_b32_e32 v94, 16, v75
	v_and_b32_e32 v95, 0xffff0000, v75
	v_lshlrev_b32_e32 v96, 16, v76
	v_and_b32_e32 v97, 0xffff0000, v76
	v_lshlrev_b32_e32 v98, 16, v77
	v_and_b32_e32 v99, 0xffff0000, v77
	v_pk_add_f32 v[100:101], v[68:69], v[92:93]
	v_pk_add_f32 v[102:103], v[70:71], v[94:95]
	v_pk_add_f32 v[106:107], v[64:65], v[96:97]
	v_pk_add_f32 v[108:109], v[66:67], v[98:99]
	v_lshlrev_b32_e32 v74, 16, v78
	v_and_b32_e32 v75, 0xffff0000, v78
	v_lshlrev_b32_e32 v76, 16, v79
	v_and_b32_e32 v77, 0xffff0000, v79
	v_lshlrev_b32_e32 v78, 16, v80
	v_and_b32_e32 v79, 0xffff0000, v80
	v_lshlrev_b32_e32 v80, 16, v81
	v_and_b32_e32 v81, 0xffff0000, v81
	v_pk_mul_f32 v[76:77], v[102:103], v[76:77]
	v_pk_mul_f32 v[74:75], v[100:101], v[74:75]
	v_pk_mul_f32 v[80:81], v[108:109], v[80:81]
	v_pk_mul_f32 v[78:79], v[106:107], v[78:79]
	v_cvt_pk_bf16_f32 v74, v74, v75
	v_cvt_pk_bf16_f32 v75, v76, v77
	v_cvt_pk_bf16_f32 v76, v78, v79
	v_cvt_pk_bf16_f32 v77, v80, v81
	global_store_dwordx4 v[82:83], v[74:77], off
	v_lshlrev_b64 v[82:83], 1, v[88:89]
	v_lshlrev_b64 v[86:87], 1, v[90:91]
	v_sub_f32_e32 v89, v93, v69
	v_sub_f32_e32 v88, v92, v68
	v_sub_f32_e32 v91, v95, v71
	v_sub_f32_e32 v90, v94, v70
	v_sub_f32_e32 v93, v97, v65
	v_sub_f32_e32 v92, v96, v64
	v_sub_f32_e32 v95, v99, v67
	v_sub_f32_e32 v94, v98, v66
	v_lshl_add_u64 v[78:79], s[44:45], 0, v[82:83]
	v_lshl_add_u64 v[80:81], s[44:45], 0, v[86:87]
	v_lshl_add_u64 v[78:79], v[78:79], 0, v[104:105]
	v_lshl_add_u64 v[80:81], v[80:81], 0, v[104:105]
	v_lshl_add_u64 v[82:83], s[36:37], 0, v[82:83]
	v_lshl_add_u64 v[82:83], v[82:83], 0, v[104:105]
	v_mov_b32_e32 v74, v252
	v_mov_b32_e32 v75, v253
	v_mov_b32_e32 v76, v254
	v_mov_b32_e32 v77, v255
	v_lshlrev_b32_e32 v96, 16, v74
	v_and_b32_e32 v97, 0xffff0000, v74
	v_lshlrev_b32_e32 v74, 16, v75
	v_and_b32_e32 v75, 0xffff0000, v75
	v_lshlrev_b32_e32 v98, 16, v76
	v_and_b32_e32 v99, 0xffff0000, v76
	v_lshlrev_b32_e32 v76, 16, v77
	v_and_b32_e32 v77, 0xffff0000, v77
	v_pk_mul_f32 v[110:111], v[90:91], v[74:75]
	v_pk_mul_f32 v[74:75], v[88:89], v[96:97]
	v_pk_mul_f32 v[96:97], v[94:95], v[76:77]
	v_pk_mul_f32 v[76:77], v[92:93], v[98:99]
	v_cvt_pk_bf16_f32 v74, v74, v75
	v_cvt_pk_bf16_f32 v75, v110, v111
	v_cvt_pk_bf16_f32 v76, v76, v77
	v_cvt_pk_bf16_f32 v77, v96, v97
	global_store_dwordx4 v[84:85], v[74:77], off
	global_load_ushort v77, v[78:79], off
	s_nop 0
	global_load_ushort v96, v[80:81], off
	global_load_ushort v97, v[80:81], off offset:-14
	global_load_ushort v98, v[78:79], off offset:-14
	global_load_dwordx3 v[74:76], v[78:79], off offset:-12
	s_nop 0
	global_load_dwordx3 v[78:80], v[80:81], off offset:-12
	v_lshl_add_u64 v[84:85], s[36:37], 0, v[86:87]
	v_lshl_add_u64 v[84:85], v[84:85], 0, v[104:105]
	s_waitcnt vmcnt(5)
	v_lshlrev_b32_e32 v81, 16, v77
	s_waitcnt vmcnt(4)
	v_lshlrev_b32_e32 v105, 16, v96
	s_waitcnt vmcnt(3)
	v_lshlrev_b32_e32 v110, 16, v97
	s_waitcnt vmcnt(2)
	v_lshlrev_b32_e32 v111, 16, v98
	s_waitcnt vmcnt(1)
	v_lshlrev_b32_e32 v86, 16, v74
	v_and_b32_e32 v87, 0xffff0000, v74
	v_lshlrev_b32_e32 v74, 16, v75
	v_and_b32_e32 v75, 0xffff0000, v75
	v_lshlrev_b32_e32 v96, 16, v76
	v_and_b32_e32 v97, 0xffff0000, v76
	s_waitcnt vmcnt(0)
	v_lshlrev_b32_e32 v76, 16, v78
	v_and_b32_e32 v77, 0xffff0000, v78
	v_lshlrev_b32_e32 v98, 16, v80
	v_and_b32_e32 v99, 0xffff0000, v80
	v_mul_f32_e32 v80, v95, v111
	v_mov_b32_e32 v95, v93
	v_mov_b32_e32 v93, v91
	v_mov_b32_e32 v91, v89
	v_mul_f32_e32 v89, v109, v110
	v_mov_b32_e32 v109, v107
	v_lshlrev_b32_e32 v78, 16, v79
	v_and_b32_e32 v79, 0xffff0000, v79
	v_mul_f32_e32 v88, v88, v81
	v_mov_b32_e32 v107, v103
	v_mov_b32_e32 v103, v101
	v_mul_f32_e32 v100, v100, v105
	v_cvt_pk_bf16_f32 v101, v80, s0
	v_pk_mul_f32 v[80:81], v[94:95], v[86:87]
	v_pk_mul_f32 v[74:75], v[92:93], v[74:75]
	v_pk_mul_f32 v[76:77], v[108:109], v[76:77]
	v_pk_mul_f32 v[86:87], v[90:91], v[96:97]
	v_cvt_pk_bf16_f32 v90, v88, s0
	v_cvt_pk_bf16_f32 v91, v89, s0
	v_pk_mul_f32 v[78:79], v[106:107], v[78:79]
	v_pk_mul_f32 v[88:89], v[102:103], v[98:99]
	v_cvt_pk_bf16_f32 v92, v100, s0
	v_cvt_pk_bf16_f32 v80, v80, v81
	v_cvt_pk_bf16_f32 v74, v74, v75
	v_cvt_pk_bf16_f32 v81, v76, v77
	v_cvt_pk_bf16_f32 v75, v86, v87
	global_store_short v[82:83], v90, off
	v_cvt_pk_bf16_f32 v76, v78, v79
	v_cvt_pk_bf16_f32 v77, v88, v89
	global_store_short v[84:85], v92, off
	v_perm_b32 v78, v80, v101, s60
	global_store_short_d16_hi v[82:83], v80, off offset:-10
	global_store_dwordx2 v[82:83], v[74:75], off offset:-8
	v_perm_b32 v74, v81, v91, s60
	global_store_short_d16_hi v[84:85], v81, off offset:-10
	global_store_dwordx2 v[84:85], v[76:77], off offset:-8
	global_store_dword v[82:83], v78, off offset:-14
	global_store_dword v[84:85], v74, off offset:-14

; DI void st_bf16x8(bf16_t* p, f32x4 a, f32x4 b) { u32x4 w = {pk2(a[0], a[1]), pk2(a[2], a[3]), pk2(b[0], b[1]), pk2(b[2], b[3])}; *(u32x4*)p = w; }
; DI void ld_bf16x8(const bf16_t* p, f32x4& a, f32x4& b) { const u32x4 w = *(const u32x4*)p; a = (f32x4){bf_lo(w.x), bf_hi(w.x), bf_lo(w.y), bf_hi(w.y)}; b = (f32x4){bf_lo(w.z), bf_hi(w.z), bf_lo(w.w), bf_hi(w.w)}; }
; DI void fnet_layer(const Args& A, LAS unsigned char* lds, const XcdBarrier& gbar, int layer, int j, bool latonly, int wv) {
;     ...
;             bf16_t* ap = A1 + ((size_t)u.i0 * 1024 + k) * DM + col;
;             if (u.i2 < 8) { st_bf16x8(ap, v0, v1); return; }
;             f32x4 a0, a1; ld_bf16x8(ap, a0, a1);
;             const size_t off = ((size_t)u.i0 * TB + k) * DM + col;
;             f32x4 g0, g1; ld_bf16x8(Gt + off, g0, g1);
;             st_bf16x8(U + off, (a0 + v0) * g0, (a1 + v1) * g1);
;             if (k != 0) { const size_t off2 = ((size_t)u.i0 * TB + (TL - k)) * DM + col; ld_bf16x8(Gt + off2, g0, g1); st_bf16x8(U + off2, (a0 - v0) * g0, (a1 - v1) * g1); }
.LBB0_2562:
	v_add_u32_e32 v64, 0x80, v150
	v_ashrrev_i32_e32 v65, 31, v64
	v_sub_u32_e32 v74, 0x780, v150
	v_lshlrev_b64 v[66:67], 12, v[64:65]
	v_ashrrev_i32_e32 v75, 31, v74
	v_lshl_add_u64 v[68:69], s[40:41], 0, v[64:65]
	v_cmp_ne_u32_e64 s[6:7], 0, v64
	v_lshl_add_u64 v[64:65], s[40:41], 0, v[74:75]
	v_lshl_add_u64 v[78:79], s[42:43], 0, v[66:67]
	v_mov_b32_e32 v153, v145
	v_lshlrev_b64 v[72:73], 11, v[68:69]
	v_lshlrev_b64 v[76:77], 11, v[64:65]
	v_lshl_add_u64 v[80:81], v[78:79], 0, v[152:153]
	s_and_b64 vcc, exec, s[4:5]
	s_mov_b64 s[46:47], -1
	s_cbranch_vccnz .LBB0_2579
	v_or_b32_e32 v68, v72, v189
	v_mov_b32_e32 v69, v73
	v_lshlrev_b64 v[82:83], 1, v[68:69]
	v_subrev_u32_e32 v248, s98, v80
	v_and_b32_e32 v249, 0xfffff000, v248
	v_and_b32_e32 v250, 0xfff, v248
	v_sub_u32_e32 v251, v250, v249
	v_add_u32_e32 v251, 0x800000, v251
	global_load_dwordx4 v[252:255], v251, s[100:101]
	global_load_dwordx4 v[64:67], v[80:81], off
	v_lshl_add_u64 v[68:69], s[44:45], 0, v[82:83]
	global_load_dwordx4 v[68:71], v[68:69], off
	v_lshl_add_u64 v[98:99], s[36:37], 0, v[82:83]
	s_waitcnt vmcnt(0)
	v_lshlrev_b32_e32 v90, 16, v64
	v_and_b32_e32 v91, 0xffff0000, v64
	v_lshlrev_b32_e32 v64, 16, v65
	v_and_b32_e32 v65, 0xffff0000, v65
	v_lshlrev_b32_e32 v94, 16, v66
	v_and_b32_e32 v95, 0xffff0000, v66
	v_lshlrev_b32_e32 v66, 16, v67
	v_and_b32_e32 v67, 0xffff0000, v67
	v_pk_add_f32 v[84:85], v[62:63], v[64:65]
	v_pk_add_f32 v[82:83], v[60:61], v[90:91]
	v_pk_add_f32 v[88:89], v[58:59], v[66:67]
	v_pk_add_f32 v[86:87], v[56:57], v[94:95]
	v_sub_f32_e32 v93, v65, v63
	v_sub_f32_e32 v92, v64, v62
	v_sub_f32_e32 v97, v67, v59
	v_sub_f32_e32 v96, v66, v58
	v_lshlrev_b32_e32 v64, 16, v68
	v_and_b32_e32 v65, 0xffff0000, v68
	v_lshlrev_b32_e32 v66, 16, v69
	v_and_b32_e32 v67, 0xffff0000, v69
	v_lshlrev_b32_e32 v68, 16, v70
	v_and_b32_e32 v69, 0xffff0000, v70
	v_lshlrev_b32_e32 v70, 16, v71
	v_and_b32_e32 v71, 0xffff0000, v71
	v_pk_mul_f32 v[66:67], v[84:85], v[66:67]
	v_pk_mul_f32 v[64:65], v[82:83], v[64:65]
	v_pk_mul_f32 v[70:71], v[88:89], v[70:71]
	v_pk_mul_f32 v[68:69], v[86:87], v[68:69]
	v_sub_f32_e32 v91, v91, v61
	v_sub_f32_e32 v90, v90, v60
	v_sub_f32_e32 v95, v95, v57
	v_cvt_pk_bf16_f32 v64, v64, v65
	v_cvt_pk_bf16_f32 v65, v66, v67
	v_cvt_pk_bf16_f32 v66, v68, v69
	v_cvt_pk_bf16_f32 v67, v70, v71
	v_sub_f32_e32 v94, v94, v56
	global_store_dwordx4 v[98:99], v[64:67], off
	s_and_saveexec_b64 s[46:47], s[6:7]
	s_xor_b64 s[46:47], exec, s[46:47]
	s_cbranch_execz .LBB0_2565
	v_or_b32_e32 v64, v76, v189
	v_mov_b32_e32 v65, v77
	v_lshlrev_b64 v[68:69], 1, v[64:65]
	v_lshl_add_u64 v[64:65], s[44:45], 0, v[68:69]
	v_lshl_add_u64 v[68:69], s[36:37], 0, v[68:69]
	v_mov_b32_e32 v64, v252
	v_mov_b32_e32 v65, v253
	v_mov_b32_e32 v66, v254
	v_mov_b32_e32 v67, v255
	v_lshlrev_b32_e32 v70, 16, v64
	v_and_b32_e32 v71, 0xffff0000, v64
	v_lshlrev_b32_e32 v64, 16, v65
	v_and_b32_e32 v65, 0xffff0000, v65
	v_lshlrev_b32_e32 v98, 16, v66
	v_and_b32_e32 v99, 0xffff0000, v66
	v_lshlrev_b32_e32 v66, 16, v67
	v_and_b32_e32 v67, 0xffff0000, v67
	v_pk_mul_f32 v[100:101], v[92:93], v[64:65]
	v_pk_mul_f32 v[64:65], v[90:91], v[70:71]
	v_pk_mul_f32 v[70:71], v[96:97], v[66:67]
	v_pk_mul_f32 v[66:67], v[94:95], v[98:99]
	v_cvt_pk_bf16_f32 v64, v64, v65
	v_cvt_pk_bf16_f32 v65, v100, v101
	v_cvt_pk_bf16_f32 v66, v66, v67
	v_cvt_pk_bf16_f32 v67, v70, v71
	global_store_dwordx4 v[68:69], v[64:67], off

; DI void st_bf16x8(bf16_t* p, f32x4 a, f32x4 b) { u32x4 w = {pk2(a[0], a[1]), pk2(a[2], a[3]), pk2(b[0], b[1]), pk2(b[2], b[3])}; *(u32x4*)p = w; }
; DI void ld_bf16x8(const bf16_t* p, f32x4& a, f32x4& b) { const u32x4 w = *(const u32x4*)p; a = (f32x4){bf_lo(w.x), bf_hi(w.x), bf_lo(w.y), bf_hi(w.y)}; b = (f32x4){bf_lo(w.z), bf_hi(w.z), bf_lo(w.w), bf_hi(w.w)}; }
; DI void fnet_layer(const Args& A, LAS unsigned char* lds, const XcdBarrier& gbar, int layer, int j, bool latonly, int wv) {
;     ...
;             bf16_t* ap = A1 + ((size_t)u.i0 * 1024 + k) * DM + col;
;             if (u.i2 < 8) { st_bf16x8(ap, v0, v1); return; }
;             f32x4 a0, a1; ld_bf16x8(ap, a0, a1);
;             const size_t off = ((size_t)u.i0 * TB + k) * DM + col;
;             f32x4 g0, g1; ld_bf16x8(Gt + off, g0, g1);
;             st_bf16x8(U + off, (a0 + v0) * g0, (a1 + v1) * g1);
;             if (k != 0) { const size_t off2 = ((size_t)u.i0 * TB + (TL - k)) * DM + col; ld_bf16x8(Gt + off2, g0, g1); st_bf16x8(U + off2, (a0 - v0) * g0, (a1 - v1) * g1); }
.LBB0_2581:
	v_mov_b32_e32 v129, v145
	v_lshl_add_u64 v[64:65], v[78:79], 0, v[128:129]
	s_and_b64 vcc, exec, s[4:5]
	s_mov_b64 s[46:47], -1
	s_cbranch_vccnz .LBB0_2591
	v_or_b32_e32 v60, v72, v172
	v_mov_b32_e32 v61, v73
	v_lshlrev_b64 v[66:67], 1, v[60:61]
	v_subrev_u32_e32 v248, s98, v64
	v_add_u32_e32 v248, 256, v248
	v_and_b32_e32 v249, 0xfffff000, v248
	v_and_b32_e32 v250, 0xfff, v248
	v_sub_u32_e32 v251, v250, v249
	v_add_u32_e32 v251, 0x800000, v251
	global_load_dwordx4 v[252:255], v251, s[100:101]
	global_load_dwordx4 v[56:59], v[64:65], off offset:256
	v_lshl_add_u64 v[60:61], s[44:45], 0, v[66:67]
	global_load_dwordx4 v[60:63], v[60:61], off
	v_lshl_add_u64 v[88:89], s[36:37], 0, v[66:67]
	s_waitcnt vmcnt(0)
	v_lshlrev_b32_e32 v80, 16, v56
	v_and_b32_e32 v81, 0xffff0000, v56
	v_lshlrev_b32_e32 v56, 16, v57
	v_and_b32_e32 v57, 0xffff0000, v57
	v_lshlrev_b32_e32 v84, 16, v58
	v_and_b32_e32 v85, 0xffff0000, v58
	v_lshlrev_b32_e32 v58, 16, v59
	v_and_b32_e32 v59, 0xffff0000, v59
	v_pk_add_f32 v[68:69], v[54:55], v[56:57]
	v_pk_add_f32 v[66:67], v[52:53], v[80:81]
	v_pk_add_f32 v[78:79], v[50:51], v[58:59]
	v_pk_add_f32 v[70:71], v[48:49], v[84:85]
	v_sub_f32_e32 v83, v57, v55
	v_sub_f32_e32 v82, v56, v54
	v_sub_f32_e32 v87, v59, v51
	v_sub_f32_e32 v86, v58, v50
	v_lshlrev_b32_e32 v56, 16, v60
	v_and_b32_e32 v57, 0xffff0000, v60
	v_lshlrev_b32_e32 v58, 16, v61
	v_and_b32_e32 v59, 0xffff0000, v61
	v_lshlrev_b32_e32 v60, 16, v62
	v_and_b32_e32 v61, 0xffff0000, v62
	v_lshlrev_b32_e32 v62, 16, v63
	v_and_b32_e32 v63, 0xffff0000, v63
	v_pk_mul_f32 v[58:59], v[68:69], v[58:59]
	v_pk_mul_f32 v[56:57], v[66:67], v[56:57]
	v_pk_mul_f32 v[62:63], v[78:79], v[62:63]
	v_pk_mul_f32 v[60:61], v[70:71], v[60:61]
	v_sub_f32_e32 v81, v81, v53
	v_sub_f32_e32 v80, v80, v52
	v_sub_f32_e32 v85, v85, v49
	v_cvt_pk_bf16_f32 v56, v56, v57
	v_cvt_pk_bf16_f32 v57, v58, v59
	v_cvt_pk_bf16_f32 v58, v60, v61
	v_cvt_pk_bf16_f32 v59, v62, v63
	v_sub_f32_e32 v84, v84, v48
	global_store_dwordx4 v[88:89], v[56:59], off
	s_and_saveexec_b64 s[46:47], s[6:7]
	s_xor_b64 s[46:47], exec, s[46:47]
	s_cbranch_execz .LBB0_2584
	v_or_b32_e32 v76, v76, v172
	v_lshlrev_b64 v[60:61], 1, v[76:77]
	v_lshl_add_u64 v[56:57], s[44:45], 0, v[60:61]
	v_lshl_add_u64 v[60:61], s[36:37], 0, v[60:61]
	v_mov_b32_e32 v56, v252
	v_mov_b32_e32 v57, v253
	v_mov_b32_e32 v58, v254
	v_mov_b32_e32 v59, v255
	v_lshlrev_b32_e32 v62, 16, v56
	v_and_b32_e32 v63, 0xffff0000, v56
	v_lshlrev_b32_e32 v56, 16, v57
	v_and_b32_e32 v57, 0xffff0000, v57
	v_lshlrev_b32_e32 v76, 16, v58
	v_and_b32_e32 v77, 0xffff0000, v58
	v_lshlrev_b32_e32 v58, 16, v59
	v_and_b32_e32 v59, 0xffff0000, v59
	v_pk_mul_f32 v[88:89], v[82:83], v[56:57]
	v_pk_mul_f32 v[56:57], v[80:81], v[62:63]
	v_pk_mul_f32 v[62:63], v[86:87], v[58:59]
	v_pk_mul_f32 v[58:59], v[84:85], v[76:77]
	v_cvt_pk_bf16_f32 v56, v56, v57
	v_cvt_pk_bf16_f32 v57, v88, v89
	v_cvt_pk_bf16_f32 v58, v58, v59
	v_cvt_pk_bf16_f32 v59, v62, v63
	global_store_dwordx4 v[60:61], v[56:59], off

; DI unsigned pk2(float a, float b) { f32x2 v = {a, b}; return __builtin_bit_cast(unsigned, __builtin_convertvector(v, bf16v2)); }
; DI float bf_lo(unsigned w) { return __uint_as_float(w << 16); }
; DI void fnet_layer(const Args& A, LAS unsigned char* lds, const XcdBarrier& gbar, int layer, int j, bool latonly, int wv) {
;     ...
;             bf16_t* ap = A1 + ((size_t)u.i0 * 1024 + k) * DM + col;
;             if (u.i2 < 8) { st_bf16x8(ap, v0, v1); return; }
;             f32x4 a0, a1; ld_bf16x8(ap, a0, a1);
;             const size_t off = ((size_t)u.i0 * TB + k) * DM + col;
;             f32x4 g0, g1; ld_bf16x8(Gt + off, g0, g1);
;             st_bf16x8(U + off, (a0 + v0) * g0, (a1 + v1) * g1);
;             if (k != 0) { const size_t off2 = ((size_t)u.i0 * TB + (TL - k)) * DM + col; ld_bf16x8(Gt + off2, g0, g1); st_bf16x8(U + off2, (a0 - v0) * g0, (a1 - v1) * g1); }
;             const f32x4 s0 = a0 + v0, s1 = a1 + v1, d0 = a0 - v0, d1 = a1 - v1;
;             const float sm[8] = {s0[0], s0[1], s0[2], s0[3], s1[0], s1[1], s1[2], s1[3]}, df[8] = {d0[0], d0[1], d0[2], d0[3], d1[0], d1[1], d1[2], d1[3]};
;             const size_t rowk = ((size_t)u.i0 * TB + k) * DM, rowT = ((size_t)u.i0 * TB + (TL - k)) * DM; const int cm = (col & ~255) + 512 - col_l;
;             {
;                 const bf16_t* gk_ = Gt + rowk + cm - 8; const bf16_t* gT_ = Gt + rowT + cm - 8; bf16_t* uk_ = U + rowk + cm - 8; bf16_t* uT_ = U + rowT + cm - 8;
;                 const unsigned short ka1 = gk_[1]; const unsigned ka2 = *(const unsigned*)(gk_ + 2); const u32x2 ka4 = *(const u32x2*)(gk_ + 4); const unsigned short ka0 = col_l ? gk_[8] : (unsigned short)0;
;                 unsigned short ta1 = 0, ta0 = 0; unsigned ta2 = 0; u32x2 ta4 = {0u, 0u};
;                 if (k != 0) { ta1 = gT_[1]; ta2 = *(const unsigned*)(gT_ + 2); ta4 = *(const u32x2*)(gT_ + 4); ta0 = col_l ? gT_[8] : (unsigned short)0; }
;                 uk_[1] = (bf16_t)(pk2(df[7] * __uint_as_float((unsigned)ka1 << 16), 0.f) & 0xffffu);
;                 *(unsigned*)(uk_ + 2) = pk2(df[6] * bf_lo(ka2), df[5] * bf_hi(ka2));
;                 *(u32x2*)(uk_ + 4) = (u32x2){pk2(df[4] * bf_lo(ka4.x), df[3] * bf_hi(ka4.x)), pk2(df[2] * bf_lo(ka4.y), df[1] * bf_hi(ka4.y))};
;                 if (col_l) uk_[8] = (bf16_t)(pk2(df[0] * __uint_as_float((unsigned)ka0 << 16), 0.f) & 0xffffu);
.LBB0_2593:
	v_add_u32_e32 v48, 0x90, v150
	v_ashrrev_i32_e32 v49, 31, v48
	v_lshlrev_b64 v[50:51], 12, v[48:49]
	v_lshl_add_u64 v[48:49], s[40:41], 0, v[48:49]
	v_lshlrev_b64 v[56:57], 11, v[48:49]
	v_sub_u32_e32 v48, 0x770, v150
	v_ashrrev_i32_e32 v49, 31, v48
	v_lshl_add_u64 v[48:49], s[40:41], 0, v[48:49]
	v_lshl_add_u64 v[60:61], s[42:43], 0, v[50:51]
	v_mov_b32_e32 v153, v145
	v_lshlrev_b64 v[58:59], 11, v[48:49]
	v_lshl_add_u64 v[62:63], v[60:61], 0, v[152:153]
	s_and_b64 vcc, exec, s[4:5]
	s_mov_b64 s[6:7], -1
	s_cbranch_vccnz .LBB0_2603
	v_or_b32_e32 v52, v56, v189
	v_mov_b32_e32 v53, v57
	v_lshlrev_b64 v[64:65], 1, v[52:53]
	v_subrev_u32_e32 v248, s98, v62
	v_and_b32_e32 v249, 0xfffff000, v248
	v_and_b32_e32 v250, 0xfff, v248
	v_sub_u32_e32 v251, v250, v249
	v_add_u32_e32 v251, 0x800000, v251
	global_load_dwordx4 v[252:255], v251, s[100:101]
	global_load_dwordx4 v[48:51], v[62:63], off
	v_lshl_add_u64 v[52:53], s[44:45], 0, v[64:65]
	global_load_dwordx4 v[52:55], v[52:53], off
	v_or_b32_e32 v66, v58, v189
	v_mov_b32_e32 v67, v59
	v_lshlrev_b64 v[72:73], 1, v[66:67]
	v_lshl_add_u64 v[74:75], s[36:37], 0, v[64:65]
	v_lshl_add_u64 v[76:77], s[44:45], 0, v[72:73]
	v_lshl_add_u64 v[86:87], s[36:37], 0, v[72:73]
	v_cmp_ne_u32_e32 vcc, 0, v151
	s_waitcnt vmcnt(0)
	v_lshlrev_b32_e32 v78, 16, v48
	v_and_b32_e32 v79, 0xffff0000, v48
	v_lshlrev_b32_e32 v80, 16, v49
	v_and_b32_e32 v81, 0xffff0000, v49
	v_lshlrev_b32_e32 v82, 16, v50
	v_and_b32_e32 v83, 0xffff0000, v50
	v_lshlrev_b32_e32 v84, 16, v51
	v_and_b32_e32 v85, 0xffff0000, v51
	v_pk_add_f32 v[66:67], v[46:47], v[80:81]
	v_pk_add_f32 v[64:65], v[44:45], v[78:79]
	v_pk_add_f32 v[70:71], v[42:43], v[84:85]
	v_pk_add_f32 v[68:69], v[40:41], v[82:83]
	v_lshlrev_b32_e32 v48, 16, v52
	v_and_b32_e32 v49, 0xffff0000, v52
	v_lshlrev_b32_e32 v50, 16, v53
	v_and_b32_e32 v51, 0xffff0000, v53
	v_lshlrev_b32_e32 v52, 16, v54
	v_and_b32_e32 v53, 0xffff0000, v54
	v_lshlrev_b32_e32 v54, 16, v55
	v_and_b32_e32 v55, 0xffff0000, v55
	v_pk_mul_f32 v[50:51], v[66:67], v[50:51]
	v_pk_mul_f32 v[48:49], v[64:65], v[48:49]
	v_pk_mul_f32 v[54:55], v[70:71], v[54:55]
	v_pk_mul_f32 v[52:53], v[68:69], v[52:53]
	v_cvt_pk_bf16_f32 v48, v48, v49
	v_cvt_pk_bf16_f32 v49, v50, v51
	v_cvt_pk_bf16_f32 v50, v52, v53
	v_cvt_pk_bf16_f32 v51, v54, v55
	global_store_dwordx4 v[74:75], v[48:51], off
	v_sub_f32_e32 v74, v80, v46
	v_sub_f32_e32 v77, v81, v47
	v_sub_f32_e32 v72, v78, v44
	v_sub_f32_e32 v51, v85, v43
	v_sub_f32_e32 v78, v84, v42
	v_mov_b32_e32 v76, v74
	v_sub_f32_e32 v75, v79, v45
	v_sub_f32_e32 v79, v83, v41
	v_mov_b32_e32 v73, v75
	v_mov_b32_e32 v50, v78
	v_mov_b32_e32 v81, v79
	v_lshl_add_u64 v[48:49], v[56:57], 1, s[44:45]
	v_lshl_add_u64 v[48:49], v[48:49], 0, v[144:145]
	v_mov_b32_e32 v52, v252
	v_mov_b32_e32 v53, v253
	v_mov_b32_e32 v54, v254
	v_mov_b32_e32 v55, v255
	v_lshlrev_b32_e32 v84, 16, v52
	v_and_b32_e32 v85, 0xffff0000, v52
	v_lshlrev_b32_e32 v52, 16, v53
	v_and_b32_e32 v53, 0xffff0000, v53
	v_pk_mul_f32 v[90:91], v[76:77], v[52:53]
	v_sub_f32_e32 v76, v82, v40
	v_lshlrev_b32_e32 v88, 16, v54
	v_and_b32_e32 v89, 0xffff0000, v54
	v_lshlrev_b32_e32 v54, 16, v55
	v_and_b32_e32 v55, 0xffff0000, v55
	v_mov_b32_e32 v80, v76
	v_pk_mul_f32 v[52:53], v[72:73], v[84:85]
	v_pk_mul_f32 v[54:55], v[50:51], v[54:55]
	v_pk_mul_f32 v[80:81], v[80:81], v[88:89]
	v_cvt_pk_bf16_f32 v52, v52, v53
	v_cvt_pk_bf16_f32 v53, v90, v91
	v_cvt_pk_bf16_f32 v55, v54, v55
	v_cvt_pk_bf16_f32 v54, v80, v81
	global_store_dwordx4 v[86:87], v[52:55], off
	global_load_ushort v83, v[48:49], off offset:-14
	s_nop 0
	global_load_dwordx3 v[52:54], v[48:49], off offset:-12
	v_mov_b32_e32 v55, 0
	v_mov_b32_e32 v73, 0
	s_and_saveexec_b64 s[6:7], vcc
	s_cbranch_execz .LBB0_2596
	global_load_ushort v48, v[48:49], off
	s_waitcnt vmcnt(0)
	v_lshlrev_b32_e32 v73, 16, v48

; DI void fnet_layer(const Args& A, LAS unsigned char* lds, const XcdBarrier& gbar, int layer, int j, bool latonly, int wv) {
;     ...
;             bf16_t* ap = A1 + ((size_t)u.i0 * 1024 + k) * DM + col;
;             if (u.i2 < 8) { st_bf16x8(ap, v0, v1); return; }
;             f32x4 a0, a1; ld_bf16x8(ap, a0, a1);
;             const size_t off = ((size_t)u.i0 * TB + k) * DM + col;
;             f32x4 g0, g1; ld_bf16x8(Gt + off, g0, g1);
;             st_bf16x8(U + off, (a0 + v0) * g0, (a1 + v1) * g1);
;             if (k != 0) { const size_t off2 = ((size_t)u.i0 * TB + (TL - k)) * DM + col; ld_bf16x8(Gt + off2, g0, g1); st_bf16x8(U + off2, (a0 - v0) * g0, (a1 - v1) * g1); }
;             const f32x4 s0 = a0 + v0, s1 = a1 + v1, d0 = a0 - v0, d1 = a1 - v1;
;             const float sm[8] = {s0[0], s0[1], s0[2], s0[3], s1[0], s1[1], s1[2], s1[3]}, df[8] = {d0[0], d0[1], d0[2], d0[3], d1[0], d1[1], d1[2], d1[3]};
;             const size_t rowk = ((size_t)u.i0 * TB + k) * DM, rowT = ((size_t)u.i0 * TB + (TL - k)) * DM; const int cm = (col & ~255) + 512 - col_l;
;             {
;                 const bf16_t* gk_ = Gt + rowk + cm - 8; const bf16_t* gT_ = Gt + rowT + cm - 8; bf16_t* uk_ = U + rowk + cm - 8; bf16_t* uT_ = U + rowT + cm - 8;
;                 const unsigned short ka1 = gk_[1]; const unsigned ka2 = *(const unsigned*)(gk_ + 2); const u32x2 ka4 = *(const u32x2*)(gk_ + 4); const unsigned short ka0 = col_l ? gk_[8] : (unsigned short)0;
;                 unsigned short ta1 = 0, ta0 = 0; unsigned ta2 = 0; u32x2 ta4 = {0u, 0u};
;                 if (k != 0) { ta1 = gT_[1]; ta2 = *(const unsigned*)(gT_ + 2); ta4 = *(const u32x2*)(gT_ + 4); ta0 = col_l ? gT_[8] : (unsigned short)0; }
;                 uk_[1] = (bf16_t)(pk2(df[7] * __uint_as_float((unsigned)ka1 << 16), 0.f) & 0xffffu);
;                 *(unsigned*)(uk_ + 2) = pk2(df[6] * bf_lo(ka2), df[5] * bf_hi(ka2));
;                 *(u32x2*)(uk_ + 4) = (u32x2){pk2(df[4] * bf_lo(ka4.x), df[3] * bf_hi(ka4.x)), pk2(df[2] * bf_lo(ka4.y), df[1] * bf_hi(ka4.y))};
;                 if (col_l) uk_[8] = (bf16_t)(pk2(df[0] * __uint_as_float((unsigned)ka0 << 16), 0.f) & 0xffffu);
;                 if (k != 0) {
;                     uT_[1] = (bf16_t)(pk2(sm[7] * __uint_as_float((unsigned)ta1 << 16), 0.f) & 0xffffu);
;                     *(unsigned*)(uT_ + 2) = pk2(sm[6] * bf_lo(ta2), sm[5] * bf_hi(ta2));
.LBB0_2605:
	v_mov_b32_e32 v129, v145
	v_lshl_add_u64 v[40:41], v[60:61], 0, v[128:129]
	s_and_b64 vcc, exec, s[4:5]
	s_mov_b64 s[6:7], -1
	s_cbranch_vccnz .LBB0_2607
	v_or_b32_e32 v46, v56, v172
	v_mov_b32_e32 v47, v57
	v_lshlrev_b64 v[50:51], 1, v[46:47]
	v_subrev_u32_e32 v248, s98, v40
	v_add_u32_e32 v248, 256, v248
	v_and_b32_e32 v249, 0xfffff000, v248
	v_and_b32_e32 v250, 0xfff, v248
	v_sub_u32_e32 v251, v250, v249
	v_add_u32_e32 v251, 0x800000, v251
	global_load_dwordx4 v[252:255], v251, s[100:101]
	global_load_dwordx4 v[42:45], v[40:41], off offset:256
	v_lshl_add_u64 v[46:47], s[44:45], 0, v[50:51]
	global_load_dwordx4 v[46:49], v[46:47], off
	v_or_b32_e32 v52, v58, v172
	v_mov_b32_e32 v53, v59
	v_lshlrev_b64 v[52:53], 1, v[52:53]
	v_lshl_add_u64 v[50:51], s[36:37], 0, v[50:51]
	v_lshl_add_u64 v[54:55], s[44:45], 0, v[52:53]
	v_mov_b32_e32 v105, v145
	v_lshl_add_u64 v[52:53], s[36:37], 0, v[52:53]
	s_mov_b64 s[6:7], 0
	s_waitcnt vmcnt(0)
	v_lshlrev_b32_e32 v60, 16, v42
	v_and_b32_e32 v61, 0xffff0000, v42
	v_lshlrev_b32_e32 v62, 16, v43
	v_and_b32_e32 v63, 0xffff0000, v43
	v_lshlrev_b32_e32 v64, 16, v44
	v_and_b32_e32 v65, 0xffff0000, v44
	v_lshlrev_b32_e32 v66, 16, v45
	v_and_b32_e32 v67, 0xffff0000, v45
	v_pk_add_f32 v[68:69], v[36:37], v[60:61]
	v_pk_add_f32 v[70:71], v[38:39], v[62:63]
	v_pk_add_f32 v[72:73], v[32:33], v[64:65]
	v_pk_add_f32 v[74:75], v[34:35], v[66:67]
	v_lshlrev_b32_e32 v42, 16, v46
	v_and_b32_e32 v43, 0xffff0000, v46
	v_lshlrev_b32_e32 v44, 16, v47
	v_and_b32_e32 v45, 0xffff0000, v47
	v_lshlrev_b32_e32 v46, 16, v48
	v_and_b32_e32 v47, 0xffff0000, v48
	v_lshlrev_b32_e32 v48, 16, v49
	v_and_b32_e32 v49, 0xffff0000, v49
	v_pk_mul_f32 v[44:45], v[70:71], v[44:45]
	v_pk_mul_f32 v[42:43], v[68:69], v[42:43]
	v_pk_mul_f32 v[48:49], v[74:75], v[48:49]
	v_pk_mul_f32 v[46:47], v[72:73], v[46:47]
	v_cvt_pk_bf16_f32 v42, v42, v43
	v_cvt_pk_bf16_f32 v43, v44, v45
	v_cvt_pk_bf16_f32 v44, v46, v47
	v_cvt_pk_bf16_f32 v45, v48, v49
	global_store_dwordx4 v[50:51], v[42:45], off
	v_lshlrev_b64 v[50:51], 1, v[56:57]
	v_lshlrev_b64 v[54:55], 1, v[58:59]
	v_sub_f32_e32 v57, v61, v37
	v_sub_f32_e32 v56, v60, v36
	v_sub_f32_e32 v59, v63, v39
	v_sub_f32_e32 v58, v62, v38
	v_sub_f32_e32 v61, v65, v33
	v_sub_f32_e32 v60, v64, v32
	v_sub_f32_e32 v63, v67, v35
	v_sub_f32_e32 v62, v66, v34
	v_lshl_add_u64 v[46:47], s[44:45], 0, v[50:51]
	v_lshl_add_u64 v[48:49], s[44:45], 0, v[54:55]
	v_lshl_add_u64 v[46:47], v[46:47], 0, v[104:105]
	v_lshl_add_u64 v[48:49], v[48:49], 0, v[104:105]
	v_lshl_add_u64 v[50:51], s[36:37], 0, v[50:51]
	v_lshl_add_u64 v[50:51], v[50:51], 0, v[104:105]
	v_mov_b32_e32 v42, v252
	v_mov_b32_e32 v43, v253
	v_mov_b32_e32 v44, v254
	v_mov_b32_e32 v45, v255
	v_lshlrev_b32_e32 v64, 16, v42
	v_and_b32_e32 v65, 0xffff0000, v42
	v_lshlrev_b32_e32 v42, 16, v43
	v_and_b32_e32 v43, 0xffff0000, v43
	v_lshlrev_b32_e32 v66, 16, v44
	v_and_b32_e32 v67, 0xffff0000, v44
	v_lshlrev_b32_e32 v44, 16, v45
	v_and_b32_e32 v45, 0xffff0000, v45
	v_pk_mul_f32 v[76:77], v[58:59], v[42:43]
	v_pk_mul_f32 v[42:43], v[56:57], v[64:65]
	v_pk_mul_f32 v[64:65], v[62:63], v[44:45]
	v_pk_mul_f32 v[44:45], v[60:61], v[66:67]
	v_cvt_pk_bf16_f32 v42, v42, v43
	v_cvt_pk_bf16_f32 v43, v76, v77
	v_cvt_pk_bf16_f32 v44, v44, v45
	v_cvt_pk_bf16_f32 v45, v64, v65
	global_store_dwordx4 v[52:53], v[42:45], off
	global_load_ushort v45, v[46:47], off
	s_nop 0
	global_load_ushort v64, v[48:49], off
	global_load_ushort v65, v[48:49], off offset:-14
	global_load_ushort v66, v[46:47], off offset:-14
	global_load_dwordx3 v[42:44], v[46:47], off offset:-12
	s_nop 0
	global_load_dwordx3 v[46:48], v[48:49], off offset:-12
	v_lshl_add_u64 v[52:53], s[36:37], 0, v[54:55]
	v_lshl_add_u64 v[52:53], v[52:53], 0, v[104:105]
	s_waitcnt vmcnt(5)
	v_lshlrev_b32_e32 v49, 16, v45
	s_waitcnt vmcnt(4)
	v_lshlrev_b32_e32 v76, 16, v64
	s_waitcnt vmcnt(3)
	v_lshlrev_b32_e32 v77, 16, v65
	s_waitcnt vmcnt(2)
	v_lshlrev_b32_e32 v78, 16, v66
	s_waitcnt vmcnt(1)
	v_lshlrev_b32_e32 v54, 16, v42
	v_and_b32_e32 v55, 0xffff0000, v42
	v_lshlrev_b32_e32 v42, 16, v43
	v_and_b32_e32 v43, 0xffff0000, v43
	v_lshlrev_b32_e32 v64, 16, v44
	v_and_b32_e32 v65, 0xffff0000, v44
	s_waitcnt vmcnt(0)
	v_lshlrev_b32_e32 v44, 16, v46
	v_and_b32_e32 v45, 0xffff0000, v46
	v_lshlrev_b32_e32 v66, 16, v48
	v_and_b32_e32 v67, 0xffff0000, v48
	v_mul_f32_e32 v48, v63, v78
	v_mov_b32_e32 v63, v61
	v_mov_b32_e32 v61, v59
	v_mov_b32_e32 v59, v57
	v_mul_f32_e32 v57, v75, v77
	v_mov_b32_e32 v75, v73
	v_lshlrev_b32_e32 v46, 16, v47
	v_and_b32_e32 v47, 0xffff0000, v47
	v_mul_f32_e32 v56, v56, v49
	v_mov_b32_e32 v73, v71
	v_mov_b32_e32 v71, v69
	v_mul_f32_e32 v68, v68, v76
	v_cvt_pk_bf16_f32 v69, v48, s0
	v_pk_mul_f32 v[48:49], v[62:63], v[54:55]
	v_pk_mul_f32 v[42:43], v[60:61], v[42:43]
	v_pk_mul_f32 v[44:45], v[74:75], v[44:45]
	v_pk_mul_f32 v[54:55], v[58:59], v[64:65]
	v_cvt_pk_bf16_f32 v58, v56, s0
	v_cvt_pk_bf16_f32 v59, v57, s0
	v_pk_mul_f32 v[46:47], v[72:73], v[46:47]
	v_pk_mul_f32 v[56:57], v[70:71], v[66:67]
	v_cvt_pk_bf16_f32 v60, v68, s0
	v_cvt_pk_bf16_f32 v48, v48, v49
	v_cvt_pk_bf16_f32 v42, v42, v43
	v_cvt_pk_bf16_f32 v49, v44, v45
	v_cvt_pk_bf16_f32 v43, v54, v55
	global_store_short v[50:51], v58, off
	v_cvt_pk_bf16_f32 v44, v46, v47
	v_cvt_pk_bf16_f32 v45, v56, v57
	global_store_short v[52:53], v60, off
	v_perm_b32 v46, v48, v69, s60
	global_store_short_d16_hi v[50:51], v48, off offset:-10
	global_store_dwordx2 v[50:51], v[42:43], off offset:-8
	v_perm_b32 v42, v49, v59, s60
	global_store_short_d16_hi v[52:53], v49, off offset:-10
	global_store_dwordx2 v[52:53], v[44:45], off offset:-8
	global_store_dword v[50:51], v46, off offset:-14
	global_store_dword v[52:53], v42, off offset:-14

; DI unsigned pk2(float a, float b) { f32x2 v = {a, b}; return __builtin_bit_cast(unsigned, __builtin_convertvector(v, bf16v2)); }
; DI float bf_lo(unsigned w) { return __uint_as_float(w << 16); }
; DI void fnet_layer(const Args& A, LAS unsigned char* lds, const XcdBarrier& gbar, int layer, int j, bool latonly, int wv) {
;     ...
;             bf16_t* ap = A1 + ((size_t)u.i0 * 1024 + k) * DM + col;
;             if (u.i2 < 8) { st_bf16x8(ap, v0, v1); return; }
;             f32x4 a0, a1; ld_bf16x8(ap, a0, a1);
;             const size_t off = ((size_t)u.i0 * TB + k) * DM + col;
;             f32x4 g0, g1; ld_bf16x8(Gt + off, g0, g1);
;             st_bf16x8(U + off, (a0 + v0) * g0, (a1 + v1) * g1);
;             if (k != 0) { const size_t off2 = ((size_t)u.i0 * TB + (TL - k)) * DM + col; ld_bf16x8(Gt + off2, g0, g1); st_bf16x8(U + off2, (a0 - v0) * g0, (a1 - v1) * g1); }
;             const f32x4 s0 = a0 + v0, s1 = a1 + v1, d0 = a0 - v0, d1 = a1 - v1;
;             const float sm[8] = {s0[0], s0[1], s0[2], s0[3], s1[0], s1[1], s1[2], s1[3]}, df[8] = {d0[0], d0[1], d0[2], d0[3], d1[0], d1[1], d1[2], d1[3]};
;             const size_t rowk = ((size_t)u.i0 * TB + k) * DM, rowT = ((size_t)u.i0 * TB + (TL - k)) * DM; const int cm = (col & ~255) + 512 - col_l;
;             {
;                 const bf16_t* gk_ = Gt + rowk + cm - 8; const bf16_t* gT_ = Gt + rowT + cm - 8; bf16_t* uk_ = U + rowk + cm - 8; bf16_t* uT_ = U + rowT + cm - 8;
;                 const unsigned short ka1 = gk_[1]; const unsigned ka2 = *(const unsigned*)(gk_ + 2); const u32x2 ka4 = *(const u32x2*)(gk_ + 4); const unsigned short ka0 = col_l ? gk_[8] : (unsigned short)0;
;                 unsigned short ta1 = 0, ta0 = 0; unsigned ta2 = 0; u32x2 ta4 = {0u, 0u};
;                 if (k != 0) { ta1 = gT_[1]; ta2 = *(const unsigned*)(gT_ + 2); ta4 = *(const u32x2*)(gT_ + 4); ta0 = col_l ? gT_[8] : (unsigned short)0; }
;                 uk_[1] = (bf16_t)(pk2(df[7] * __uint_as_float((unsigned)ka1 << 16), 0.f) & 0xffffu);
;                 *(unsigned*)(uk_ + 2) = pk2(df[6] * bf_lo(ka2), df[5] * bf_hi(ka2));
;                 *(u32x2*)(uk_ + 4) = (u32x2){pk2(df[4] * bf_lo(ka4.x), df[3] * bf_hi(ka4.x)), pk2(df[2] * bf_lo(ka4.y), df[1] * bf_hi(ka4.y))};
;                 if (col_l) uk_[8] = (bf16_t)(pk2(df[0] * __uint_as_float((unsigned)ka0 << 16), 0.f) & 0xffffu);
.LBB0_2609:
	v_add_u32_e32 v32, 0xa0, v150
	v_ashrrev_i32_e32 v33, 31, v32
	v_lshlrev_b64 v[34:35], 12, v[32:33]
	v_lshl_add_u64 v[32:33], s[40:41], 0, v[32:33]
	v_lshlrev_b64 v[40:41], 11, v[32:33]
	v_sub_u32_e32 v32, 0x760, v150
	v_ashrrev_i32_e32 v33, 31, v32
	v_lshl_add_u64 v[32:33], s[40:41], 0, v[32:33]
	v_lshl_add_u64 v[44:45], s[42:43], 0, v[34:35]
	v_mov_b32_e32 v153, v145
	v_lshlrev_b64 v[42:43], 11, v[32:33]
	v_lshl_add_u64 v[46:47], v[44:45], 0, v[152:153]
	s_and_b64 vcc, exec, s[4:5]
	s_mov_b64 s[6:7], -1
	s_cbranch_vccnz .LBB0_2619
	v_or_b32_e32 v36, v40, v189
	v_mov_b32_e32 v37, v41
	v_lshlrev_b64 v[48:49], 1, v[36:37]
	v_subrev_u32_e32 v248, s98, v46
	v_and_b32_e32 v249, 0xfffff000, v248
	v_and_b32_e32 v250, 0xfff, v248
	v_sub_u32_e32 v251, v250, v249
	v_add_u32_e32 v251, 0x800000, v251
	global_load_dwordx4 v[252:255], v251, s[100:101]
	global_load_dwordx4 v[32:35], v[46:47], off
	v_lshl_add_u64 v[36:37], s[44:45], 0, v[48:49]
	global_load_dwordx4 v[36:39], v[36:37], off
	v_or_b32_e32 v50, v42, v189
	v_mov_b32_e32 v51, v43
	v_lshlrev_b64 v[56:57], 1, v[50:51]
	v_lshl_add_u64 v[58:59], s[36:37], 0, v[48:49]
	v_lshl_add_u64 v[60:61], s[44:45], 0, v[56:57]
	v_lshl_add_u64 v[70:71], s[36:37], 0, v[56:57]
	v_cmp_ne_u32_e32 vcc, 0, v151
	s_waitcnt vmcnt(0)
	v_lshlrev_b32_e32 v62, 16, v32
	v_and_b32_e32 v63, 0xffff0000, v32
	v_lshlrev_b32_e32 v64, 16, v33
	v_and_b32_e32 v65, 0xffff0000, v33
	v_lshlrev_b32_e32 v66, 16, v34
	v_and_b32_e32 v67, 0xffff0000, v34
	v_lshlrev_b32_e32 v68, 16, v35
	v_and_b32_e32 v69, 0xffff0000, v35
	v_pk_add_f32 v[50:51], v[30:31], v[64:65]
	v_pk_add_f32 v[48:49], v[28:29], v[62:63]
	v_pk_add_f32 v[54:55], v[26:27], v[68:69]
	v_pk_add_f32 v[52:53], v[24:25], v[66:67]
	v_lshlrev_b32_e32 v32, 16, v36
	v_and_b32_e32 v33, 0xffff0000, v36
	v_lshlrev_b32_e32 v34, 16, v37
	v_and_b32_e32 v35, 0xffff0000, v37
	v_lshlrev_b32_e32 v36, 16, v38
	v_and_b32_e32 v37, 0xffff0000, v38
	v_lshlrev_b32_e32 v38, 16, v39
	v_and_b32_e32 v39, 0xffff0000, v39
	v_pk_mul_f32 v[34:35], v[50:51], v[34:35]
	v_pk_mul_f32 v[32:33], v[48:49], v[32:33]
	v_pk_mul_f32 v[38:39], v[54:55], v[38:39]
	v_pk_mul_f32 v[36:37], v[52:53], v[36:37]
	v_cvt_pk_bf16_f32 v32, v32, v33
	v_cvt_pk_bf16_f32 v33, v34, v35
	v_cvt_pk_bf16_f32 v34, v36, v37
	v_cvt_pk_bf16_f32 v35, v38, v39
	global_store_dwordx4 v[58:59], v[32:35], off
	v_sub_f32_e32 v58, v64, v30
	v_sub_f32_e32 v61, v65, v31
	v_sub_f32_e32 v56, v62, v28
	v_sub_f32_e32 v35, v69, v27
	v_sub_f32_e32 v62, v68, v26
	v_mov_b32_e32 v60, v58
	v_sub_f32_e32 v59, v63, v29
	v_sub_f32_e32 v63, v67, v25
	v_mov_b32_e32 v57, v59
	v_mov_b32_e32 v34, v62
	v_mov_b32_e32 v65, v63
	v_lshl_add_u64 v[32:33], v[40:41], 1, s[44:45]
	v_lshl_add_u64 v[32:33], v[32:33], 0, v[144:145]
	v_mov_b32_e32 v36, v252
	v_mov_b32_e32 v37, v253
	v_mov_b32_e32 v38, v254
	v_mov_b32_e32 v39, v255
	v_lshlrev_b32_e32 v68, 16, v36
	v_and_b32_e32 v69, 0xffff0000, v36
	v_lshlrev_b32_e32 v36, 16, v37
	v_and_b32_e32 v37, 0xffff0000, v37
	v_pk_mul_f32 v[74:75], v[60:61], v[36:37]
	v_sub_f32_e32 v60, v66, v24
	v_lshlrev_b32_e32 v72, 16, v38
	v_and_b32_e32 v73, 0xffff0000, v38
	v_lshlrev_b32_e32 v38, 16, v39
	v_and_b32_e32 v39, 0xffff0000, v39
	v_mov_b32_e32 v64, v60
	v_pk_mul_f32 v[36:37], v[56:57], v[68:69]
	v_pk_mul_f32 v[38:39], v[34:35], v[38:39]
	v_pk_mul_f32 v[64:65], v[64:65], v[72:73]
	v_cvt_pk_bf16_f32 v36, v36, v37
	v_cvt_pk_bf16_f32 v37, v74, v75
	v_cvt_pk_bf16_f32 v39, v38, v39
	v_cvt_pk_bf16_f32 v38, v64, v65
	global_store_dwordx4 v[70:71], v[36:39], off
	global_load_ushort v67, v[32:33], off offset:-14
	s_nop 0
	global_load_dwordx3 v[36:38], v[32:33], off offset:-12
	v_mov_b32_e32 v39, 0
	v_mov_b32_e32 v57, 0
	s_and_saveexec_b64 s[6:7], vcc
	s_cbranch_execz .LBB0_2612
	global_load_ushort v32, v[32:33], off
	s_waitcnt vmcnt(0)
	v_lshlrev_b32_e32 v57, 16, v32

; DI void fnet_layer(const Args& A, LAS unsigned char* lds, const XcdBarrier& gbar, int layer, int j, bool latonly, int wv) {
;     ...
;             bf16_t* ap = A1 + ((size_t)u.i0 * 1024 + k) * DM + col;
;             if (u.i2 < 8) { st_bf16x8(ap, v0, v1); return; }
;             f32x4 a0, a1; ld_bf16x8(ap, a0, a1);
;             const size_t off = ((size_t)u.i0 * TB + k) * DM + col;
;             f32x4 g0, g1; ld_bf16x8(Gt + off, g0, g1);
;             st_bf16x8(U + off, (a0 + v0) * g0, (a1 + v1) * g1);
;             if (k != 0) { const size_t off2 = ((size_t)u.i0 * TB + (TL - k)) * DM + col; ld_bf16x8(Gt + off2, g0, g1); st_bf16x8(U + off2, (a0 - v0) * g0, (a1 - v1) * g1); }
;             const f32x4 s0 = a0 + v0, s1 = a1 + v1, d0 = a0 - v0, d1 = a1 - v1;
;             const float sm[8] = {s0[0], s0[1], s0[2], s0[3], s1[0], s1[1], s1[2], s1[3]}, df[8] = {d0[0], d0[1], d0[2], d0[3], d1[0], d1[1], d1[2], d1[3]};
;             const size_t rowk = ((size_t)u.i0 * TB + k) * DM, rowT = ((size_t)u.i0 * TB + (TL - k)) * DM; const int cm = (col & ~255) + 512 - col_l;
;             {
;                 const bf16_t* gk_ = Gt + rowk + cm - 8; const bf16_t* gT_ = Gt + rowT + cm - 8; bf16_t* uk_ = U + rowk + cm - 8; bf16_t* uT_ = U + rowT + cm - 8;
;                 const unsigned short ka1 = gk_[1]; const unsigned ka2 = *(const unsigned*)(gk_ + 2); const u32x2 ka4 = *(const u32x2*)(gk_ + 4); const unsigned short ka0 = col_l ? gk_[8] : (unsigned short)0;
;                 unsigned short ta1 = 0, ta0 = 0; unsigned ta2 = 0; u32x2 ta4 = {0u, 0u};
;                 if (k != 0) { ta1 = gT_[1]; ta2 = *(const unsigned*)(gT_ + 2); ta4 = *(const u32x2*)(gT_ + 4); ta0 = col_l ? gT_[8] : (unsigned short)0; }
;                 uk_[1] = (bf16_t)(pk2(df[7] * __uint_as_float((unsigned)ka1 << 16), 0.f) & 0xffffu);
;                 *(unsigned*)(uk_ + 2) = pk2(df[6] * bf_lo(ka2), df[5] * bf_hi(ka2));
;                 *(u32x2*)(uk_ + 4) = (u32x2){pk2(df[4] * bf_lo(ka4.x), df[3] * bf_hi(ka4.x)), pk2(df[2] * bf_lo(ka4.y), df[1] * bf_hi(ka4.y))};
;                 if (col_l) uk_[8] = (bf16_t)(pk2(df[0] * __uint_as_float((unsigned)ka0 << 16), 0.f) & 0xffffu);
;                 if (k != 0) {
;                     uT_[1] = (bf16_t)(pk2(sm[7] * __uint_as_float((unsigned)ta1 << 16), 0.f) & 0xffffu);
;                     *(unsigned*)(uT_ + 2) = pk2(sm[6] * bf_lo(ta2), sm[5] * bf_hi(ta2));
.LBB0_2621:
	v_mov_b32_e32 v129, v145
	v_lshl_add_u64 v[24:25], v[44:45], 0, v[128:129]
	s_and_b64 vcc, exec, s[4:5]
	s_mov_b64 s[6:7], -1
	s_cbranch_vccnz .LBB0_2623
	v_or_b32_e32 v30, v40, v172
	v_mov_b32_e32 v31, v41
	v_lshlrev_b64 v[34:35], 1, v[30:31]
	v_subrev_u32_e32 v248, s98, v24
	v_add_u32_e32 v248, 256, v248
	v_and_b32_e32 v249, 0xfffff000, v248
	v_and_b32_e32 v250, 0xfff, v248
	v_sub_u32_e32 v251, v250, v249
	v_add_u32_e32 v251, 0x800000, v251
	global_load_dwordx4 v[252:255], v251, s[100:101]
	global_load_dwordx4 v[26:29], v[24:25], off offset:256
	v_lshl_add_u64 v[30:31], s[44:45], 0, v[34:35]
	global_load_dwordx4 v[30:33], v[30:31], off
	v_or_b32_e32 v36, v42, v172
	v_mov_b32_e32 v37, v43
	v_lshlrev_b64 v[36:37], 1, v[36:37]
	v_lshl_add_u64 v[34:35], s[36:37], 0, v[34:35]
	v_lshl_add_u64 v[38:39], s[44:45], 0, v[36:37]
	v_mov_b32_e32 v105, v145
	v_lshl_add_u64 v[36:37], s[36:37], 0, v[36:37]
	s_mov_b64 s[6:7], 0
	s_waitcnt vmcnt(0)
	v_lshlrev_b32_e32 v44, 16, v26
	v_and_b32_e32 v45, 0xffff0000, v26
	v_lshlrev_b32_e32 v46, 16, v27
	v_and_b32_e32 v47, 0xffff0000, v27
	v_lshlrev_b32_e32 v48, 16, v28
	v_and_b32_e32 v49, 0xffff0000, v28
	v_lshlrev_b32_e32 v50, 16, v29
	v_and_b32_e32 v51, 0xffff0000, v29
	v_pk_add_f32 v[52:53], v[20:21], v[44:45]
	v_pk_add_f32 v[54:55], v[22:23], v[46:47]
	v_pk_add_f32 v[56:57], v[16:17], v[48:49]
	v_pk_add_f32 v[58:59], v[18:19], v[50:51]
	v_lshlrev_b32_e32 v26, 16, v30
	v_and_b32_e32 v27, 0xffff0000, v30
	v_lshlrev_b32_e32 v28, 16, v31
	v_and_b32_e32 v29, 0xffff0000, v31
	v_lshlrev_b32_e32 v30, 16, v32
	v_and_b32_e32 v31, 0xffff0000, v32
	v_lshlrev_b32_e32 v32, 16, v33
	v_and_b32_e32 v33, 0xffff0000, v33
	v_pk_mul_f32 v[28:29], v[54:55], v[28:29]
	v_pk_mul_f32 v[26:27], v[52:53], v[26:27]
	v_pk_mul_f32 v[32:33], v[58:59], v[32:33]
	v_pk_mul_f32 v[30:31], v[56:57], v[30:31]
	v_cvt_pk_bf16_f32 v26, v26, v27
	v_cvt_pk_bf16_f32 v27, v28, v29
	v_cvt_pk_bf16_f32 v28, v30, v31
	v_cvt_pk_bf16_f32 v29, v32, v33
	global_store_dwordx4 v[34:35], v[26:29], off
	v_lshlrev_b64 v[34:35], 1, v[40:41]
	v_lshlrev_b64 v[38:39], 1, v[42:43]
	v_sub_f32_e32 v41, v45, v21
	v_sub_f32_e32 v40, v44, v20
	v_sub_f32_e32 v43, v47, v23
	v_sub_f32_e32 v42, v46, v22
	v_sub_f32_e32 v45, v49, v17
	v_sub_f32_e32 v44, v48, v16
	v_sub_f32_e32 v47, v51, v19
	v_sub_f32_e32 v46, v50, v18
	v_lshl_add_u64 v[30:31], s[44:45], 0, v[34:35]
	v_lshl_add_u64 v[32:33], s[44:45], 0, v[38:39]
	v_lshl_add_u64 v[30:31], v[30:31], 0, v[104:105]
	v_lshl_add_u64 v[32:33], v[32:33], 0, v[104:105]
	v_lshl_add_u64 v[34:35], s[36:37], 0, v[34:35]
	v_lshl_add_u64 v[34:35], v[34:35], 0, v[104:105]
	v_mov_b32_e32 v26, v252
	v_mov_b32_e32 v27, v253
	v_mov_b32_e32 v28, v254
	v_mov_b32_e32 v29, v255
	v_lshlrev_b32_e32 v48, 16, v26
	v_and_b32_e32 v49, 0xffff0000, v26
	v_lshlrev_b32_e32 v26, 16, v27
	v_and_b32_e32 v27, 0xffff0000, v27
	v_lshlrev_b32_e32 v50, 16, v28
	v_and_b32_e32 v51, 0xffff0000, v28
	v_lshlrev_b32_e32 v28, 16, v29
	v_and_b32_e32 v29, 0xffff0000, v29
	v_pk_mul_f32 v[60:61], v[42:43], v[26:27]
	v_pk_mul_f32 v[26:27], v[40:41], v[48:49]
	v_pk_mul_f32 v[48:49], v[46:47], v[28:29]
	v_pk_mul_f32 v[28:29], v[44:45], v[50:51]
	v_cvt_pk_bf16_f32 v26, v26, v27
	v_cvt_pk_bf16_f32 v27, v60, v61
	v_cvt_pk_bf16_f32 v28, v28, v29
	v_cvt_pk_bf16_f32 v29, v48, v49
	global_store_dwordx4 v[36:37], v[26:29], off
	global_load_ushort v29, v[30:31], off
	s_nop 0
	global_load_ushort v48, v[32:33], off
	global_load_ushort v49, v[32:33], off offset:-14
	global_load_ushort v50, v[30:31], off offset:-14
	global_load_dwordx3 v[26:28], v[30:31], off offset:-12
	s_nop 0
	global_load_dwordx3 v[30:32], v[32:33], off offset:-12
	v_lshl_add_u64 v[36:37], s[36:37], 0, v[38:39]
	v_lshl_add_u64 v[36:37], v[36:37], 0, v[104:105]
	s_waitcnt vmcnt(5)
	v_lshlrev_b32_e32 v33, 16, v29
	s_waitcnt vmcnt(4)
	v_lshlrev_b32_e32 v60, 16, v48
	s_waitcnt vmcnt(3)
	v_lshlrev_b32_e32 v61, 16, v49
	s_waitcnt vmcnt(2)
	v_lshlrev_b32_e32 v62, 16, v50
	s_waitcnt vmcnt(1)
	v_lshlrev_b32_e32 v38, 16, v26
	v_and_b32_e32 v39, 0xffff0000, v26
	v_lshlrev_b32_e32 v26, 16, v27
	v_and_b32_e32 v27, 0xffff0000, v27
	v_lshlrev_b32_e32 v48, 16, v28
	v_and_b32_e32 v49, 0xffff0000, v28
	s_waitcnt vmcnt(0)
	v_lshlrev_b32_e32 v28, 16, v30
	v_and_b32_e32 v29, 0xffff0000, v30
	v_lshlrev_b32_e32 v30, 16, v31
	v_and_b32_e32 v31, 0xffff0000, v31
	v_lshlrev_b32_e32 v50, 16, v32
	v_and_b32_e32 v51, 0xffff0000, v32
	v_mul_f32_e32 v32, v47, v62
	v_mov_b32_e32 v47, v45
	v_mov_b32_e32 v45, v43
	v_mov_b32_e32 v43, v41
	v_mul_f32_e32 v40, v40, v33
	v_mul_f32_e32 v41, v59, v61
	v_mov_b32_e32 v59, v57
	v_mov_b32_e32 v57, v55
	v_mov_b32_e32 v55, v53
	v_mul_f32_e32 v52, v52, v60
	v_cvt_pk_bf16_f32 v53, v32, s0
	v_pk_mul_f32 v[32:33], v[46:47], v[38:39]
	v_pk_mul_f32 v[26:27], v[44:45], v[26:27]
	v_pk_mul_f32 v[38:39], v[42:43], v[48:49]
	v_cvt_pk_bf16_f32 v42, v40, s0
	v_cvt_pk_bf16_f32 v43, v41, s0
	v_pk_mul_f32 v[28:29], v[58:59], v[28:29]
	v_pk_mul_f32 v[30:31], v[56:57], v[30:31]
	v_pk_mul_f32 v[40:41], v[54:55], v[50:51]
	v_cvt_pk_bf16_f32 v44, v52, s0
	v_cvt_pk_bf16_f32 v32, v32, v33
	v_cvt_pk_bf16_f32 v26, v26, v27
	v_cvt_pk_bf16_f32 v33, v28, v29
	v_cvt_pk_bf16_f32 v28, v30, v31
	v_cvt_pk_bf16_f32 v29, v40, v41
	v_cvt_pk_bf16_f32 v27, v38, v39
	global_store_short v[34:35], v42, off
	global_store_short v[36:37], v44, off
	v_perm_b32 v30, v32, v53, s60
	global_store_short_d16_hi v[34:35], v32, off offset:-10
	global_store_dwordx2 v[34:35], v[26:27], off offset:-8
	v_perm_b32 v26, v33, v43, s60
	global_store_dwordx2 v[36:37], v[28:29], off offset:-8
	global_store_dword v[34:35], v30, off offset:-14
	global_store_short_d16_hi v[36:37], v33, off offset:-10
	global_store_dword v[36:37], v26, off offset:-14

; DI unsigned pk2(float a, float b) { f32x2 v = {a, b}; return __builtin_bit_cast(unsigned, __builtin_convertvector(v, bf16v2)); }
; DI float bf_lo(unsigned w) { return __uint_as_float(w << 16); }
; DI void fnet_layer(const Args& A, LAS unsigned char* lds, const XcdBarrier& gbar, int layer, int j, bool latonly, int wv) {
;     ...
;             bf16_t* ap = A1 + ((size_t)u.i0 * 1024 + k) * DM + col;
;             if (u.i2 < 8) { st_bf16x8(ap, v0, v1); return; }
;             f32x4 a0, a1; ld_bf16x8(ap, a0, a1);
;             const size_t off = ((size_t)u.i0 * TB + k) * DM + col;
;             f32x4 g0, g1; ld_bf16x8(Gt + off, g0, g1);
;             st_bf16x8(U + off, (a0 + v0) * g0, (a1 + v1) * g1);
;             if (k != 0) { const size_t off2 = ((size_t)u.i0 * TB + (TL - k)) * DM + col; ld_bf16x8(Gt + off2, g0, g1); st_bf16x8(U + off2, (a0 - v0) * g0, (a1 - v1) * g1); }
;             const f32x4 s0 = a0 + v0, s1 = a1 + v1, d0 = a0 - v0, d1 = a1 - v1;
;             const float sm[8] = {s0[0], s0[1], s0[2], s0[3], s1[0], s1[1], s1[2], s1[3]}, df[8] = {d0[0], d0[1], d0[2], d0[3], d1[0], d1[1], d1[2], d1[3]};
;             const size_t rowk = ((size_t)u.i0 * TB + k) * DM, rowT = ((size_t)u.i0 * TB + (TL - k)) * DM; const int cm = (col & ~255) + 512 - col_l;
;             {
;                 const bf16_t* gk_ = Gt + rowk + cm - 8; const bf16_t* gT_ = Gt + rowT + cm - 8; bf16_t* uk_ = U + rowk + cm - 8; bf16_t* uT_ = U + rowT + cm - 8;
;                 const unsigned short ka1 = gk_[1]; const unsigned ka2 = *(const unsigned*)(gk_ + 2); const u32x2 ka4 = *(const u32x2*)(gk_ + 4); const unsigned short ka0 = col_l ? gk_[8] : (unsigned short)0;
;                 unsigned short ta1 = 0, ta0 = 0; unsigned ta2 = 0; u32x2 ta4 = {0u, 0u};
;                 if (k != 0) { ta1 = gT_[1]; ta2 = *(const unsigned*)(gT_ + 2); ta4 = *(const u32x2*)(gT_ + 4); ta0 = col_l ? gT_[8] : (unsigned short)0; }
;                 uk_[1] = (bf16_t)(pk2(df[7] * __uint_as_float((unsigned)ka1 << 16), 0.f) & 0xffffu);
;                 *(unsigned*)(uk_ + 2) = pk2(df[6] * bf_lo(ka2), df[5] * bf_hi(ka2));
;                 *(u32x2*)(uk_ + 4) = (u32x2){pk2(df[4] * bf_lo(ka4.x), df[3] * bf_hi(ka4.x)), pk2(df[2] * bf_lo(ka4.y), df[1] * bf_hi(ka4.y))};
;                 if (col_l) uk_[8] = (bf16_t)(pk2(df[0] * __uint_as_float((unsigned)ka0 << 16), 0.f) & 0xffffu);
.LBB0_2625:
	v_add_u32_e32 v16, 0xb0, v150
	v_ashrrev_i32_e32 v17, 31, v16
	v_lshlrev_b64 v[18:19], 12, v[16:17]
	v_lshl_add_u64 v[16:17], s[40:41], 0, v[16:17]
	v_lshlrev_b64 v[24:25], 11, v[16:17]
	v_sub_u32_e32 v16, 0x750, v150
	v_ashrrev_i32_e32 v17, 31, v16
	v_lshl_add_u64 v[16:17], s[40:41], 0, v[16:17]
	v_lshl_add_u64 v[28:29], s[42:43], 0, v[18:19]
	v_mov_b32_e32 v153, v145
	v_lshlrev_b64 v[26:27], 11, v[16:17]
	v_lshl_add_u64 v[30:31], v[28:29], 0, v[152:153]
	s_and_b64 vcc, exec, s[4:5]
	s_mov_b64 s[6:7], -1
	s_cbranch_vccnz .LBB0_2635
	v_or_b32_e32 v20, v24, v189
	v_mov_b32_e32 v21, v25
	v_lshlrev_b64 v[32:33], 1, v[20:21]
	v_subrev_u32_e32 v248, s98, v30
	v_and_b32_e32 v249, 0xfffff000, v248
	v_and_b32_e32 v250, 0xfff, v248
	v_sub_u32_e32 v251, v250, v249
	v_add_u32_e32 v251, 0x800000, v251
	global_load_dwordx4 v[252:255], v251, s[100:101]
	global_load_dwordx4 v[16:19], v[30:31], off
	v_lshl_add_u64 v[20:21], s[44:45], 0, v[32:33]
	global_load_dwordx4 v[20:23], v[20:21], off
	v_or_b32_e32 v34, v26, v189
	v_mov_b32_e32 v35, v27
	v_lshlrev_b64 v[40:41], 1, v[34:35]
	v_lshl_add_u64 v[42:43], s[36:37], 0, v[32:33]
	v_lshl_add_u64 v[44:45], s[44:45], 0, v[40:41]
	v_lshl_add_u64 v[54:55], s[36:37], 0, v[40:41]
	v_cmp_ne_u32_e32 vcc, 0, v151
	s_waitcnt vmcnt(0)
	v_lshlrev_b32_e32 v46, 16, v16
	v_and_b32_e32 v47, 0xffff0000, v16
	v_lshlrev_b32_e32 v48, 16, v17
	v_and_b32_e32 v49, 0xffff0000, v17
	v_lshlrev_b32_e32 v50, 16, v18
	v_and_b32_e32 v51, 0xffff0000, v18
	v_lshlrev_b32_e32 v52, 16, v19
	v_and_b32_e32 v53, 0xffff0000, v19
	v_pk_add_f32 v[34:35], v[14:15], v[48:49]
	v_pk_add_f32 v[32:33], v[12:13], v[46:47]
	v_pk_add_f32 v[38:39], v[10:11], v[52:53]
	v_pk_add_f32 v[36:37], v[8:9], v[50:51]
	v_lshlrev_b32_e32 v16, 16, v20
	v_and_b32_e32 v17, 0xffff0000, v20
	v_lshlrev_b32_e32 v18, 16, v21
	v_and_b32_e32 v19, 0xffff0000, v21
	v_lshlrev_b32_e32 v20, 16, v22
	v_and_b32_e32 v21, 0xffff0000, v22
	v_lshlrev_b32_e32 v22, 16, v23
	v_and_b32_e32 v23, 0xffff0000, v23
	v_pk_mul_f32 v[18:19], v[34:35], v[18:19]
	v_pk_mul_f32 v[16:17], v[32:33], v[16:17]
	v_pk_mul_f32 v[22:23], v[38:39], v[22:23]
	v_pk_mul_f32 v[20:21], v[36:37], v[20:21]
	v_cvt_pk_bf16_f32 v16, v16, v17
	v_cvt_pk_bf16_f32 v17, v18, v19
	v_cvt_pk_bf16_f32 v18, v20, v21
	v_cvt_pk_bf16_f32 v19, v22, v23
	global_store_dwordx4 v[42:43], v[16:19], off
	v_sub_f32_e32 v42, v48, v14
	v_sub_f32_e32 v45, v49, v15
	v_sub_f32_e32 v40, v46, v12
	v_sub_f32_e32 v19, v53, v11
	v_sub_f32_e32 v46, v52, v10
	v_mov_b32_e32 v44, v42
	v_sub_f32_e32 v43, v47, v13
	v_sub_f32_e32 v47, v51, v9
	v_mov_b32_e32 v41, v43
	v_mov_b32_e32 v18, v46
	v_mov_b32_e32 v49, v47
	v_lshl_add_u64 v[16:17], v[24:25], 1, s[44:45]
	v_lshl_add_u64 v[16:17], v[16:17], 0, v[144:145]
	v_mov_b32_e32 v20, v252
	v_mov_b32_e32 v21, v253
	v_mov_b32_e32 v22, v254
	v_mov_b32_e32 v23, v255
	v_lshlrev_b32_e32 v52, 16, v20
	v_and_b32_e32 v53, 0xffff0000, v20
	v_lshlrev_b32_e32 v20, 16, v21
	v_and_b32_e32 v21, 0xffff0000, v21
	v_pk_mul_f32 v[58:59], v[44:45], v[20:21]
	v_sub_f32_e32 v44, v50, v8
	v_lshlrev_b32_e32 v56, 16, v22
	v_and_b32_e32 v57, 0xffff0000, v22
	v_lshlrev_b32_e32 v22, 16, v23
	v_and_b32_e32 v23, 0xffff0000, v23
	v_mov_b32_e32 v48, v44
	v_pk_mul_f32 v[20:21], v[40:41], v[52:53]
	v_pk_mul_f32 v[22:23], v[18:19], v[22:23]
	v_pk_mul_f32 v[48:49], v[48:49], v[56:57]
	v_cvt_pk_bf16_f32 v20, v20, v21
	v_cvt_pk_bf16_f32 v21, v58, v59
	v_cvt_pk_bf16_f32 v23, v22, v23
	v_cvt_pk_bf16_f32 v22, v48, v49
	global_store_dwordx4 v[54:55], v[20:23], off
	global_load_ushort v51, v[16:17], off offset:-14
	s_nop 0
	global_load_dwordx3 v[20:22], v[16:17], off offset:-12
	v_mov_b32_e32 v23, 0
	v_mov_b32_e32 v41, 0
	s_and_saveexec_b64 s[6:7], vcc
	s_cbranch_execz .LBB0_2628
	global_load_ushort v16, v[16:17], off
	s_waitcnt vmcnt(0)
	v_lshlrev_b32_e32 v41, 16, v16

; DI void fnet_layer(const Args& A, LAS unsigned char* lds, const XcdBarrier& gbar, int layer, int j, bool latonly, int wv) {
;     ...
;             bf16_t* ap = A1 + ((size_t)u.i0 * 1024 + k) * DM + col;
;             if (u.i2 < 8) { st_bf16x8(ap, v0, v1); return; }
;             f32x4 a0, a1; ld_bf16x8(ap, a0, a1);
;             const size_t off = ((size_t)u.i0 * TB + k) * DM + col;
;             f32x4 g0, g1; ld_bf16x8(Gt + off, g0, g1);
;             st_bf16x8(U + off, (a0 + v0) * g0, (a1 + v1) * g1);
;             if (k != 0) { const size_t off2 = ((size_t)u.i0 * TB + (TL - k)) * DM + col; ld_bf16x8(Gt + off2, g0, g1); st_bf16x8(U + off2, (a0 - v0) * g0, (a1 - v1) * g1); }
;             const f32x4 s0 = a0 + v0, s1 = a1 + v1, d0 = a0 - v0, d1 = a1 - v1;
;             const float sm[8] = {s0[0], s0[1], s0[2], s0[3], s1[0], s1[1], s1[2], s1[3]}, df[8] = {d0[0], d0[1], d0[2], d0[3], d1[0], d1[1], d1[2], d1[3]};
;             const size_t rowk = ((size_t)u.i0 * TB + k) * DM, rowT = ((size_t)u.i0 * TB + (TL - k)) * DM; const int cm = (col & ~255) + 512 - col_l;
;             {
;                 const bf16_t* gk_ = Gt + rowk + cm - 8; const bf16_t* gT_ = Gt + rowT + cm - 8; bf16_t* uk_ = U + rowk + cm - 8; bf16_t* uT_ = U + rowT + cm - 8;
;                 const unsigned short ka1 = gk_[1]; const unsigned ka2 = *(const unsigned*)(gk_ + 2); const u32x2 ka4 = *(const u32x2*)(gk_ + 4); const unsigned short ka0 = col_l ? gk_[8] : (unsigned short)0;
;                 unsigned short ta1 = 0, ta0 = 0; unsigned ta2 = 0; u32x2 ta4 = {0u, 0u};
;                 if (k != 0) { ta1 = gT_[1]; ta2 = *(const unsigned*)(gT_ + 2); ta4 = *(const u32x2*)(gT_ + 4); ta0 = col_l ? gT_[8] : (unsigned short)0; }
;                 uk_[1] = (bf16_t)(pk2(df[7] * __uint_as_float((unsigned)ka1 << 16), 0.f) & 0xffffu);
;                 *(unsigned*)(uk_ + 2) = pk2(df[6] * bf_lo(ka2), df[5] * bf_hi(ka2));
;                 *(u32x2*)(uk_ + 4) = (u32x2){pk2(df[4] * bf_lo(ka4.x), df[3] * bf_hi(ka4.x)), pk2(df[2] * bf_lo(ka4.y), df[1] * bf_hi(ka4.y))};
;                 if (col_l) uk_[8] = (bf16_t)(pk2(df[0] * __uint_as_float((unsigned)ka0 << 16), 0.f) & 0xffffu);
;                 if (k != 0) {
;                     uT_[1] = (bf16_t)(pk2(sm[7] * __uint_as_float((unsigned)ta1 << 16), 0.f) & 0xffffu);
;                     *(unsigned*)(uT_ + 2) = pk2(sm[6] * bf_lo(ta2), sm[5] * bf_hi(ta2));
.LBB0_2637:
	v_mov_b32_e32 v129, v145
	v_lshl_add_u64 v[8:9], v[28:29], 0, v[128:129]
	s_and_b64 vcc, exec, s[4:5]
	s_mov_b64 s[4:5], -1
	s_cbranch_vccnz .LBB0_2640
	v_or_b32_e32 v14, v24, v172
	v_mov_b32_e32 v15, v25
	v_lshlrev_b64 v[18:19], 1, v[14:15]
	v_subrev_u32_e32 v248, s98, v8
	v_add_u32_e32 v248, 256, v248
	v_and_b32_e32 v249, 0xfffff000, v248
	v_and_b32_e32 v250, 0xfff, v248
	v_sub_u32_e32 v251, v250, v249
	v_add_u32_e32 v251, 0x800000, v251
	global_load_dwordx4 v[252:255], v251, s[100:101]
	global_load_dwordx4 v[10:13], v[8:9], off offset:256
	v_lshl_add_u64 v[14:15], s[44:45], 0, v[18:19]
	global_load_dwordx4 v[14:17], v[14:15], off
	v_or_b32_e32 v20, v26, v172
	v_mov_b32_e32 v21, v27
	v_lshlrev_b64 v[20:21], 1, v[20:21]
	v_lshl_add_u64 v[18:19], s[36:37], 0, v[18:19]
	v_lshl_add_u64 v[22:23], s[44:45], 0, v[20:21]
	v_mov_b32_e32 v105, v145
	v_lshl_add_u64 v[20:21], s[36:37], 0, v[20:21]
	s_waitcnt vmcnt(0)
	v_lshlrev_b32_e32 v28, 16, v10
	v_and_b32_e32 v29, 0xffff0000, v10
	v_lshlrev_b32_e32 v30, 16, v11
	v_and_b32_e32 v31, 0xffff0000, v11
	v_lshlrev_b32_e32 v32, 16, v12
	v_and_b32_e32 v33, 0xffff0000, v12
	v_lshlrev_b32_e32 v34, 16, v13
	v_and_b32_e32 v35, 0xffff0000, v13
	v_pk_add_f32 v[36:37], v[4:5], v[28:29]
	v_pk_add_f32 v[38:39], v[6:7], v[30:31]
	v_pk_add_f32 v[40:41], v[0:1], v[32:33]
	v_pk_add_f32 v[42:43], v[2:3], v[34:35]
	v_lshlrev_b32_e32 v10, 16, v14
	v_and_b32_e32 v11, 0xffff0000, v14
	v_lshlrev_b32_e32 v12, 16, v15
	v_and_b32_e32 v13, 0xffff0000, v15
	v_lshlrev_b32_e32 v14, 16, v16
	v_and_b32_e32 v15, 0xffff0000, v16
	v_lshlrev_b32_e32 v16, 16, v17
	v_and_b32_e32 v17, 0xffff0000, v17
	v_pk_mul_f32 v[12:13], v[38:39], v[12:13]
	v_pk_mul_f32 v[10:11], v[36:37], v[10:11]
	v_pk_mul_f32 v[16:17], v[42:43], v[16:17]
	v_pk_mul_f32 v[14:15], v[40:41], v[14:15]
	v_cvt_pk_bf16_f32 v10, v10, v11
	v_cvt_pk_bf16_f32 v11, v12, v13
	v_cvt_pk_bf16_f32 v12, v14, v15
	v_cvt_pk_bf16_f32 v13, v16, v17
	global_store_dwordx4 v[18:19], v[10:13], off
	v_lshlrev_b64 v[18:19], 1, v[24:25]
	v_lshlrev_b64 v[22:23], 1, v[26:27]
	v_sub_f32_e32 v25, v29, v5
	v_sub_f32_e32 v24, v28, v4
	v_sub_f32_e32 v27, v31, v7
	v_sub_f32_e32 v26, v30, v6
	v_sub_f32_e32 v29, v33, v1
	v_sub_f32_e32 v28, v32, v0
	v_sub_f32_e32 v31, v35, v3
	v_sub_f32_e32 v30, v34, v2
	v_lshl_add_u64 v[14:15], s[44:45], 0, v[18:19]
	v_lshl_add_u64 v[16:17], s[44:45], 0, v[22:23]
	v_lshl_add_u64 v[14:15], v[14:15], 0, v[104:105]
	v_lshl_add_u64 v[16:17], v[16:17], 0, v[104:105]
	v_lshl_add_u64 v[18:19], s[36:37], 0, v[18:19]
	v_lshl_add_u64 v[18:19], v[18:19], 0, v[104:105]
	v_mov_b32_e32 v10, v252
	v_mov_b32_e32 v11, v253
	v_mov_b32_e32 v12, v254
	v_mov_b32_e32 v13, v255
	v_lshlrev_b32_e32 v32, 16, v10
	v_and_b32_e32 v33, 0xffff0000, v10
	v_lshlrev_b32_e32 v10, 16, v11
	v_and_b32_e32 v11, 0xffff0000, v11
	v_lshlrev_b32_e32 v34, 16, v12
	v_and_b32_e32 v35, 0xffff0000, v12
	v_lshlrev_b32_e32 v12, 16, v13
	v_and_b32_e32 v13, 0xffff0000, v13
	v_pk_mul_f32 v[44:45], v[26:27], v[10:11]
	v_pk_mul_f32 v[10:11], v[24:25], v[32:33]
	v_pk_mul_f32 v[32:33], v[30:31], v[12:13]
	v_pk_mul_f32 v[12:13], v[28:29], v[34:35]
	v_cvt_pk_bf16_f32 v10, v10, v11
	v_cvt_pk_bf16_f32 v11, v44, v45
	v_cvt_pk_bf16_f32 v12, v12, v13
	v_cvt_pk_bf16_f32 v13, v32, v33
	global_store_dwordx4 v[20:21], v[10:13], off
	global_load_ushort v13, v[14:15], off
	s_nop 0
	global_load_ushort v32, v[16:17], off
	global_load_ushort v33, v[16:17], off offset:-14
	global_load_ushort v34, v[14:15], off offset:-14
	global_load_dwordx3 v[10:12], v[14:15], off offset:-12
	s_nop 0
	global_load_dwordx3 v[14:16], v[16:17], off offset:-12
	v_lshl_add_u64 v[20:21], s[36:37], 0, v[22:23]
	v_lshl_add_u64 v[20:21], v[20:21], 0, v[104:105]
	s_waitcnt vmcnt(5)
	v_lshlrev_b32_e32 v17, 16, v13
	s_waitcnt vmcnt(4)
	v_lshlrev_b32_e32 v44, 16, v32
	s_waitcnt vmcnt(3)
	v_lshlrev_b32_e32 v45, 16, v33
	s_waitcnt vmcnt(2)
	v_lshlrev_b32_e32 v46, 16, v34
	s_waitcnt vmcnt(1)
	v_lshlrev_b32_e32 v22, 16, v10
	v_and_b32_e32 v23, 0xffff0000, v10
	v_lshlrev_b32_e32 v10, 16, v11
	v_and_b32_e32 v11, 0xffff0000, v11
	v_lshlrev_b32_e32 v32, 16, v12
	v_and_b32_e32 v33, 0xffff0000, v12
	s_waitcnt vmcnt(0)
	v_lshlrev_b32_e32 v12, 16, v14
	v_and_b32_e32 v13, 0xffff0000, v14
	v_lshlrev_b32_e32 v34, 16, v16
	v_and_b32_e32 v35, 0xffff0000, v16
	v_mul_f32_e32 v16, v31, v46
	v_mov_b32_e32 v31, v29
	v_mov_b32_e32 v29, v27
	v_mov_b32_e32 v27, v25
	v_mul_f32_e32 v25, v43, v45
	v_mov_b32_e32 v43, v41
	v_lshlrev_b32_e32 v14, 16, v15
	v_and_b32_e32 v15, 0xffff0000, v15
	v_mul_f32_e32 v24, v24, v17
	v_mov_b32_e32 v41, v39
	v_mov_b32_e32 v39, v37
	v_mul_f32_e32 v36, v36, v44
	v_cvt_pk_bf16_f32 v37, v16, s0
	v_pk_mul_f32 v[16:17], v[30:31], v[22:23]
	v_pk_mul_f32 v[10:11], v[28:29], v[10:11]
	v_pk_mul_f32 v[12:13], v[42:43], v[12:13]
	v_pk_mul_f32 v[22:23], v[26:27], v[32:33]
	v_cvt_pk_bf16_f32 v26, v24, s0
	v_cvt_pk_bf16_f32 v27, v25, s0
	v_pk_mul_f32 v[14:15], v[40:41], v[14:15]
	v_pk_mul_f32 v[24:25], v[38:39], v[34:35]
	v_cvt_pk_bf16_f32 v28, v36, s0
	v_cvt_pk_bf16_f32 v16, v16, v17
	v_cvt_pk_bf16_f32 v10, v10, v11
	v_cvt_pk_bf16_f32 v17, v12, v13
	v_cvt_pk_bf16_f32 v11, v22, v23
	global_store_short v[18:19], v26, off
	v_cvt_pk_bf16_f32 v12, v14, v15
	v_cvt_pk_bf16_f32 v13, v24, v25
	global_store_short v[20:21], v28, off
	v_perm_b32 v14, v16, v37, s60
	global_store_short_d16_hi v[18:19], v16, off offset:-10
	global_store_dwordx2 v[18:19], v[10:11], off offset:-8
	v_perm_b32 v10, v17, v27, s60
	global_store_short_d16_hi v[20:21], v17, off offset:-10
	global_store_dwordx2 v[20:21], v[12:13], off offset:-8
	global_store_dword v[18:19], v14, off offset:-14
	global_store_dword v[20:21], v10, off offset:-14
	s_cbranch_execz .LBB0_2641

; __global__ void __launch_bounds__(NTHREADS, 2) fwd_megakernel(Args A) {
;     extern __shared__ __attribute__((aligned(16))) unsigned char lds_raw[];
	.amdhsa_kernel _Z14fwd_megakernel4Args
		.amdhsa_group_segment_fixed_size 0
		.amdhsa_private_segment_fixed_size 0
		.amdhsa_kernarg_size 424
		.amdhsa_user_sgpr_count 2
		.amdhsa_user_sgpr_dispatch_ptr 0
		.amdhsa_user_sgpr_queue_ptr 0
		.amdhsa_user_sgpr_kernarg_segment_ptr 1
		.amdhsa_user_sgpr_dispatch_id 0
		.amdhsa_user_sgpr_kernarg_preload_length 0
		.amdhsa_user_sgpr_kernarg_preload_offset 0
		.amdhsa_user_sgpr_private_segment_size 0
		.amdhsa_uses_dynamic_stack 0
		.amdhsa_enable_private_segment 0
		.amdhsa_system_sgpr_workgroup_id_x 1
		.amdhsa_system_sgpr_workgroup_id_y 0
		.amdhsa_system_sgpr_workgroup_id_z 0
		.amdhsa_system_sgpr_workgroup_info 0
		.amdhsa_system_vgpr_workitem_id 2
		.amdhsa_next_free_vgpr 256
		.amdhsa_next_free_sgpr 102
		.amdhsa_accum_offset 256
		.amdhsa_reserve_vcc 1
		.amdhsa_float_round_mode_32 0
		.amdhsa_float_round_mode_16_64 0
		.amdhsa_float_denorm_mode_32 3
		.amdhsa_float_denorm_mode_16_64 3
		.amdhsa_dx10_clamp 1
		.amdhsa_ieee_mode 1
		.amdhsa_fp16_overflow 0
		.amdhsa_tg_split 0
		.amdhsa_exception_fp_ieee_invalid_op 0
		.amdhsa_exception_fp_denorm_src 0
		.amdhsa_exception_fp_ieee_div_zero 0
		.amdhsa_exception_fp_ieee_overflow 0
		.amdhsa_exception_fp_ieee_underflow 0
		.amdhsa_exception_fp_ieee_inexact 0
		.amdhsa_exception_int_div_zero 0
	.end_amdhsa_kernel

; __global__ void __launch_bounds__(NTHREADS, 2) fwd_megakernel(Args A) {
;     extern __shared__ __attribute__((aligned(16))) unsigned char lds_raw[];
amdhsa.kernels:
  - .agpr_count:     0
    .args:
      - .offset:         0
        .size:           168
        .value_kind:     by_value
      - .offset:         168
        .size:           4
        .value_kind:     hidden_block_count_x
      - .offset:         172
        .size:           4
        .value_kind:     hidden_block_count_y
      - .offset:         176
        .size:           4
        .value_kind:     hidden_block_count_z
      - .offset:         180
        .size:           2
        .value_kind:     hidden_group_size_x
      - .offset:         182
        .size:           2
        .value_kind:     hidden_group_size_y
      - .offset:         184
        .size:           2
        .value_kind:     hidden_group_size_z
      - .offset:         186
        .size:           2
        .value_kind:     hidden_remainder_x
      - .offset:         188
        .size:           2
        .value_kind:     hidden_remainder_y
      - .offset:         190
        .size:           2
        .value_kind:     hidden_remainder_z
      - .offset:         208
        .size:           8
        .value_kind:     hidden_global_offset_x
      - .offset:         216
        .size:           8
        .value_kind:     hidden_global_offset_y
      - .offset:         224
        .size:           8
        .value_kind:     hidden_global_offset_z
      - .offset:         232
        .size:           2
        .value_kind:     hidden_grid_dims
      - .offset:         256
        .size:           8
        .value_kind:     hidden_multigrid_sync_arg
      - .offset:         288
        .size:           4
        .value_kind:     hidden_dynamic_lds_size
    .group_segment_fixed_size: 0
    .kernarg_segment_align: 8
    .kernarg_segment_size: 424
    .language:       OpenCL C
    .language_version:
      - 2
      - 0
    .max_flat_workgroup_size: 512
    .name:           _Z14fwd_megakernel4Args
    .private_segment_fixed_size: 0
    .sgpr_count:     108
    .sgpr_spill_count: 71
    .symbol:         _Z14fwd_megakernel4Args.kd
    .uniform_work_group_size: 1
    .uses_dynamic_stack: false
    .vgpr_count:     256
    .vgpr_spill_count: 0
    .wavefront_size: 64
